# K-loops: LDS-DMA stages rotated by one phase (memory parts: 12 reads / 4 reads+2 DMA / 8 reads+2 DMA / 4 DMA); stage order and vmcnt points unchanged
# speedup vs baseline: 1.0074x; 1.0027x over previous
.LBB0_122:
	v_mov_b64_e32 v[0:1], 0x180
	s_ashr_i32 s15, s14, 31
	v_cmp_lt_i64_e32 vcc, s[16:17], v[0:1]
	s_lshl_b64 s[16:17], s[14:15], 19
	s_add_u32 s16, s30, s16
	s_addc_u32 s17, s31, s17
	s_and_b64 s[18:19], vcc, exec
	s_cselect_b32 s7, s17, s21
	s_cselect_b32 s9, s16, s20
	s_ashr_i32 s13, s12, 31
	s_lshl_b64 s[18:19], s[12:13], 19
	s_add_u32 s18, s34, s18
	s_addc_u32 s19, s35, s19
	s_and_b64 s[22:23], vcc, exec
	s_cselect_b32 s13, s19, s3
	s_cselect_b32 s15, s18, s2
	s_add_u32 s20, s20, 0x40080
	s_addc_u32 s21, s21, 0
	s_add_u32 s50, s2, 0x100
	s_addc_u32 s51, s3, 0
	s_mov_b32 s52, -2
	s_add_u32 s2, s20, 0xfffc0080
	s_addc_u32 s3, s21, -1
	ds_read_b128 v[24:27], v164
	ds_read_b128 v[28:31], v164 offset:1024
	ds_read_b128 v[32:35], v164 offset:2048
	ds_read_b128 v[36:39], v164 offset:3072
	s_cmp_eq_u32 s52, 12
	s_cselect_b32 s23, s7, s3
	s_cselect_b32 s22, s9, s2
	s_cselect_b32 s3, s13, s51
	s_cselect_b32 s2, s15, s50
	ds_read_b128 v[154:157], v165
	ds_read_b128 v[158:161], v165 offset:1024
	ds_read_b128 v[180:183], v165 offset:2048
	ds_read_b128 v[184:187], v165 offset:3072
	ds_read_b128 v[188:191], v165 offset:4096
	ds_read_b128 v[192:195], v165 offset:5120
	ds_read_b128 v[196:199], v165 offset:6144
	ds_read_b128 v[200:203], v165 offset:7168
	s_waitcnt lgkmcnt(8)
	s_barrier
	s_waitcnt lgkmcnt(0)
	v_mfma_f32_16x16x32_bf16 v[140:143], v[24:27], v[154:157], 0
	v_mfma_f32_16x16x32_bf16 v[136:139], v[32:35], v[154:157], 0
	v_mfma_f32_16x16x32_bf16 v[124:127], v[24:27], v[180:183], 0
	v_mfma_f32_16x16x32_bf16 v[120:123], v[32:35], v[180:183], 0
	v_mfma_f32_16x16x32_bf16 v[108:111], v[24:27], v[188:191], 0
	v_mfma_f32_16x16x32_bf16 v[104:107], v[32:35], v[188:191], 0
	v_mfma_f32_16x16x32_bf16 v[92:95], v[24:27], v[196:199], 0
	v_mfma_f32_16x16x32_bf16 v[88:91], v[32:35], v[196:199], 0
	v_mfma_f32_16x16x32_bf16 v[140:143], v[28:31], v[158:161], v[140:143]
	v_mfma_f32_16x16x32_bf16 v[136:139], v[36:39], v[158:161], v[136:139]
	v_mfma_f32_16x16x32_bf16 v[124:127], v[28:31], v[184:187], v[124:127]
	v_mfma_f32_16x16x32_bf16 v[120:123], v[36:39], v[184:187], v[120:123]
	v_mfma_f32_16x16x32_bf16 v[108:111], v[28:31], v[192:195], v[108:111]
	v_mfma_f32_16x16x32_bf16 v[104:107], v[36:39], v[192:195], v[104:107]
	v_mfma_f32_16x16x32_bf16 v[92:95], v[28:31], v[200:203], v[92:95]
	v_mfma_f32_16x16x32_bf16 v[88:91], v[36:39], v[200:203], v[88:91]
	s_barrier
	s_add_i32 m0, s37, 0xc000
	ds_read_b128 v[204:207], v164 offset:16384
	ds_read_b128 v[208:211], v164 offset:17408
	ds_read_b128 v[212:215], v164 offset:18432
	global_load_lds_dwordx4 v150, s[20:21]
	s_add_i32 m0, s37, 0xe000
	ds_read_b128 v[216:219], v164 offset:19456
	global_load_lds_dwordx4 v152, s[20:21]
	s_add_u32 s98, s2, 0x80
	s_addc_u32 s99, s3, 0
	s_barrier
	s_waitcnt lgkmcnt(0)
	v_mfma_f32_16x16x32_bf16 v[132:135], v[204:207], v[154:157], 0
	v_mfma_f32_16x16x32_bf16 v[128:131], v[212:215], v[154:157], 0
	v_mfma_f32_16x16x32_bf16 v[116:119], v[204:207], v[180:183], 0
	v_mfma_f32_16x16x32_bf16 v[112:115], v[212:215], v[180:183], 0
	v_mfma_f32_16x16x32_bf16 v[100:103], v[204:207], v[188:191], 0
	v_mfma_f32_16x16x32_bf16 v[96:99], v[212:215], v[188:191], 0
	v_mfma_f32_16x16x32_bf16 v[84:87], v[204:207], v[196:199], 0
	v_mfma_f32_16x16x32_bf16 v[80:83], v[212:215], v[196:199], 0
	v_mfma_f32_16x16x32_bf16 v[132:135], v[208:211], v[158:161], v[132:135]
	v_mfma_f32_16x16x32_bf16 v[128:131], v[216:219], v[158:161], v[128:131]
	v_mfma_f32_16x16x32_bf16 v[116:119], v[208:211], v[184:187], v[116:119]
	v_mfma_f32_16x16x32_bf16 v[112:115], v[216:219], v[184:187], v[112:115]
	v_mfma_f32_16x16x32_bf16 v[100:103], v[208:211], v[192:195], v[100:103]
	v_mfma_f32_16x16x32_bf16 v[96:99], v[216:219], v[192:195], v[96:99]
	v_mfma_f32_16x16x32_bf16 v[84:87], v[208:211], v[200:203], v[84:87]
	v_mfma_f32_16x16x32_bf16 v[80:83], v[216:219], v[200:203], v[80:83]
	s_add_u32 s100, s22, 0x80
	s_addc_u32 s101, s23, 0
	s_barrier
	ds_read_b128 v[154:157], v165 offset:16384
	ds_read_b128 v[158:161], v165 offset:17408
	ds_read_b128 v[180:183], v165 offset:18432
	ds_read_b128 v[184:187], v165 offset:19456
	ds_read_b128 v[188:191], v165 offset:20480
	ds_read_b128 v[192:195], v165 offset:21504
	ds_read_b128 v[196:199], v165 offset:22528
	ds_read_b128 v[200:203], v165 offset:23552
	s_add_i32 m0, s36, 0x10000
	s_nop 0
	global_load_lds_dwordx4 v168, s[2:3]
	s_add_i32 m0, s36, 0x12000
	s_nop 0
	global_load_lds_dwordx4 v148, s[2:3]
	s_barrier
	s_waitcnt lgkmcnt(0)
	v_mfma_f32_16x16x32_bf16 v[76:79], v[24:27], v[154:157], 0
	v_mfma_f32_16x16x32_bf16 v[72:75], v[32:35], v[154:157], 0
	v_mfma_f32_16x16x32_bf16 v[60:63], v[24:27], v[180:183], 0
	v_mfma_f32_16x16x32_bf16 v[56:59], v[32:35], v[180:183], 0
	v_mfma_f32_16x16x32_bf16 v[44:47], v[24:27], v[188:191], 0
	v_mfma_f32_16x16x32_bf16 v[40:43], v[32:35], v[188:191], 0
	v_mfma_f32_16x16x32_bf16 v[12:15], v[24:27], v[196:199], 0
	v_mfma_f32_16x16x32_bf16 v[8:11], v[32:35], v[196:199], 0
	v_mfma_f32_16x16x32_bf16 v[76:79], v[28:31], v[158:161], v[76:79]
	v_mfma_f32_16x16x32_bf16 v[72:75], v[36:39], v[158:161], v[72:75]
	v_mfma_f32_16x16x32_bf16 v[60:63], v[28:31], v[184:187], v[60:63]
	v_mfma_f32_16x16x32_bf16 v[56:59], v[36:39], v[184:187], v[56:59]
	v_mfma_f32_16x16x32_bf16 v[44:47], v[28:31], v[192:195], v[44:47]
	v_mfma_f32_16x16x32_bf16 v[40:43], v[36:39], v[192:195], v[40:43]
	v_mfma_f32_16x16x32_bf16 v[12:15], v[28:31], v[200:203], v[12:15]
	v_mfma_f32_16x16x32_bf16 v[8:11], v[36:39], v[200:203], v[8:11]
	s_barrier
	s_mov_b32 m0, s37
	s_nop 0
	global_load_lds_dwordx4 v144, s[22:23]
	s_mov_b32 m0, s38
	s_nop 0
	global_load_lds_dwordx4 v146, s[22:23]
	s_add_i32 m0, s36, 0x14000
	s_add_u32 s54, s2, 0x40000
	s_addc_u32 s55, s3, 0
	global_load_lds_dwordx4 v168, s[54:55]
	s_add_i32 m0, s36, 0x16000
	s_add_u32 s22, s22, 0x40000
	s_addc_u32 s23, s23, 0
	global_load_lds_dwordx4 v148, s[54:55]
	s_waitcnt vmcnt(6)
	s_barrier
	v_mfma_f32_16x16x32_bf16 v[20:23], v[204:207], v[188:191], 0
	v_mfma_f32_16x16x32_bf16 v[16:19], v[212:215], v[188:191], 0
	v_mfma_f32_16x16x32_bf16 v[4:7], v[204:207], v[196:199], 0
	v_mfma_f32_16x16x32_bf16 v[0:3], v[212:215], v[196:199], 0
	v_mfma_f32_16x16x32_bf16 v[24:27], v[204:207], v[154:157], 0
	v_mfma_f32_16x16x32_bf16 v[28:31], v[212:215], v[154:157], 0
	v_mfma_f32_16x16x32_bf16 v[32:35], v[204:207], v[180:183], 0
	v_mfma_f32_16x16x32_bf16 v[36:39], v[212:215], v[180:183], 0
	v_mfma_f32_16x16x32_bf16 v[20:23], v[208:211], v[192:195], v[20:23]
	v_mfma_f32_16x16x32_bf16 v[16:19], v[216:219], v[192:195], v[16:19]
	v_mfma_f32_16x16x32_bf16 v[4:7], v[208:211], v[200:203], v[4:7]
	v_mfma_f32_16x16x32_bf16 v[0:3], v[216:219], v[200:203], v[0:3]
	v_mfma_f32_16x16x32_bf16 v[24:27], v[208:211], v[158:161], v[24:27]
	v_mfma_f32_16x16x32_bf16 v[28:31], v[216:219], v[158:161], v[28:31]
	v_mfma_f32_16x16x32_bf16 v[32:35], v[208:211], v[184:187], v[32:35]
	v_mfma_f32_16x16x32_bf16 v[36:39], v[216:219], v[184:187], v[36:39]
	s_barrier
	ds_read_b128 v[48:51], v164 offset:32768
	ds_read_b128 v[52:55], v164 offset:33792
	ds_read_b128 v[64:67], v164 offset:34816
	ds_read_b128 v[68:71], v164 offset:35840
	ds_read_b128 v[154:157], v165 offset:32768
	ds_read_b128 v[158:161], v165 offset:33792
	ds_read_b128 v[180:183], v165 offset:34816
	ds_read_b128 v[184:187], v165 offset:35840
	ds_read_b128 v[188:191], v165 offset:36864
	ds_read_b128 v[192:195], v165 offset:37888
	ds_read_b128 v[196:199], v165 offset:38912
	ds_read_b128 v[200:203], v165 offset:39936
	s_waitcnt lgkmcnt(8)
	s_barrier
	s_waitcnt lgkmcnt(0)
	v_mfma_f32_16x16x32_bf16 v[140:143], v[48:51], v[154:157], v[140:143]
	v_mfma_f32_16x16x32_bf16 v[136:139], v[64:67], v[154:157], v[136:139]
	v_mfma_f32_16x16x32_bf16 v[124:127], v[48:51], v[180:183], v[124:127]
	v_mfma_f32_16x16x32_bf16 v[120:123], v[64:67], v[180:183], v[120:123]
	v_mfma_f32_16x16x32_bf16 v[108:111], v[48:51], v[188:191], v[108:111]
	v_mfma_f32_16x16x32_bf16 v[104:107], v[64:67], v[188:191], v[104:107]
	v_mfma_f32_16x16x32_bf16 v[92:95], v[48:51], v[196:199], v[92:95]
	v_mfma_f32_16x16x32_bf16 v[88:91], v[64:67], v[196:199], v[88:91]
	v_mfma_f32_16x16x32_bf16 v[140:143], v[52:55], v[158:161], v[140:143]
	v_mfma_f32_16x16x32_bf16 v[136:139], v[68:71], v[158:161], v[136:139]
	v_mfma_f32_16x16x32_bf16 v[124:127], v[52:55], v[184:187], v[124:127]
	v_mfma_f32_16x16x32_bf16 v[120:123], v[68:71], v[184:187], v[120:123]
	v_mfma_f32_16x16x32_bf16 v[108:111], v[52:55], v[192:195], v[108:111]
	v_mfma_f32_16x16x32_bf16 v[104:107], v[68:71], v[192:195], v[104:107]
	v_mfma_f32_16x16x32_bf16 v[92:95], v[52:55], v[200:203], v[92:95]
	v_mfma_f32_16x16x32_bf16 v[88:91], v[68:71], v[200:203], v[88:91]
	s_barrier
	s_mov_b32 m0, s39
	ds_read_b128 v[204:207], v164 offset:49152
	ds_read_b128 v[208:211], v164 offset:50176
	ds_read_b128 v[212:215], v164 offset:51200
	global_load_lds_dwordx4 v144, s[22:23]
	s_mov_b32 m0, s40
	ds_read_b128 v[216:219], v164 offset:52224
	global_load_lds_dwordx4 v146, s[22:23]
	s_barrier
	s_waitcnt lgkmcnt(0)
	v_mfma_f32_16x16x32_bf16 v[132:135], v[204:207], v[154:157], v[132:135]
	v_mfma_f32_16x16x32_bf16 v[128:131], v[212:215], v[154:157], v[128:131]
	v_mfma_f32_16x16x32_bf16 v[116:119], v[204:207], v[180:183], v[116:119]
	v_mfma_f32_16x16x32_bf16 v[112:115], v[212:215], v[180:183], v[112:115]
	v_mfma_f32_16x16x32_bf16 v[100:103], v[204:207], v[188:191], v[100:103]
	v_mfma_f32_16x16x32_bf16 v[96:99], v[212:215], v[188:191], v[96:99]
	v_mfma_f32_16x16x32_bf16 v[84:87], v[204:207], v[196:199], v[84:87]
	v_mfma_f32_16x16x32_bf16 v[80:83], v[212:215], v[196:199], v[80:83]
	v_mfma_f32_16x16x32_bf16 v[132:135], v[208:211], v[158:161], v[132:135]
	v_mfma_f32_16x16x32_bf16 v[128:131], v[216:219], v[158:161], v[128:131]
	v_mfma_f32_16x16x32_bf16 v[116:119], v[208:211], v[184:187], v[116:119]
	v_mfma_f32_16x16x32_bf16 v[112:115], v[216:219], v[184:187], v[112:115]
	v_mfma_f32_16x16x32_bf16 v[100:103], v[208:211], v[192:195], v[100:103]
	v_mfma_f32_16x16x32_bf16 v[96:99], v[216:219], v[192:195], v[96:99]
	v_mfma_f32_16x16x32_bf16 v[84:87], v[208:211], v[200:203], v[84:87]
	v_mfma_f32_16x16x32_bf16 v[80:83], v[216:219], v[200:203], v[80:83]
	s_barrier
	ds_read_b128 v[154:157], v165 offset:49152
	ds_read_b128 v[158:161], v165 offset:50176
	ds_read_b128 v[180:183], v165 offset:51200
	ds_read_b128 v[184:187], v165 offset:52224
	ds_read_b128 v[188:191], v165 offset:53248
	ds_read_b128 v[192:195], v165 offset:54272
	ds_read_b128 v[196:199], v165 offset:55296
	ds_read_b128 v[200:203], v165 offset:56320
	s_add_i32 m0, s36, 0x18000
	s_nop 0
	global_load_lds_dwordx4 v168, s[98:99]
	s_add_i32 m0, s36, 0x1a000
	s_nop 0
	global_load_lds_dwordx4 v148, s[98:99]
	s_barrier
	s_waitcnt lgkmcnt(0)
	v_mfma_f32_16x16x32_bf16 v[76:79], v[48:51], v[154:157], v[76:79]
	v_mfma_f32_16x16x32_bf16 v[72:75], v[64:67], v[154:157], v[72:75]
	v_mfma_f32_16x16x32_bf16 v[60:63], v[48:51], v[180:183], v[60:63]
	v_mfma_f32_16x16x32_bf16 v[56:59], v[64:67], v[180:183], v[56:59]
	v_mfma_f32_16x16x32_bf16 v[44:47], v[48:51], v[188:191], v[44:47]
	v_mfma_f32_16x16x32_bf16 v[40:43], v[64:67], v[188:191], v[40:43]
	v_mfma_f32_16x16x32_bf16 v[12:15], v[48:51], v[196:199], v[12:15]
	v_mfma_f32_16x16x32_bf16 v[8:11], v[64:67], v[196:199], v[8:11]
	v_mfma_f32_16x16x32_bf16 v[76:79], v[52:55], v[158:161], v[76:79]
	v_mfma_f32_16x16x32_bf16 v[72:75], v[68:71], v[158:161], v[72:75]
	v_mfma_f32_16x16x32_bf16 v[60:63], v[52:55], v[184:187], v[60:63]
	v_mfma_f32_16x16x32_bf16 v[56:59], v[68:71], v[184:187], v[56:59]
	v_mfma_f32_16x16x32_bf16 v[44:47], v[52:55], v[192:195], v[44:47]
	v_mfma_f32_16x16x32_bf16 v[40:43], v[68:71], v[192:195], v[40:43]
	v_mfma_f32_16x16x32_bf16 v[12:15], v[52:55], v[200:203], v[12:15]
	v_mfma_f32_16x16x32_bf16 v[8:11], v[68:71], v[200:203], v[8:11]
	s_barrier
	s_mov_b32 m0, s45
	s_nop 0
	global_load_lds_dwordx4 v144, s[100:101]
	s_mov_b32 m0, s46
	s_nop 0
	global_load_lds_dwordx4 v146, s[100:101]
	s_add_i32 m0, s36, 0x1c000
	s_add_u32 s2, s2, 0x40080
	s_addc_u32 s3, s3, 0
	global_load_lds_dwordx4 v168, s[2:3]
	s_add_i32 m0, s36, 0x1e000
	s_add_i32 s52, s52, 2
	global_load_lds_dwordx4 v148, s[2:3]
	s_waitcnt vmcnt(6)
	s_barrier
	v_mfma_f32_16x16x32_bf16 v[24:27], v[204:207], v[154:157], v[24:27]
	v_mfma_f32_16x16x32_bf16 v[68:71], v[208:211], v[158:161], v[24:27]
	v_mfma_f32_16x16x32_bf16 v[24:27], v[212:215], v[154:157], v[28:31]
	v_mfma_f32_16x16x32_bf16 v[64:67], v[216:219], v[158:161], v[24:27]
	v_mfma_f32_16x16x32_bf16 v[24:27], v[204:207], v[180:183], v[32:35]
	v_mfma_f32_16x16x32_bf16 v[52:55], v[208:211], v[184:187], v[24:27]
	v_mfma_f32_16x16x32_bf16 v[24:27], v[212:215], v[180:183], v[36:39]
	v_mfma_f32_16x16x32_bf16 v[20:23], v[204:207], v[188:191], v[20:23]
	v_mfma_f32_16x16x32_bf16 v[16:19], v[212:215], v[188:191], v[16:19]
	v_mfma_f32_16x16x32_bf16 v[4:7], v[204:207], v[196:199], v[4:7]
	v_mfma_f32_16x16x32_bf16 v[0:3], v[212:215], v[196:199], v[0:3]
	v_mfma_f32_16x16x32_bf16 v[48:51], v[216:219], v[184:187], v[24:27]
	v_mfma_f32_16x16x32_bf16 v[20:23], v[208:211], v[192:195], v[20:23]
	v_mfma_f32_16x16x32_bf16 v[16:19], v[216:219], v[192:195], v[16:19]
	v_mfma_f32_16x16x32_bf16 v[4:7], v[208:211], v[200:203], v[4:7]
	v_mfma_f32_16x16x32_bf16 v[0:3], v[216:219], v[200:203], v[0:3]
	s_add_u32 s20, s20, 0x100
	s_addc_u32 s21, s21, 0
	s_add_u32 s50, s50, 0x100
	s_addc_u32 s51, s51, 0
	s_cmp_gt_u32 s52, 13
	s_barrier
.LBB0_123:
	s_add_u32 s2, s20, 0xfffc0080
	s_addc_u32 s3, s21, -1
	ds_read_b128 v[24:27], v164
	ds_read_b128 v[28:31], v164 offset:1024
	ds_read_b128 v[32:35], v164 offset:2048
	ds_read_b128 v[36:39], v164 offset:3072
	s_cmp_eq_u32 s52, 12
	s_cselect_b32 s23, s7, s3
	s_cselect_b32 s22, s9, s2
	s_cselect_b32 s3, s13, s51
	s_cselect_b32 s2, s15, s50
	ds_read_b128 v[154:157], v165
	ds_read_b128 v[158:161], v165 offset:1024
	ds_read_b128 v[180:183], v165 offset:2048
	ds_read_b128 v[184:187], v165 offset:3072
	ds_read_b128 v[188:191], v165 offset:4096
	ds_read_b128 v[192:195], v165 offset:5120
	ds_read_b128 v[196:199], v165 offset:6144
	ds_read_b128 v[200:203], v165 offset:7168
	s_waitcnt lgkmcnt(8)
	s_barrier
	s_waitcnt lgkmcnt(0)
	v_mfma_f32_16x16x32_bf16 v[140:143], v[24:27], v[154:157], v[140:143]
	v_mfma_f32_16x16x32_bf16 v[136:139], v[32:35], v[154:157], v[136:139]
	v_mfma_f32_16x16x32_bf16 v[124:127], v[24:27], v[180:183], v[124:127]
	v_mfma_f32_16x16x32_bf16 v[120:123], v[32:35], v[180:183], v[120:123]
	v_mfma_f32_16x16x32_bf16 v[108:111], v[24:27], v[188:191], v[108:111]
	v_mfma_f32_16x16x32_bf16 v[104:107], v[32:35], v[188:191], v[104:107]
	v_mfma_f32_16x16x32_bf16 v[92:95], v[24:27], v[196:199], v[92:95]
	v_mfma_f32_16x16x32_bf16 v[88:91], v[32:35], v[196:199], v[88:91]
	v_mfma_f32_16x16x32_bf16 v[140:143], v[28:31], v[158:161], v[140:143]
	v_mfma_f32_16x16x32_bf16 v[136:139], v[36:39], v[158:161], v[136:139]
	v_mfma_f32_16x16x32_bf16 v[124:127], v[28:31], v[184:187], v[124:127]
	v_mfma_f32_16x16x32_bf16 v[120:123], v[36:39], v[184:187], v[120:123]
	v_mfma_f32_16x16x32_bf16 v[108:111], v[28:31], v[192:195], v[108:111]
	v_mfma_f32_16x16x32_bf16 v[104:107], v[36:39], v[192:195], v[104:107]
	v_mfma_f32_16x16x32_bf16 v[92:95], v[28:31], v[200:203], v[92:95]
	v_mfma_f32_16x16x32_bf16 v[88:91], v[36:39], v[200:203], v[88:91]
	s_barrier
	s_add_i32 m0, s37, 0xc000
	ds_read_b128 v[204:207], v164 offset:16384
	ds_read_b128 v[208:211], v164 offset:17408
	ds_read_b128 v[212:215], v164 offset:18432
	global_load_lds_dwordx4 v150, s[20:21]
	s_add_i32 m0, s37, 0xe000
	ds_read_b128 v[216:219], v164 offset:19456
	global_load_lds_dwordx4 v152, s[20:21]
	s_add_u32 s98, s2, 0x80
	s_addc_u32 s99, s3, 0
	s_barrier
	s_waitcnt lgkmcnt(0)
	v_mfma_f32_16x16x32_bf16 v[132:135], v[204:207], v[154:157], v[132:135]
	v_mfma_f32_16x16x32_bf16 v[128:131], v[212:215], v[154:157], v[128:131]
	v_mfma_f32_16x16x32_bf16 v[116:119], v[204:207], v[180:183], v[116:119]
	v_mfma_f32_16x16x32_bf16 v[112:115], v[212:215], v[180:183], v[112:115]
	v_mfma_f32_16x16x32_bf16 v[100:103], v[204:207], v[188:191], v[100:103]
	v_mfma_f32_16x16x32_bf16 v[96:99], v[212:215], v[188:191], v[96:99]
	v_mfma_f32_16x16x32_bf16 v[84:87], v[204:207], v[196:199], v[84:87]
	v_mfma_f32_16x16x32_bf16 v[80:83], v[212:215], v[196:199], v[80:83]
	v_mfma_f32_16x16x32_bf16 v[132:135], v[208:211], v[158:161], v[132:135]
	v_mfma_f32_16x16x32_bf16 v[128:131], v[216:219], v[158:161], v[128:131]
	v_mfma_f32_16x16x32_bf16 v[116:119], v[208:211], v[184:187], v[116:119]
	v_mfma_f32_16x16x32_bf16 v[112:115], v[216:219], v[184:187], v[112:115]
	v_mfma_f32_16x16x32_bf16 v[100:103], v[208:211], v[192:195], v[100:103]
	v_mfma_f32_16x16x32_bf16 v[96:99], v[216:219], v[192:195], v[96:99]
	v_mfma_f32_16x16x32_bf16 v[84:87], v[208:211], v[200:203], v[84:87]
	v_mfma_f32_16x16x32_bf16 v[80:83], v[216:219], v[200:203], v[80:83]
	s_add_u32 s100, s22, 0x80
	s_addc_u32 s101, s23, 0
	s_barrier
	ds_read_b128 v[154:157], v165 offset:16384
	ds_read_b128 v[158:161], v165 offset:17408
	ds_read_b128 v[180:183], v165 offset:18432
	ds_read_b128 v[184:187], v165 offset:19456
	ds_read_b128 v[188:191], v165 offset:20480
	ds_read_b128 v[192:195], v165 offset:21504
	ds_read_b128 v[196:199], v165 offset:22528
	ds_read_b128 v[200:203], v165 offset:23552
	s_add_i32 m0, s36, 0x10000
	s_nop 0
	global_load_lds_dwordx4 v168, s[2:3]
	s_add_i32 m0, s36, 0x12000
	s_nop 0
	global_load_lds_dwordx4 v148, s[2:3]
	s_barrier
	s_waitcnt lgkmcnt(0)
	v_mfma_f32_16x16x32_bf16 v[76:79], v[24:27], v[154:157], v[76:79]
	v_mfma_f32_16x16x32_bf16 v[72:75], v[32:35], v[154:157], v[72:75]
	v_mfma_f32_16x16x32_bf16 v[60:63], v[24:27], v[180:183], v[60:63]
	v_mfma_f32_16x16x32_bf16 v[56:59], v[32:35], v[180:183], v[56:59]
	v_mfma_f32_16x16x32_bf16 v[44:47], v[24:27], v[188:191], v[44:47]
	v_mfma_f32_16x16x32_bf16 v[40:43], v[32:35], v[188:191], v[40:43]
	v_mfma_f32_16x16x32_bf16 v[12:15], v[24:27], v[196:199], v[12:15]
	v_mfma_f32_16x16x32_bf16 v[8:11], v[32:35], v[196:199], v[8:11]
	v_mfma_f32_16x16x32_bf16 v[76:79], v[28:31], v[158:161], v[76:79]
	v_mfma_f32_16x16x32_bf16 v[72:75], v[36:39], v[158:161], v[72:75]
	v_mfma_f32_16x16x32_bf16 v[60:63], v[28:31], v[184:187], v[60:63]
	v_mfma_f32_16x16x32_bf16 v[56:59], v[36:39], v[184:187], v[56:59]
	v_mfma_f32_16x16x32_bf16 v[44:47], v[28:31], v[192:195], v[44:47]
	v_mfma_f32_16x16x32_bf16 v[40:43], v[36:39], v[192:195], v[40:43]
	v_mfma_f32_16x16x32_bf16 v[12:15], v[28:31], v[200:203], v[12:15]
	v_mfma_f32_16x16x32_bf16 v[8:11], v[36:39], v[200:203], v[8:11]
	s_barrier
	s_mov_b32 m0, s37
	s_nop 0
	global_load_lds_dwordx4 v144, s[22:23]
	s_mov_b32 m0, s38
	s_nop 0
	global_load_lds_dwordx4 v146, s[22:23]
	s_add_i32 m0, s36, 0x14000
	s_add_u32 s54, s2, 0x40000
	s_addc_u32 s55, s3, 0
	global_load_lds_dwordx4 v168, s[54:55]
	s_add_i32 m0, s36, 0x16000
	s_add_u32 s22, s22, 0x40000
	s_addc_u32 s23, s23, 0
	global_load_lds_dwordx4 v148, s[54:55]
	s_waitcnt vmcnt(6)
	s_barrier
	v_mfma_f32_16x16x32_bf16 v[20:23], v[204:207], v[188:191], v[20:23]
	v_mfma_f32_16x16x32_bf16 v[16:19], v[212:215], v[188:191], v[16:19]
	v_mfma_f32_16x16x32_bf16 v[4:7], v[204:207], v[196:199], v[4:7]
	v_mfma_f32_16x16x32_bf16 v[0:3], v[212:215], v[196:199], v[0:3]
	v_mfma_f32_16x16x32_bf16 v[24:27], v[204:207], v[154:157], v[68:71]
	v_mfma_f32_16x16x32_bf16 v[28:31], v[212:215], v[154:157], v[64:67]
	v_mfma_f32_16x16x32_bf16 v[32:35], v[204:207], v[180:183], v[52:55]
	v_mfma_f32_16x16x32_bf16 v[36:39], v[212:215], v[180:183], v[48:51]
	v_mfma_f32_16x16x32_bf16 v[20:23], v[208:211], v[192:195], v[20:23]
	v_mfma_f32_16x16x32_bf16 v[16:19], v[216:219], v[192:195], v[16:19]
	v_mfma_f32_16x16x32_bf16 v[4:7], v[208:211], v[200:203], v[4:7]
	v_mfma_f32_16x16x32_bf16 v[0:3], v[216:219], v[200:203], v[0:3]
	v_mfma_f32_16x16x32_bf16 v[24:27], v[208:211], v[158:161], v[24:27]
	v_mfma_f32_16x16x32_bf16 v[28:31], v[216:219], v[158:161], v[28:31]
	v_mfma_f32_16x16x32_bf16 v[32:35], v[208:211], v[184:187], v[32:35]
	v_mfma_f32_16x16x32_bf16 v[36:39], v[216:219], v[184:187], v[36:39]
	s_barrier
	ds_read_b128 v[48:51], v164 offset:32768
	ds_read_b128 v[52:55], v164 offset:33792
	ds_read_b128 v[64:67], v164 offset:34816
	ds_read_b128 v[68:71], v164 offset:35840
	ds_read_b128 v[154:157], v165 offset:32768
	ds_read_b128 v[158:161], v165 offset:33792
	ds_read_b128 v[180:183], v165 offset:34816
	ds_read_b128 v[184:187], v165 offset:35840
	ds_read_b128 v[188:191], v165 offset:36864
	ds_read_b128 v[192:195], v165 offset:37888
	ds_read_b128 v[196:199], v165 offset:38912
	ds_read_b128 v[200:203], v165 offset:39936
	s_waitcnt lgkmcnt(8)
	s_barrier
	s_waitcnt lgkmcnt(0)
	v_mfma_f32_16x16x32_bf16 v[140:143], v[48:51], v[154:157], v[140:143]
	v_mfma_f32_16x16x32_bf16 v[136:139], v[64:67], v[154:157], v[136:139]
	v_mfma_f32_16x16x32_bf16 v[124:127], v[48:51], v[180:183], v[124:127]
	v_mfma_f32_16x16x32_bf16 v[120:123], v[64:67], v[180:183], v[120:123]
	v_mfma_f32_16x16x32_bf16 v[108:111], v[48:51], v[188:191], v[108:111]
	v_mfma_f32_16x16x32_bf16 v[104:107], v[64:67], v[188:191], v[104:107]
	v_mfma_f32_16x16x32_bf16 v[92:95], v[48:51], v[196:199], v[92:95]
	v_mfma_f32_16x16x32_bf16 v[88:91], v[64:67], v[196:199], v[88:91]
	v_mfma_f32_16x16x32_bf16 v[140:143], v[52:55], v[158:161], v[140:143]
	v_mfma_f32_16x16x32_bf16 v[136:139], v[68:71], v[158:161], v[136:139]
	v_mfma_f32_16x16x32_bf16 v[124:127], v[52:55], v[184:187], v[124:127]
	v_mfma_f32_16x16x32_bf16 v[120:123], v[68:71], v[184:187], v[120:123]
	v_mfma_f32_16x16x32_bf16 v[108:111], v[52:55], v[192:195], v[108:111]
	v_mfma_f32_16x16x32_bf16 v[104:107], v[68:71], v[192:195], v[104:107]
	v_mfma_f32_16x16x32_bf16 v[92:95], v[52:55], v[200:203], v[92:95]
	v_mfma_f32_16x16x32_bf16 v[88:91], v[68:71], v[200:203], v[88:91]
	s_barrier
	s_mov_b32 m0, s39
	ds_read_b128 v[204:207], v164 offset:49152
	ds_read_b128 v[208:211], v164 offset:50176
	ds_read_b128 v[212:215], v164 offset:51200
	global_load_lds_dwordx4 v144, s[22:23]
	s_mov_b32 m0, s40
	ds_read_b128 v[216:219], v164 offset:52224
	global_load_lds_dwordx4 v146, s[22:23]
	s_barrier
	s_waitcnt lgkmcnt(0)
	v_mfma_f32_16x16x32_bf16 v[132:135], v[204:207], v[154:157], v[132:135]
	v_mfma_f32_16x16x32_bf16 v[128:131], v[212:215], v[154:157], v[128:131]
	v_mfma_f32_16x16x32_bf16 v[116:119], v[204:207], v[180:183], v[116:119]
	v_mfma_f32_16x16x32_bf16 v[112:115], v[212:215], v[180:183], v[112:115]
	v_mfma_f32_16x16x32_bf16 v[100:103], v[204:207], v[188:191], v[100:103]
	v_mfma_f32_16x16x32_bf16 v[96:99], v[212:215], v[188:191], v[96:99]
	v_mfma_f32_16x16x32_bf16 v[84:87], v[204:207], v[196:199], v[84:87]
	v_mfma_f32_16x16x32_bf16 v[80:83], v[212:215], v[196:199], v[80:83]
	v_mfma_f32_16x16x32_bf16 v[132:135], v[208:211], v[158:161], v[132:135]
	v_mfma_f32_16x16x32_bf16 v[128:131], v[216:219], v[158:161], v[128:131]
	v_mfma_f32_16x16x32_bf16 v[116:119], v[208:211], v[184:187], v[116:119]
	v_mfma_f32_16x16x32_bf16 v[112:115], v[216:219], v[184:187], v[112:115]
	v_mfma_f32_16x16x32_bf16 v[100:103], v[208:211], v[192:195], v[100:103]
	v_mfma_f32_16x16x32_bf16 v[96:99], v[216:219], v[192:195], v[96:99]
	v_mfma_f32_16x16x32_bf16 v[84:87], v[208:211], v[200:203], v[84:87]
	v_mfma_f32_16x16x32_bf16 v[80:83], v[216:219], v[200:203], v[80:83]
	s_barrier
	ds_read_b128 v[154:157], v165 offset:49152
	ds_read_b128 v[158:161], v165 offset:50176
	ds_read_b128 v[180:183], v165 offset:51200
	ds_read_b128 v[184:187], v165 offset:52224
	ds_read_b128 v[188:191], v165 offset:53248
	ds_read_b128 v[192:195], v165 offset:54272
	ds_read_b128 v[196:199], v165 offset:55296
	ds_read_b128 v[200:203], v165 offset:56320
	s_add_i32 m0, s36, 0x18000
	s_nop 0
	global_load_lds_dwordx4 v168, s[98:99]
	s_add_i32 m0, s36, 0x1a000
	s_nop 0
	global_load_lds_dwordx4 v148, s[98:99]
	s_barrier
	s_waitcnt lgkmcnt(0)
	v_mfma_f32_16x16x32_bf16 v[76:79], v[48:51], v[154:157], v[76:79]
	v_mfma_f32_16x16x32_bf16 v[72:75], v[64:67], v[154:157], v[72:75]
	v_mfma_f32_16x16x32_bf16 v[60:63], v[48:51], v[180:183], v[60:63]
	v_mfma_f32_16x16x32_bf16 v[56:59], v[64:67], v[180:183], v[56:59]
	v_mfma_f32_16x16x32_bf16 v[44:47], v[48:51], v[188:191], v[44:47]
	v_mfma_f32_16x16x32_bf16 v[40:43], v[64:67], v[188:191], v[40:43]
	v_mfma_f32_16x16x32_bf16 v[12:15], v[48:51], v[196:199], v[12:15]
	v_mfma_f32_16x16x32_bf16 v[8:11], v[64:67], v[196:199], v[8:11]
	v_mfma_f32_16x16x32_bf16 v[76:79], v[52:55], v[158:161], v[76:79]
	v_mfma_f32_16x16x32_bf16 v[72:75], v[68:71], v[158:161], v[72:75]
	v_mfma_f32_16x16x32_bf16 v[60:63], v[52:55], v[184:187], v[60:63]
	v_mfma_f32_16x16x32_bf16 v[56:59], v[68:71], v[184:187], v[56:59]
	v_mfma_f32_16x16x32_bf16 v[44:47], v[52:55], v[192:195], v[44:47]
	v_mfma_f32_16x16x32_bf16 v[40:43], v[68:71], v[192:195], v[40:43]
	v_mfma_f32_16x16x32_bf16 v[12:15], v[52:55], v[200:203], v[12:15]
	v_mfma_f32_16x16x32_bf16 v[8:11], v[68:71], v[200:203], v[8:11]
	s_barrier
	s_mov_b32 m0, s45
	s_nop 0
	global_load_lds_dwordx4 v144, s[100:101]
	s_mov_b32 m0, s46
	s_nop 0
	global_load_lds_dwordx4 v146, s[100:101]
	s_add_i32 m0, s36, 0x1c000
	s_add_u32 s2, s2, 0x40080
	s_addc_u32 s3, s3, 0
	global_load_lds_dwordx4 v168, s[2:3]
	s_add_i32 m0, s36, 0x1e000
	s_add_i32 s52, s52, 2
	global_load_lds_dwordx4 v148, s[2:3]
	s_waitcnt vmcnt(6)
	s_barrier
	v_mfma_f32_16x16x32_bf16 v[24:27], v[204:207], v[154:157], v[24:27]
	v_mfma_f32_16x16x32_bf16 v[68:71], v[208:211], v[158:161], v[24:27]
	v_mfma_f32_16x16x32_bf16 v[24:27], v[212:215], v[154:157], v[28:31]
	v_mfma_f32_16x16x32_bf16 v[64:67], v[216:219], v[158:161], v[24:27]
	v_mfma_f32_16x16x32_bf16 v[24:27], v[204:207], v[180:183], v[32:35]
	v_mfma_f32_16x16x32_bf16 v[52:55], v[208:211], v[184:187], v[24:27]
	v_mfma_f32_16x16x32_bf16 v[24:27], v[212:215], v[180:183], v[36:39]
	v_mfma_f32_16x16x32_bf16 v[20:23], v[204:207], v[188:191], v[20:23]
	v_mfma_f32_16x16x32_bf16 v[16:19], v[212:215], v[188:191], v[16:19]
	v_mfma_f32_16x16x32_bf16 v[4:7], v[204:207], v[196:199], v[4:7]
	v_mfma_f32_16x16x32_bf16 v[0:3], v[212:215], v[196:199], v[0:3]
	v_mfma_f32_16x16x32_bf16 v[48:51], v[216:219], v[184:187], v[24:27]
	v_mfma_f32_16x16x32_bf16 v[20:23], v[208:211], v[192:195], v[20:23]
	v_mfma_f32_16x16x32_bf16 v[16:19], v[216:219], v[192:195], v[16:19]
	v_mfma_f32_16x16x32_bf16 v[4:7], v[208:211], v[200:203], v[4:7]
	v_mfma_f32_16x16x32_bf16 v[0:3], v[216:219], v[200:203], v[0:3]
	s_add_u32 s20, s20, 0x100
	s_addc_u32 s21, s21, 0
	s_add_u32 s50, s50, 0x100
	s_addc_u32 s51, s51, 0
	s_cmp_gt_u32 s52, 13
	s_barrier
	s_cbranch_scc0 .LBB0_123
	s_lshl_b32 s2, s6, 8
	s_add_i32 s3, s2, s43
	s_lshl_b32 s2, s8, 8
	s_cmp_gt_i32 s8, 3
	s_cselect_b64 s[20:21], -1, 0
	s_and_b64 s[22:23], s[20:21], exec
	s_mov_b32 s7, 0x8982000
	s_cselect_b32 s7, s7, 0x7182000
	s_add_u32 s22, s26, s7
	s_addc_u32 s23, s25, 0
	s_add_i32 s7, s6, -16
	v_mov_b32_e32 v160, v163
	v_mov_b32_e32 v24, v162
	s_lshr_b32 s7, s7, 3
	s_add_i32 s96, s7, 1
	v_add_u32_e32 v154, s3, v24
	s_lshl_b64 s[50:51], s[96:97], 11
	v_ashrrev_i32_e32 v155, 31, v154
	s_cmp_gt_i32 s6, 15
	v_lshl_add_u64 v[156:157], v[154:155], 2, s[10:11]
	s_cselect_b32 s7, s51, 0
	s_cselect_b32 s6, s50, 0
	global_load_dword v166, v[156:157], off
	global_load_dword v191, v[156:157], off offset:64
	global_load_dword v192, v[156:157], off offset:128
	global_load_dword v193, v[156:157], off offset:192
	global_load_dword v194, v[156:157], off offset:512
	global_load_dword v195, v[156:157], off offset:576
	global_load_dword v196, v[156:157], off offset:640
	global_load_dword v197, v[156:157], off offset:704
	s_lshl_b64 s[6:7], s[6:7], 2
	s_add_u32 s9, s41, s6
	s_addc_u32 s13, s42, s7
	s_ashr_i32 s3, s2, 31
	s_lshl_b64 s[6:7], s[2:3], 2
	s_add_u32 s3, s9, s6
	s_addc_u32 s7, s13, s7
	v_lshlrev_b32_e32 v158, 3, v160
	s_add_u32 s6, s3, s49
	s_addc_u32 s7, s7, 0
	v_ashrrev_i32_e32 v159, 31, v158
	v_lshl_add_u64 v[24:25], v[158:159], 2, s[6:7]
	global_load_dwordx4 v[36:39], v[24:25], off
	global_load_dwordx4 v[32:35], v[24:25], off offset:16
	global_load_dwordx4 v[28:31], v[24:25], off offset:512
	s_nop 0
	global_load_dwordx4 v[24:27], v[24:25], off offset:528
	s_and_b32 s2, s2, 0x300
	s_or_b32 s2, s2, s44
	v_add_u32_e32 v158, s2, v158
	v_cmp_eq_u32_e64 s[6:7], 0, v160
	v_lshlrev_b64 v[160:161], 11, v[154:155]
	s_cmp_lt_i32 s8, 4
	s_waitcnt vmcnt(0)
	v_ashrrev_i32_e32 v159, 31, v158
	v_lshl_add_u64 v[158:159], v[158:159], 1, s[22:23]
	v_lshl_add_u64 v[160:161], v[158:159], 0, v[160:161]
	v_lshl_add_u64 v[156:157], v[154:155], 2, s[0:1]
	s_and_b64 s[6:7], s[6:7], s[20:21]
	s_mov_b64 s[2:3], 0x8000
	s_mov_b64 s[50:51], 0x28000
	v_mov_b32_e32 v180, 0xc0135761
	v_mov_b32_e32 v181, 0xc0135761
	v_mov_b32_e32 v182, 0xbdd2d3e7
	v_mov_b32_e32 v183, 0xbdd2d3e7
	v_fmamk_f32 v166, v166, 0x3a800000, v225
	v_fmamk_f32 v190, v191, 0x3a800000, v225
	v_fmamk_f32 v192, v192, 0x3a800000, v225
	v_fmamk_f32 v188, v193, 0x3a800000, v225
	v_fmamk_f32 v194, v194, 0x3a800000, v225
	v_fmamk_f32 v186, v195, 0x3a800000, v225
	v_fmamk_f32 v196, v196, 0x3a800000, v225
	v_fmamk_f32 v184, v197, 0x3a800000, v225
	v_rsq_f32_e32 v166, v166
	v_rsq_f32_e32 v190, v190
	v_rsq_f32_e32 v192, v192
	v_rsq_f32_e32 v188, v188
	v_rsq_f32_e32 v194, v194
	v_rsq_f32_e32 v186, v186
	v_rsq_f32_e32 v196, v196
	v_rsq_f32_e32 v184, v184
	v_pk_fma_f32 v[140:141], v[140:141], v[166:167], v[36:37] op_sel_hi:[1,0,1]
	v_pk_fma_f32 v[142:143], v[142:143], v[166:167], v[38:39] op_sel_hi:[1,0,1]
	v_pk_fma_f32 v[136:137], v[136:137], v[166:167], v[32:33] op_sel_hi:[1,0,1]
	v_pk_fma_f32 v[138:139], v[138:139], v[166:167], v[34:35] op_sel_hi:[1,0,1]
	v_pk_fma_f32 v[132:133], v[132:133], v[166:167], v[28:29] op_sel_hi:[1,0,1]
	v_pk_fma_f32 v[134:135], v[134:135], v[166:167], v[30:31] op_sel_hi:[1,0,1]
	v_pk_fma_f32 v[128:129], v[128:129], v[166:167], v[24:25] op_sel_hi:[1,0,1]
	v_pk_fma_f32 v[130:131], v[130:131], v[166:167], v[26:27] op_sel_hi:[1,0,1]
	v_pk_fma_f32 v[124:125], v[124:125], v[190:191], v[36:37] op_sel_hi:[1,0,1]
	v_pk_fma_f32 v[126:127], v[126:127], v[190:191], v[38:39] op_sel_hi:[1,0,1]
	v_pk_fma_f32 v[120:121], v[120:121], v[190:191], v[32:33] op_sel_hi:[1,0,1]
	v_pk_fma_f32 v[122:123], v[122:123], v[190:191], v[34:35] op_sel_hi:[1,0,1]
	v_pk_fma_f32 v[116:117], v[116:117], v[190:191], v[28:29] op_sel_hi:[1,0,1]
	v_pk_fma_f32 v[118:119], v[118:119], v[190:191], v[30:31] op_sel_hi:[1,0,1]
	v_pk_fma_f32 v[112:113], v[112:113], v[190:191], v[24:25] op_sel_hi:[1,0,1]
	v_pk_fma_f32 v[114:115], v[114:115], v[190:191], v[26:27] op_sel_hi:[1,0,1]
	v_pk_fma_f32 v[108:109], v[108:109], v[192:193], v[36:37] op_sel_hi:[1,0,1]
	v_pk_fma_f32 v[110:111], v[110:111], v[192:193], v[38:39] op_sel_hi:[1,0,1]
	v_pk_fma_f32 v[104:105], v[104:105], v[192:193], v[32:33] op_sel_hi:[1,0,1]
	v_pk_fma_f32 v[106:107], v[106:107], v[192:193], v[34:35] op_sel_hi:[1,0,1]
	v_pk_fma_f32 v[100:101], v[100:101], v[192:193], v[28:29] op_sel_hi:[1,0,1]
	v_pk_fma_f32 v[102:103], v[102:103], v[192:193], v[30:31] op_sel_hi:[1,0,1]
	v_pk_fma_f32 v[96:97], v[96:97], v[192:193], v[24:25] op_sel_hi:[1,0,1]
	v_pk_fma_f32 v[98:99], v[98:99], v[192:193], v[26:27] op_sel_hi:[1,0,1]
	v_pk_fma_f32 v[92:93], v[92:93], v[188:189], v[36:37] op_sel_hi:[1,0,1]
	v_pk_fma_f32 v[94:95], v[94:95], v[188:189], v[38:39] op_sel_hi:[1,0,1]
	v_pk_fma_f32 v[88:89], v[88:89], v[188:189], v[32:33] op_sel_hi:[1,0,1]
	v_pk_fma_f32 v[90:91], v[90:91], v[188:189], v[34:35] op_sel_hi:[1,0,1]
	v_pk_fma_f32 v[84:85], v[84:85], v[188:189], v[28:29] op_sel_hi:[1,0,1]
	v_pk_fma_f32 v[86:87], v[86:87], v[188:189], v[30:31] op_sel_hi:[1,0,1]
	v_pk_fma_f32 v[80:81], v[80:81], v[188:189], v[24:25] op_sel_hi:[1,0,1]
	v_pk_fma_f32 v[82:83], v[82:83], v[188:189], v[26:27] op_sel_hi:[1,0,1]
	v_pk_fma_f32 v[76:77], v[76:77], v[194:195], v[36:37] op_sel_hi:[1,0,1]
	v_pk_fma_f32 v[78:79], v[78:79], v[194:195], v[38:39] op_sel_hi:[1,0,1]
	v_pk_fma_f32 v[72:73], v[72:73], v[194:195], v[32:33] op_sel_hi:[1,0,1]
	v_pk_fma_f32 v[74:75], v[74:75], v[194:195], v[34:35] op_sel_hi:[1,0,1]
	v_pk_fma_f32 v[68:69], v[68:69], v[194:195], v[28:29] op_sel_hi:[1,0,1]
	v_pk_fma_f32 v[70:71], v[70:71], v[194:195], v[30:31] op_sel_hi:[1,0,1]
	v_pk_fma_f32 v[64:65], v[64:65], v[194:195], v[24:25] op_sel_hi:[1,0,1]
	v_pk_fma_f32 v[66:67], v[66:67], v[194:195], v[26:27] op_sel_hi:[1,0,1]
	v_pk_fma_f32 v[60:61], v[60:61], v[186:187], v[36:37] op_sel_hi:[1,0,1]
	v_pk_fma_f32 v[62:63], v[62:63], v[186:187], v[38:39] op_sel_hi:[1,0,1]
	v_pk_fma_f32 v[56:57], v[56:57], v[186:187], v[32:33] op_sel_hi:[1,0,1]
	v_pk_fma_f32 v[58:59], v[58:59], v[186:187], v[34:35] op_sel_hi:[1,0,1]
	v_pk_fma_f32 v[52:53], v[52:53], v[186:187], v[28:29] op_sel_hi:[1,0,1]
	v_pk_fma_f32 v[54:55], v[54:55], v[186:187], v[30:31] op_sel_hi:[1,0,1]
	v_pk_fma_f32 v[48:49], v[48:49], v[186:187], v[24:25] op_sel_hi:[1,0,1]
	v_pk_fma_f32 v[50:51], v[50:51], v[186:187], v[26:27] op_sel_hi:[1,0,1]
	v_pk_fma_f32 v[44:45], v[44:45], v[196:197], v[36:37] op_sel_hi:[1,0,1]
	v_pk_fma_f32 v[46:47], v[46:47], v[196:197], v[38:39] op_sel_hi:[1,0,1]
	v_pk_fma_f32 v[40:41], v[40:41], v[196:197], v[32:33] op_sel_hi:[1,0,1]
	v_pk_fma_f32 v[42:43], v[42:43], v[196:197], v[34:35] op_sel_hi:[1,0,1]
	v_pk_fma_f32 v[20:21], v[20:21], v[196:197], v[28:29] op_sel_hi:[1,0,1]
	v_pk_fma_f32 v[22:23], v[22:23], v[196:197], v[30:31] op_sel_hi:[1,0,1]
	v_pk_fma_f32 v[16:17], v[16:17], v[196:197], v[24:25] op_sel_hi:[1,0,1]
	v_pk_fma_f32 v[18:19], v[18:19], v[196:197], v[26:27] op_sel_hi:[1,0,1]
	v_pk_fma_f32 v[12:13], v[12:13], v[184:185], v[36:37] op_sel_hi:[1,0,1]
	v_pk_fma_f32 v[14:15], v[14:15], v[184:185], v[38:39] op_sel_hi:[1,0,1]
	v_pk_fma_f32 v[8:9], v[8:9], v[184:185], v[32:33] op_sel_hi:[1,0,1]
	v_pk_fma_f32 v[10:11], v[10:11], v[184:185], v[34:35] op_sel_hi:[1,0,1]
	v_pk_fma_f32 v[4:5], v[4:5], v[184:185], v[28:29] op_sel_hi:[1,0,1]
	v_pk_fma_f32 v[6:7], v[6:7], v[184:185], v[30:31] op_sel_hi:[1,0,1]
	v_pk_fma_f32 v[0:1], v[0:1], v[184:185], v[24:25] op_sel_hi:[1,0,1]
	v_pk_fma_f32 v[2:3], v[2:3], v[184:185], v[26:27] op_sel_hi:[1,0,1]
	v_pk_mul_f32 v[24:25], v[140:141], v[140:141]
	v_pk_mul_f32 v[26:27], v[142:143], v[142:143]
	v_pk_mul_f32 v[28:29], v[136:137], v[136:137]
	v_pk_mul_f32 v[30:31], v[138:139], v[138:139]
	v_pk_mul_f32 v[32:33], v[132:133], v[132:133]
	v_pk_mul_f32 v[34:35], v[134:135], v[134:135]
	v_pk_mul_f32 v[36:37], v[128:129], v[128:129]
	v_pk_mul_f32 v[38:39], v[130:131], v[130:131]
	v_pk_fma_f32 v[24:25], v[24:25], v[182:183], v[180:181]
	v_pk_fma_f32 v[26:27], v[26:27], v[182:183], v[180:181]
	v_pk_fma_f32 v[28:29], v[28:29], v[182:183], v[180:181]
	v_pk_fma_f32 v[30:31], v[30:31], v[182:183], v[180:181]
	v_pk_fma_f32 v[32:33], v[32:33], v[182:183], v[180:181]
	v_pk_fma_f32 v[34:35], v[34:35], v[182:183], v[180:181]
	v_pk_fma_f32 v[36:37], v[36:37], v[182:183], v[180:181]
	v_pk_fma_f32 v[38:39], v[38:39], v[182:183], v[180:181]
	v_pk_mul_f32 v[24:25], v[24:25], v[140:141]
	v_pk_mul_f32 v[26:27], v[26:27], v[142:143]
	v_pk_mul_f32 v[28:29], v[28:29], v[136:137]
	v_pk_mul_f32 v[30:31], v[30:31], v[138:139]
	v_pk_mul_f32 v[32:33], v[32:33], v[132:133]
	v_pk_mul_f32 v[34:35], v[34:35], v[134:135]
	v_pk_mul_f32 v[36:37], v[36:37], v[128:129]
	v_pk_mul_f32 v[38:39], v[38:39], v[130:131]
	v_exp_f32_e32 v24, v24
	v_exp_f32_e32 v25, v25
	v_exp_f32_e32 v26, v26
	v_exp_f32_e32 v27, v27
	v_exp_f32_e32 v28, v28
	v_exp_f32_e32 v29, v29
	v_exp_f32_e32 v30, v30
	v_exp_f32_e32 v31, v31
	v_exp_f32_e32 v32, v32
	v_exp_f32_e32 v33, v33
	v_exp_f32_e32 v34, v34
	v_exp_f32_e32 v35, v35
	v_exp_f32_e32 v36, v36
	v_exp_f32_e32 v37, v37
	v_exp_f32_e32 v38, v38
	v_exp_f32_e32 v39, v39
	v_pk_add_f32 v[24:25], v[24:25], 1.0 op_sel_hi:[1,0]
	v_pk_add_f32 v[26:27], v[26:27], 1.0 op_sel_hi:[1,0]
	v_pk_add_f32 v[28:29], v[28:29], 1.0 op_sel_hi:[1,0]
	v_pk_add_f32 v[30:31], v[30:31], 1.0 op_sel_hi:[1,0]
	v_pk_add_f32 v[32:33], v[32:33], 1.0 op_sel_hi:[1,0]
	v_pk_add_f32 v[34:35], v[34:35], 1.0 op_sel_hi:[1,0]
	v_pk_add_f32 v[36:37], v[36:37], 1.0 op_sel_hi:[1,0]
	v_pk_add_f32 v[38:39], v[38:39], 1.0 op_sel_hi:[1,0]
	v_rcp_f32_e32 v24, v24
	v_rcp_f32_e32 v25, v25
	v_rcp_f32_e32 v26, v26
	v_rcp_f32_e32 v27, v27
	v_rcp_f32_e32 v28, v28
	v_rcp_f32_e32 v29, v29
	v_rcp_f32_e32 v30, v30
	v_rcp_f32_e32 v31, v31
	v_rcp_f32_e32 v32, v32
	v_rcp_f32_e32 v33, v33
	v_rcp_f32_e32 v34, v34
	v_rcp_f32_e32 v35, v35
	v_rcp_f32_e32 v36, v36
	v_rcp_f32_e32 v37, v37
	v_rcp_f32_e32 v38, v38
	v_rcp_f32_e32 v39, v39
	v_pk_mul_f32 v[140:141], v[140:141], v[24:25]
	v_pk_mul_f32 v[142:143], v[142:143], v[26:27]
	v_pk_mul_f32 v[136:137], v[136:137], v[28:29]
	v_pk_mul_f32 v[138:139], v[138:139], v[30:31]
	v_pk_mul_f32 v[132:133], v[132:133], v[32:33]
	v_pk_mul_f32 v[134:135], v[134:135], v[34:35]
	v_pk_mul_f32 v[128:129], v[128:129], v[36:37]
	v_pk_mul_f32 v[130:131], v[130:131], v[38:39]
	v_cvt_pk_bf16_f32 v24, v140, v141
	v_cvt_pk_bf16_f32 v25, v142, v143
	v_cvt_pk_bf16_f32 v26, v136, v137
	v_cvt_pk_bf16_f32 v27, v138, v139
	v_cvt_pk_bf16_f32 v28, v132, v133
	v_cvt_pk_bf16_f32 v29, v134, v135
	v_cvt_pk_bf16_f32 v30, v128, v129
	v_cvt_pk_bf16_f32 v31, v130, v131
	global_store_dwordx4 v[160:161], v[24:27], off
	global_store_dwordx4 v[160:161], v[28:31], off offset:256
	s_and_b64 vcc, exec, s[20:21]
	s_cbranch_vccz .Lio_skip_0
	v_pk_mul_f32 v[32:33], v[140:141], v[140:141]
	v_pk_fma_f32 v[32:33], v[142:143], v[142:143], v[32:33]
	v_pk_fma_f32 v[32:33], v[136:137], v[136:137], v[32:33]
	v_pk_fma_f32 v[32:33], v[138:139], v[138:139], v[32:33]
	v_pk_fma_f32 v[32:33], v[132:133], v[132:133], v[32:33]
	v_pk_fma_f32 v[32:33], v[134:135], v[134:135], v[32:33]
	v_pk_fma_f32 v[32:33], v[128:129], v[128:129], v[32:33]
	v_pk_fma_f32 v[32:33], v[130:131], v[130:131], v[32:33]
	s_nop 0
	v_add_f32_e32 v32, v32, v33
	v_mov_b32_e32 v33, v32
	s_nop 1
	v_permlane16_swap_b32_e32 v32, v33
	v_add_f32_e32 v32, v32, v33
	v_mov_b32_e32 v33, v32
	s_nop 1
	v_permlane32_swap_b32_e32 v32, v33
	s_and_saveexec_b64 vcc, s[6:7]
	v_add_f32_e32 v32, v32, v33
	global_atomic_add_f32 v[156:157], v32, off
	s_mov_b64 exec, vcc

.Lie_done_b:
.LBB0_354:
	s_ashr_i32 s31, s30, 31
	v_cmp_lt_i64_e32 vcc, s[8:9], v[170:171]
	s_lshl_b64 s[8:9], s[30:31], 19
	s_add_u32 s34, s52, s8
	s_addc_u32 s35, s53, s9
	s_and_b64 s[8:9], vcc, exec
	s_cselect_b32 s1, s35, s7
	s_cselect_b32 s31, s34, s6
	s_ashr_i32 s29, s28, 31
	s_lshl_b64 s[8:9], s[28:29], 19
	s_add_u32 s36, s43, s8
	s_addc_u32 s37, s42, s9
	s_and_b64 s[8:9], vcc, exec
	s_cselect_b32 s29, s37, s3
	s_cselect_b32 s38, s36, s2
	s_add_u32 s6, s6, 0x40080
	s_addc_u32 s7, s7, 0
	s_add_u32 s39, s2, 0x100
	s_addc_u32 s40, s3, 0
	s_mov_b32 s41, -2
	s_add_u32 s2, s6, 0xfffc0080
	s_addc_u32 s3, s7, -1
	ds_read_b128 v[128:131], v208
	ds_read_b128 v[132:135], v208 offset:1024
	ds_read_b128 v[136:139], v208 offset:2048
	ds_read_b128 v[140:143], v208 offset:3072
	s_cmp_eq_u32 s41, 12
	s_cselect_b32 s9, s1, s3
	s_cselect_b32 s8, s31, s2
	s_cselect_b32 s3, s29, s40
	s_cselect_b32 s2, s38, s39
	ds_read_b128 v[144:147], v209
	ds_read_b128 v[148:151], v209 offset:1024
	ds_read_b128 v[152:155], v209 offset:2048
	ds_read_b128 v[156:159], v209 offset:3072
	ds_read_b128 v[180:183], v209 offset:4096
	ds_read_b128 v[184:187], v209 offset:5120
	ds_read_b128 v[188:191], v209 offset:6144
	ds_read_b128 v[192:195], v209 offset:7168
	s_waitcnt lgkmcnt(8)
	s_barrier
	s_waitcnt lgkmcnt(0)
	v_mfma_f32_16x16x32_bf16 v[124:127], v[128:131], v[144:147], 0
	v_mfma_f32_16x16x32_bf16 v[120:123], v[136:139], v[144:147], 0
	v_mfma_f32_16x16x32_bf16 v[116:119], v[128:131], v[152:155], 0
	v_mfma_f32_16x16x32_bf16 v[112:115], v[136:139], v[152:155], 0
	v_mfma_f32_16x16x32_bf16 v[100:103], v[128:131], v[180:183], 0
	v_mfma_f32_16x16x32_bf16 v[96:99], v[136:139], v[180:183], 0
	v_mfma_f32_16x16x32_bf16 v[84:87], v[128:131], v[188:191], 0
	v_mfma_f32_16x16x32_bf16 v[80:83], v[136:139], v[188:191], 0
	v_mfma_f32_16x16x32_bf16 v[124:127], v[132:135], v[148:151], v[124:127]
	v_mfma_f32_16x16x32_bf16 v[120:123], v[140:143], v[148:151], v[120:123]
	v_mfma_f32_16x16x32_bf16 v[116:119], v[132:135], v[156:159], v[116:119]
	v_mfma_f32_16x16x32_bf16 v[112:115], v[140:143], v[156:159], v[112:115]
	v_mfma_f32_16x16x32_bf16 v[100:103], v[132:135], v[184:187], v[100:103]
	v_mfma_f32_16x16x32_bf16 v[96:99], v[140:143], v[184:187], v[96:99]
	v_mfma_f32_16x16x32_bf16 v[84:87], v[132:135], v[192:195], v[84:87]
	v_mfma_f32_16x16x32_bf16 v[80:83], v[140:143], v[192:195], v[80:83]
	s_barrier
	s_add_i32 m0, s21, 0xc000
	ds_read_b128 v[196:199], v208 offset:16384
	ds_read_b128 v[200:203], v208 offset:17408
	ds_read_b128 v[210:213], v208 offset:18432
	global_load_lds_dwordx4 v164, s[6:7]
	s_add_i32 m0, s21, 0xe000
	ds_read_b128 v[214:217], v208 offset:19456
	global_load_lds_dwordx4 v166, s[6:7]
	s_add_u32 s98, s2, 0x80
	s_addc_u32 s99, s3, 0
	s_barrier
	s_waitcnt lgkmcnt(0)
	v_mfma_f32_16x16x32_bf16 v[108:111], v[196:199], v[144:147], 0
	v_mfma_f32_16x16x32_bf16 v[104:107], v[210:213], v[144:147], 0
	v_mfma_f32_16x16x32_bf16 v[92:95], v[196:199], v[152:155], 0
	v_mfma_f32_16x16x32_bf16 v[88:91], v[210:213], v[152:155], 0
	v_mfma_f32_16x16x32_bf16 v[76:79], v[196:199], v[180:183], 0
	v_mfma_f32_16x16x32_bf16 v[72:75], v[210:213], v[180:183], 0
	v_mfma_f32_16x16x32_bf16 v[68:71], v[196:199], v[188:191], 0
	v_mfma_f32_16x16x32_bf16 v[64:67], v[210:213], v[188:191], 0
	v_mfma_f32_16x16x32_bf16 v[108:111], v[200:203], v[148:151], v[108:111]
	v_mfma_f32_16x16x32_bf16 v[104:107], v[214:217], v[148:151], v[104:107]
	v_mfma_f32_16x16x32_bf16 v[92:95], v[200:203], v[156:159], v[92:95]
	v_mfma_f32_16x16x32_bf16 v[88:91], v[214:217], v[156:159], v[88:91]
	v_mfma_f32_16x16x32_bf16 v[76:79], v[200:203], v[184:187], v[76:79]
	v_mfma_f32_16x16x32_bf16 v[72:75], v[214:217], v[184:187], v[72:75]
	v_mfma_f32_16x16x32_bf16 v[68:71], v[200:203], v[192:195], v[68:71]
	v_mfma_f32_16x16x32_bf16 v[64:67], v[214:217], v[192:195], v[64:67]
	s_add_u32 s100, s8, 0x80
	s_addc_u32 s101, s9, 0
	s_barrier
	ds_read_b128 v[144:147], v209 offset:16384
	ds_read_b128 v[148:151], v209 offset:17408
	ds_read_b128 v[152:155], v209 offset:18432
	ds_read_b128 v[156:159], v209 offset:19456
	ds_read_b128 v[180:183], v209 offset:20480
	ds_read_b128 v[184:187], v209 offset:21504
	ds_read_b128 v[188:191], v209 offset:22528
	ds_read_b128 v[192:195], v209 offset:23552
	s_add_i32 m0, s54, 0x10000
	s_nop 0
	global_load_lds_dwordx4 v160, s[2:3]
	s_add_i32 m0, s54, 0x12000
	s_nop 0
	global_load_lds_dwordx4 v162, s[2:3]
	s_barrier
	s_waitcnt lgkmcnt(0)
	v_mfma_f32_16x16x32_bf16 v[60:63], v[128:131], v[144:147], 0
	v_mfma_f32_16x16x32_bf16 v[56:59], v[136:139], v[144:147], 0
	v_mfma_f32_16x16x32_bf16 v[52:55], v[128:131], v[152:155], 0
	v_mfma_f32_16x16x32_bf16 v[48:51], v[136:139], v[152:155], 0
	v_mfma_f32_16x16x32_bf16 v[36:39], v[128:131], v[180:183], 0
	v_mfma_f32_16x16x32_bf16 v[32:35], v[136:139], v[180:183], 0
	v_mfma_f32_16x16x32_bf16 v[20:23], v[128:131], v[188:191], 0
	v_mfma_f32_16x16x32_bf16 v[16:19], v[136:139], v[188:191], 0
	v_mfma_f32_16x16x32_bf16 v[60:63], v[132:135], v[148:151], v[60:63]
	v_mfma_f32_16x16x32_bf16 v[56:59], v[140:143], v[148:151], v[56:59]
	v_mfma_f32_16x16x32_bf16 v[52:55], v[132:135], v[156:159], v[52:55]
	v_mfma_f32_16x16x32_bf16 v[48:51], v[140:143], v[156:159], v[48:51]
	v_mfma_f32_16x16x32_bf16 v[36:39], v[132:135], v[184:187], v[36:39]
	v_mfma_f32_16x16x32_bf16 v[32:35], v[140:143], v[184:187], v[32:35]
	v_mfma_f32_16x16x32_bf16 v[20:23], v[132:135], v[192:195], v[20:23]
	v_mfma_f32_16x16x32_bf16 v[16:19], v[140:143], v[192:195], v[16:19]
	s_barrier
	s_mov_b32 m0, s21
	s_nop 0
	global_load_lds_dwordx4 v160, s[8:9]
	s_mov_b32 m0, s55
	s_nop 0
	global_load_lds_dwordx4 v162, s[8:9]
	s_add_i32 m0, s54, 0x14000
	s_add_u32 s64, s2, 0x40000
	s_addc_u32 s65, s3, 0
	global_load_lds_dwordx4 v160, s[64:65]
	s_add_i32 m0, s54, 0x16000
	s_add_u32 s8, s8, 0x40000
	s_addc_u32 s9, s9, 0
	global_load_lds_dwordx4 v162, s[64:65]
	s_waitcnt vmcnt(6)
	s_barrier
	v_mfma_f32_16x16x32_bf16 v[44:47], v[196:199], v[144:147], 0
	v_mfma_f32_16x16x32_bf16 v[40:43], v[210:213], v[144:147], 0
	v_mfma_f32_16x16x32_bf16 v[28:31], v[196:199], v[152:155], 0
	v_mfma_f32_16x16x32_bf16 v[24:27], v[210:213], v[152:155], 0
	v_mfma_f32_16x16x32_bf16 v[12:15], v[196:199], v[180:183], 0
	v_mfma_f32_16x16x32_bf16 v[8:11], v[210:213], v[180:183], 0
	v_mfma_f32_16x16x32_bf16 v[4:7], v[196:199], v[188:191], 0
	v_mfma_f32_16x16x32_bf16 v[0:3], v[210:213], v[188:191], 0
	v_mfma_f32_16x16x32_bf16 v[44:47], v[200:203], v[148:151], v[44:47]
	v_mfma_f32_16x16x32_bf16 v[40:43], v[214:217], v[148:151], v[40:43]
	v_mfma_f32_16x16x32_bf16 v[28:31], v[200:203], v[156:159], v[28:31]
	v_mfma_f32_16x16x32_bf16 v[24:27], v[214:217], v[156:159], v[24:27]
	v_mfma_f32_16x16x32_bf16 v[12:15], v[200:203], v[184:187], v[12:15]
	v_mfma_f32_16x16x32_bf16 v[8:11], v[214:217], v[184:187], v[8:11]
	v_mfma_f32_16x16x32_bf16 v[4:7], v[200:203], v[192:195], v[4:7]
	v_mfma_f32_16x16x32_bf16 v[0:3], v[214:217], v[192:195], v[0:3]
	s_barrier
	ds_read_b128 v[128:131], v208 offset:32768
	ds_read_b128 v[132:135], v208 offset:33792
	ds_read_b128 v[136:139], v208 offset:34816
	ds_read_b128 v[140:143], v208 offset:35840
	ds_read_b128 v[144:147], v209 offset:32768
	ds_read_b128 v[148:151], v209 offset:33792
	ds_read_b128 v[152:155], v209 offset:34816
	ds_read_b128 v[156:159], v209 offset:35840
	ds_read_b128 v[180:183], v209 offset:36864
	ds_read_b128 v[184:187], v209 offset:37888
	ds_read_b128 v[188:191], v209 offset:38912
	ds_read_b128 v[192:195], v209 offset:39936
	s_waitcnt lgkmcnt(8)
	s_barrier
	s_waitcnt lgkmcnt(0)
	v_mfma_f32_16x16x32_bf16 v[124:127], v[128:131], v[144:147], v[124:127]
	v_mfma_f32_16x16x32_bf16 v[120:123], v[136:139], v[144:147], v[120:123]
	v_mfma_f32_16x16x32_bf16 v[116:119], v[128:131], v[152:155], v[116:119]
	v_mfma_f32_16x16x32_bf16 v[112:115], v[136:139], v[152:155], v[112:115]
	v_mfma_f32_16x16x32_bf16 v[100:103], v[128:131], v[180:183], v[100:103]
	v_mfma_f32_16x16x32_bf16 v[96:99], v[136:139], v[180:183], v[96:99]
	v_mfma_f32_16x16x32_bf16 v[84:87], v[128:131], v[188:191], v[84:87]
	v_mfma_f32_16x16x32_bf16 v[80:83], v[136:139], v[188:191], v[80:83]
	v_mfma_f32_16x16x32_bf16 v[124:127], v[132:135], v[148:151], v[124:127]
	v_mfma_f32_16x16x32_bf16 v[120:123], v[140:143], v[148:151], v[120:123]
	v_mfma_f32_16x16x32_bf16 v[116:119], v[132:135], v[156:159], v[116:119]
	v_mfma_f32_16x16x32_bf16 v[112:115], v[140:143], v[156:159], v[112:115]
	v_mfma_f32_16x16x32_bf16 v[100:103], v[132:135], v[184:187], v[100:103]
	v_mfma_f32_16x16x32_bf16 v[96:99], v[140:143], v[184:187], v[96:99]
	v_mfma_f32_16x16x32_bf16 v[84:87], v[132:135], v[192:195], v[84:87]
	v_mfma_f32_16x16x32_bf16 v[80:83], v[140:143], v[192:195], v[80:83]
	s_barrier
	s_mov_b32 m0, s56
	ds_read_b128 v[196:199], v208 offset:49152
	ds_read_b128 v[200:203], v208 offset:50176
	ds_read_b128 v[210:213], v208 offset:51200
	global_load_lds_dwordx4 v160, s[8:9]
	s_mov_b32 m0, s57
	ds_read_b128 v[214:217], v208 offset:52224
	global_load_lds_dwordx4 v162, s[8:9]
	s_barrier
	s_waitcnt lgkmcnt(0)
	v_mfma_f32_16x16x32_bf16 v[108:111], v[196:199], v[144:147], v[108:111]
	v_mfma_f32_16x16x32_bf16 v[104:107], v[210:213], v[144:147], v[104:107]
	v_mfma_f32_16x16x32_bf16 v[92:95], v[196:199], v[152:155], v[92:95]
	v_mfma_f32_16x16x32_bf16 v[88:91], v[210:213], v[152:155], v[88:91]
	v_mfma_f32_16x16x32_bf16 v[76:79], v[196:199], v[180:183], v[76:79]
	v_mfma_f32_16x16x32_bf16 v[72:75], v[210:213], v[180:183], v[72:75]
	v_mfma_f32_16x16x32_bf16 v[68:71], v[196:199], v[188:191], v[68:71]
	v_mfma_f32_16x16x32_bf16 v[64:67], v[210:213], v[188:191], v[64:67]
	v_mfma_f32_16x16x32_bf16 v[108:111], v[200:203], v[148:151], v[108:111]
	v_mfma_f32_16x16x32_bf16 v[104:107], v[214:217], v[148:151], v[104:107]
	v_mfma_f32_16x16x32_bf16 v[92:95], v[200:203], v[156:159], v[92:95]
	v_mfma_f32_16x16x32_bf16 v[88:91], v[214:217], v[156:159], v[88:91]
	v_mfma_f32_16x16x32_bf16 v[76:79], v[200:203], v[184:187], v[76:79]
	v_mfma_f32_16x16x32_bf16 v[72:75], v[214:217], v[184:187], v[72:75]
	v_mfma_f32_16x16x32_bf16 v[68:71], v[200:203], v[192:195], v[68:71]
	v_mfma_f32_16x16x32_bf16 v[64:67], v[214:217], v[192:195], v[64:67]
	s_barrier
	ds_read_b128 v[144:147], v209 offset:49152
	ds_read_b128 v[148:151], v209 offset:50176
	ds_read_b128 v[152:155], v209 offset:51200
	ds_read_b128 v[156:159], v209 offset:52224
	ds_read_b128 v[180:183], v209 offset:53248
	ds_read_b128 v[184:187], v209 offset:54272
	ds_read_b128 v[188:191], v209 offset:55296
	ds_read_b128 v[192:195], v209 offset:56320
	s_add_i32 m0, s54, 0x18000
	s_nop 0
	global_load_lds_dwordx4 v160, s[98:99]
	s_add_i32 m0, s54, 0x1a000
	s_nop 0
	global_load_lds_dwordx4 v162, s[98:99]
	s_barrier
	s_waitcnt lgkmcnt(0)
	v_mfma_f32_16x16x32_bf16 v[60:63], v[128:131], v[144:147], v[60:63]
	v_mfma_f32_16x16x32_bf16 v[56:59], v[136:139], v[144:147], v[56:59]
	v_mfma_f32_16x16x32_bf16 v[52:55], v[128:131], v[152:155], v[52:55]
	v_mfma_f32_16x16x32_bf16 v[48:51], v[136:139], v[152:155], v[48:51]
	v_mfma_f32_16x16x32_bf16 v[36:39], v[128:131], v[180:183], v[36:39]
	v_mfma_f32_16x16x32_bf16 v[32:35], v[136:139], v[180:183], v[32:35]
	v_mfma_f32_16x16x32_bf16 v[20:23], v[128:131], v[188:191], v[20:23]
	v_mfma_f32_16x16x32_bf16 v[16:19], v[136:139], v[188:191], v[16:19]
	v_mfma_f32_16x16x32_bf16 v[60:63], v[132:135], v[148:151], v[60:63]
	v_mfma_f32_16x16x32_bf16 v[56:59], v[140:143], v[148:151], v[56:59]
	v_mfma_f32_16x16x32_bf16 v[52:55], v[132:135], v[156:159], v[52:55]
	v_mfma_f32_16x16x32_bf16 v[48:51], v[140:143], v[156:159], v[48:51]
	v_mfma_f32_16x16x32_bf16 v[36:39], v[132:135], v[184:187], v[36:39]
	v_mfma_f32_16x16x32_bf16 v[32:35], v[140:143], v[184:187], v[32:35]
	v_mfma_f32_16x16x32_bf16 v[20:23], v[132:135], v[192:195], v[20:23]
	v_mfma_f32_16x16x32_bf16 v[16:19], v[140:143], v[192:195], v[16:19]
	s_barrier
	s_mov_b32 m0, s60
	s_nop 0
	global_load_lds_dwordx4 v160, s[100:101]
	s_mov_b32 m0, s61
	s_nop 0
	global_load_lds_dwordx4 v162, s[100:101]
	s_add_i32 m0, s54, 0x1c000
	s_add_u32 s2, s2, 0x40080
	s_addc_u32 s3, s3, 0
	global_load_lds_dwordx4 v160, s[2:3]
	s_add_i32 m0, s54, 0x1e000
	s_add_i32 s41, s41, 2
	global_load_lds_dwordx4 v162, s[2:3]
	s_waitcnt vmcnt(6)
	s_barrier
	v_mfma_f32_16x16x32_bf16 v[44:47], v[196:199], v[144:147], v[44:47]
	v_mfma_f32_16x16x32_bf16 v[40:43], v[210:213], v[144:147], v[40:43]
	v_mfma_f32_16x16x32_bf16 v[28:31], v[196:199], v[152:155], v[28:31]
	v_mfma_f32_16x16x32_bf16 v[24:27], v[210:213], v[152:155], v[24:27]
	v_mfma_f32_16x16x32_bf16 v[12:15], v[196:199], v[180:183], v[12:15]
	v_mfma_f32_16x16x32_bf16 v[8:11], v[210:213], v[180:183], v[8:11]
	v_mfma_f32_16x16x32_bf16 v[4:7], v[196:199], v[188:191], v[4:7]
	v_mfma_f32_16x16x32_bf16 v[0:3], v[210:213], v[188:191], v[0:3]
	v_mfma_f32_16x16x32_bf16 v[44:47], v[200:203], v[148:151], v[44:47]
	v_mfma_f32_16x16x32_bf16 v[40:43], v[214:217], v[148:151], v[40:43]
	v_mfma_f32_16x16x32_bf16 v[28:31], v[200:203], v[156:159], v[28:31]
	v_mfma_f32_16x16x32_bf16 v[24:27], v[214:217], v[156:159], v[24:27]
	v_mfma_f32_16x16x32_bf16 v[12:15], v[200:203], v[184:187], v[12:15]
	v_mfma_f32_16x16x32_bf16 v[8:11], v[214:217], v[184:187], v[8:11]
	v_mfma_f32_16x16x32_bf16 v[4:7], v[200:203], v[192:195], v[4:7]
	v_mfma_f32_16x16x32_bf16 v[0:3], v[214:217], v[192:195], v[0:3]
	s_add_u32 s6, s6, 0x100
	s_addc_u32 s7, s7, 0
	s_add_u32 s39, s39, 0x100
	s_addc_u32 s40, s40, 0
	s_cmp_gt_u32 s41, 13
	s_barrier
.LBB0_355:
	s_add_u32 s2, s6, 0xfffc0080
	s_addc_u32 s3, s7, -1
	ds_read_b128 v[128:131], v208
	ds_read_b128 v[132:135], v208 offset:1024
	ds_read_b128 v[136:139], v208 offset:2048
	ds_read_b128 v[140:143], v208 offset:3072
	s_cmp_eq_u32 s41, 12
	s_cselect_b32 s9, s1, s3
	s_cselect_b32 s8, s31, s2
	s_cselect_b32 s3, s29, s40
	s_cselect_b32 s2, s38, s39
	ds_read_b128 v[144:147], v209
	ds_read_b128 v[148:151], v209 offset:1024
	ds_read_b128 v[152:155], v209 offset:2048
	ds_read_b128 v[156:159], v209 offset:3072
	ds_read_b128 v[180:183], v209 offset:4096
	ds_read_b128 v[184:187], v209 offset:5120
	ds_read_b128 v[188:191], v209 offset:6144
	ds_read_b128 v[192:195], v209 offset:7168
	s_waitcnt lgkmcnt(8)
	s_barrier
	s_waitcnt lgkmcnt(0)
	v_mfma_f32_16x16x32_bf16 v[124:127], v[128:131], v[144:147], v[124:127]
	v_mfma_f32_16x16x32_bf16 v[120:123], v[136:139], v[144:147], v[120:123]
	v_mfma_f32_16x16x32_bf16 v[116:119], v[128:131], v[152:155], v[116:119]
	v_mfma_f32_16x16x32_bf16 v[112:115], v[136:139], v[152:155], v[112:115]
	v_mfma_f32_16x16x32_bf16 v[100:103], v[128:131], v[180:183], v[100:103]
	v_mfma_f32_16x16x32_bf16 v[96:99], v[136:139], v[180:183], v[96:99]
	v_mfma_f32_16x16x32_bf16 v[84:87], v[128:131], v[188:191], v[84:87]
	v_mfma_f32_16x16x32_bf16 v[80:83], v[136:139], v[188:191], v[80:83]
	v_mfma_f32_16x16x32_bf16 v[124:127], v[132:135], v[148:151], v[124:127]
	v_mfma_f32_16x16x32_bf16 v[120:123], v[140:143], v[148:151], v[120:123]
	v_mfma_f32_16x16x32_bf16 v[116:119], v[132:135], v[156:159], v[116:119]
	v_mfma_f32_16x16x32_bf16 v[112:115], v[140:143], v[156:159], v[112:115]
	v_mfma_f32_16x16x32_bf16 v[100:103], v[132:135], v[184:187], v[100:103]
	v_mfma_f32_16x16x32_bf16 v[96:99], v[140:143], v[184:187], v[96:99]
	v_mfma_f32_16x16x32_bf16 v[84:87], v[132:135], v[192:195], v[84:87]
	v_mfma_f32_16x16x32_bf16 v[80:83], v[140:143], v[192:195], v[80:83]
	s_barrier
	s_add_i32 m0, s21, 0xc000
	ds_read_b128 v[196:199], v208 offset:16384
	ds_read_b128 v[200:203], v208 offset:17408
	ds_read_b128 v[210:213], v208 offset:18432
	global_load_lds_dwordx4 v164, s[6:7]
	s_add_i32 m0, s21, 0xe000
	ds_read_b128 v[214:217], v208 offset:19456
	global_load_lds_dwordx4 v166, s[6:7]
	s_add_u32 s98, s2, 0x80
	s_addc_u32 s99, s3, 0
	s_barrier
	s_waitcnt lgkmcnt(0)
	v_mfma_f32_16x16x32_bf16 v[108:111], v[196:199], v[144:147], v[108:111]
	v_mfma_f32_16x16x32_bf16 v[104:107], v[210:213], v[144:147], v[104:107]
	v_mfma_f32_16x16x32_bf16 v[92:95], v[196:199], v[152:155], v[92:95]
	v_mfma_f32_16x16x32_bf16 v[88:91], v[210:213], v[152:155], v[88:91]
	v_mfma_f32_16x16x32_bf16 v[76:79], v[196:199], v[180:183], v[76:79]
	v_mfma_f32_16x16x32_bf16 v[72:75], v[210:213], v[180:183], v[72:75]
	v_mfma_f32_16x16x32_bf16 v[68:71], v[196:199], v[188:191], v[68:71]
	v_mfma_f32_16x16x32_bf16 v[64:67], v[210:213], v[188:191], v[64:67]
	v_mfma_f32_16x16x32_bf16 v[108:111], v[200:203], v[148:151], v[108:111]
	v_mfma_f32_16x16x32_bf16 v[104:107], v[214:217], v[148:151], v[104:107]
	v_mfma_f32_16x16x32_bf16 v[92:95], v[200:203], v[156:159], v[92:95]
	v_mfma_f32_16x16x32_bf16 v[88:91], v[214:217], v[156:159], v[88:91]
	v_mfma_f32_16x16x32_bf16 v[76:79], v[200:203], v[184:187], v[76:79]
	v_mfma_f32_16x16x32_bf16 v[72:75], v[214:217], v[184:187], v[72:75]
	v_mfma_f32_16x16x32_bf16 v[68:71], v[200:203], v[192:195], v[68:71]
	v_mfma_f32_16x16x32_bf16 v[64:67], v[214:217], v[192:195], v[64:67]
	s_add_u32 s100, s8, 0x80
	s_addc_u32 s101, s9, 0
	s_barrier
	ds_read_b128 v[144:147], v209 offset:16384
	ds_read_b128 v[148:151], v209 offset:17408
	ds_read_b128 v[152:155], v209 offset:18432
	ds_read_b128 v[156:159], v209 offset:19456
	ds_read_b128 v[180:183], v209 offset:20480
	ds_read_b128 v[184:187], v209 offset:21504
	ds_read_b128 v[188:191], v209 offset:22528
	ds_read_b128 v[192:195], v209 offset:23552
	s_add_i32 m0, s54, 0x10000
	s_nop 0
	global_load_lds_dwordx4 v160, s[2:3]
	s_add_i32 m0, s54, 0x12000
	s_nop 0
	global_load_lds_dwordx4 v162, s[2:3]
	s_barrier
	s_waitcnt lgkmcnt(0)
	v_mfma_f32_16x16x32_bf16 v[60:63], v[128:131], v[144:147], v[60:63]
	v_mfma_f32_16x16x32_bf16 v[56:59], v[136:139], v[144:147], v[56:59]
	v_mfma_f32_16x16x32_bf16 v[52:55], v[128:131], v[152:155], v[52:55]
	v_mfma_f32_16x16x32_bf16 v[48:51], v[136:139], v[152:155], v[48:51]
	v_mfma_f32_16x16x32_bf16 v[36:39], v[128:131], v[180:183], v[36:39]
	v_mfma_f32_16x16x32_bf16 v[32:35], v[136:139], v[180:183], v[32:35]
	v_mfma_f32_16x16x32_bf16 v[20:23], v[128:131], v[188:191], v[20:23]
	v_mfma_f32_16x16x32_bf16 v[16:19], v[136:139], v[188:191], v[16:19]
	v_mfma_f32_16x16x32_bf16 v[60:63], v[132:135], v[148:151], v[60:63]
	v_mfma_f32_16x16x32_bf16 v[56:59], v[140:143], v[148:151], v[56:59]
	v_mfma_f32_16x16x32_bf16 v[52:55], v[132:135], v[156:159], v[52:55]
	v_mfma_f32_16x16x32_bf16 v[48:51], v[140:143], v[156:159], v[48:51]
	v_mfma_f32_16x16x32_bf16 v[36:39], v[132:135], v[184:187], v[36:39]
	v_mfma_f32_16x16x32_bf16 v[32:35], v[140:143], v[184:187], v[32:35]
	v_mfma_f32_16x16x32_bf16 v[20:23], v[132:135], v[192:195], v[20:23]
	v_mfma_f32_16x16x32_bf16 v[16:19], v[140:143], v[192:195], v[16:19]
	s_barrier
	s_mov_b32 m0, s21
	s_nop 0
	global_load_lds_dwordx4 v160, s[8:9]
	s_mov_b32 m0, s55
	s_nop 0
	global_load_lds_dwordx4 v162, s[8:9]
	s_add_i32 m0, s54, 0x14000
	s_add_u32 s64, s2, 0x40000
	s_addc_u32 s65, s3, 0
	global_load_lds_dwordx4 v160, s[64:65]
	s_add_i32 m0, s54, 0x16000
	s_add_u32 s8, s8, 0x40000
	s_addc_u32 s9, s9, 0
	global_load_lds_dwordx4 v162, s[64:65]
	s_waitcnt vmcnt(6)
	s_barrier
	v_mfma_f32_16x16x32_bf16 v[44:47], v[196:199], v[144:147], v[44:47]
	v_mfma_f32_16x16x32_bf16 v[40:43], v[210:213], v[144:147], v[40:43]
	v_mfma_f32_16x16x32_bf16 v[28:31], v[196:199], v[152:155], v[28:31]
	v_mfma_f32_16x16x32_bf16 v[24:27], v[210:213], v[152:155], v[24:27]
	v_mfma_f32_16x16x32_bf16 v[12:15], v[196:199], v[180:183], v[12:15]
	v_mfma_f32_16x16x32_bf16 v[8:11], v[210:213], v[180:183], v[8:11]
	v_mfma_f32_16x16x32_bf16 v[4:7], v[196:199], v[188:191], v[4:7]
	v_mfma_f32_16x16x32_bf16 v[0:3], v[210:213], v[188:191], v[0:3]
	v_mfma_f32_16x16x32_bf16 v[44:47], v[200:203], v[148:151], v[44:47]
	v_mfma_f32_16x16x32_bf16 v[40:43], v[214:217], v[148:151], v[40:43]
	v_mfma_f32_16x16x32_bf16 v[28:31], v[200:203], v[156:159], v[28:31]
	v_mfma_f32_16x16x32_bf16 v[24:27], v[214:217], v[156:159], v[24:27]
	v_mfma_f32_16x16x32_bf16 v[12:15], v[200:203], v[184:187], v[12:15]
	v_mfma_f32_16x16x32_bf16 v[8:11], v[214:217], v[184:187], v[8:11]
	v_mfma_f32_16x16x32_bf16 v[4:7], v[200:203], v[192:195], v[4:7]
	v_mfma_f32_16x16x32_bf16 v[0:3], v[214:217], v[192:195], v[0:3]
	s_barrier
	ds_read_b128 v[128:131], v208 offset:32768
	ds_read_b128 v[132:135], v208 offset:33792
	ds_read_b128 v[136:139], v208 offset:34816
	ds_read_b128 v[140:143], v208 offset:35840
	ds_read_b128 v[144:147], v209 offset:32768
	ds_read_b128 v[148:151], v209 offset:33792
	ds_read_b128 v[152:155], v209 offset:34816
	ds_read_b128 v[156:159], v209 offset:35840
	ds_read_b128 v[180:183], v209 offset:36864
	ds_read_b128 v[184:187], v209 offset:37888
	ds_read_b128 v[188:191], v209 offset:38912
	ds_read_b128 v[192:195], v209 offset:39936
	s_waitcnt lgkmcnt(8)
	s_barrier
	s_waitcnt lgkmcnt(0)
	v_mfma_f32_16x16x32_bf16 v[124:127], v[128:131], v[144:147], v[124:127]
	v_mfma_f32_16x16x32_bf16 v[120:123], v[136:139], v[144:147], v[120:123]
	v_mfma_f32_16x16x32_bf16 v[116:119], v[128:131], v[152:155], v[116:119]
	v_mfma_f32_16x16x32_bf16 v[112:115], v[136:139], v[152:155], v[112:115]
	v_mfma_f32_16x16x32_bf16 v[100:103], v[128:131], v[180:183], v[100:103]
	v_mfma_f32_16x16x32_bf16 v[96:99], v[136:139], v[180:183], v[96:99]
	v_mfma_f32_16x16x32_bf16 v[84:87], v[128:131], v[188:191], v[84:87]
	v_mfma_f32_16x16x32_bf16 v[80:83], v[136:139], v[188:191], v[80:83]
	v_mfma_f32_16x16x32_bf16 v[124:127], v[132:135], v[148:151], v[124:127]
	v_mfma_f32_16x16x32_bf16 v[120:123], v[140:143], v[148:151], v[120:123]
	v_mfma_f32_16x16x32_bf16 v[116:119], v[132:135], v[156:159], v[116:119]
	v_mfma_f32_16x16x32_bf16 v[112:115], v[140:143], v[156:159], v[112:115]
	v_mfma_f32_16x16x32_bf16 v[100:103], v[132:135], v[184:187], v[100:103]
	v_mfma_f32_16x16x32_bf16 v[96:99], v[140:143], v[184:187], v[96:99]
	v_mfma_f32_16x16x32_bf16 v[84:87], v[132:135], v[192:195], v[84:87]
	v_mfma_f32_16x16x32_bf16 v[80:83], v[140:143], v[192:195], v[80:83]
	s_barrier
	s_mov_b32 m0, s56
	ds_read_b128 v[196:199], v208 offset:49152
	ds_read_b128 v[200:203], v208 offset:50176
	ds_read_b128 v[210:213], v208 offset:51200
	global_load_lds_dwordx4 v160, s[8:9]
	s_mov_b32 m0, s57
	ds_read_b128 v[214:217], v208 offset:52224
	global_load_lds_dwordx4 v162, s[8:9]
	s_barrier
	s_waitcnt lgkmcnt(0)
	v_mfma_f32_16x16x32_bf16 v[108:111], v[196:199], v[144:147], v[108:111]
	v_mfma_f32_16x16x32_bf16 v[104:107], v[210:213], v[144:147], v[104:107]
	v_mfma_f32_16x16x32_bf16 v[92:95], v[196:199], v[152:155], v[92:95]
	v_mfma_f32_16x16x32_bf16 v[88:91], v[210:213], v[152:155], v[88:91]
	v_mfma_f32_16x16x32_bf16 v[76:79], v[196:199], v[180:183], v[76:79]
	v_mfma_f32_16x16x32_bf16 v[72:75], v[210:213], v[180:183], v[72:75]
	v_mfma_f32_16x16x32_bf16 v[68:71], v[196:199], v[188:191], v[68:71]
	v_mfma_f32_16x16x32_bf16 v[64:67], v[210:213], v[188:191], v[64:67]
	v_mfma_f32_16x16x32_bf16 v[108:111], v[200:203], v[148:151], v[108:111]
	v_mfma_f32_16x16x32_bf16 v[104:107], v[214:217], v[148:151], v[104:107]
	v_mfma_f32_16x16x32_bf16 v[92:95], v[200:203], v[156:159], v[92:95]
	v_mfma_f32_16x16x32_bf16 v[88:91], v[214:217], v[156:159], v[88:91]
	v_mfma_f32_16x16x32_bf16 v[76:79], v[200:203], v[184:187], v[76:79]
	v_mfma_f32_16x16x32_bf16 v[72:75], v[214:217], v[184:187], v[72:75]
	v_mfma_f32_16x16x32_bf16 v[68:71], v[200:203], v[192:195], v[68:71]
	v_mfma_f32_16x16x32_bf16 v[64:67], v[214:217], v[192:195], v[64:67]
	s_barrier
	ds_read_b128 v[144:147], v209 offset:49152
	ds_read_b128 v[148:151], v209 offset:50176
	ds_read_b128 v[152:155], v209 offset:51200
	ds_read_b128 v[156:159], v209 offset:52224
	ds_read_b128 v[180:183], v209 offset:53248
	ds_read_b128 v[184:187], v209 offset:54272
	ds_read_b128 v[188:191], v209 offset:55296
	ds_read_b128 v[192:195], v209 offset:56320
	s_add_i32 m0, s54, 0x18000
	s_nop 0
	global_load_lds_dwordx4 v160, s[98:99]
	s_add_i32 m0, s54, 0x1a000
	s_nop 0
	global_load_lds_dwordx4 v162, s[98:99]
	s_barrier
	s_waitcnt lgkmcnt(0)
	v_mfma_f32_16x16x32_bf16 v[60:63], v[128:131], v[144:147], v[60:63]
	v_mfma_f32_16x16x32_bf16 v[56:59], v[136:139], v[144:147], v[56:59]
	v_mfma_f32_16x16x32_bf16 v[52:55], v[128:131], v[152:155], v[52:55]
	v_mfma_f32_16x16x32_bf16 v[48:51], v[136:139], v[152:155], v[48:51]
	v_mfma_f32_16x16x32_bf16 v[36:39], v[128:131], v[180:183], v[36:39]
	v_mfma_f32_16x16x32_bf16 v[32:35], v[136:139], v[180:183], v[32:35]
	v_mfma_f32_16x16x32_bf16 v[20:23], v[128:131], v[188:191], v[20:23]
	v_mfma_f32_16x16x32_bf16 v[16:19], v[136:139], v[188:191], v[16:19]
	v_mfma_f32_16x16x32_bf16 v[60:63], v[132:135], v[148:151], v[60:63]
	v_mfma_f32_16x16x32_bf16 v[56:59], v[140:143], v[148:151], v[56:59]
	v_mfma_f32_16x16x32_bf16 v[52:55], v[132:135], v[156:159], v[52:55]
	v_mfma_f32_16x16x32_bf16 v[48:51], v[140:143], v[156:159], v[48:51]
	v_mfma_f32_16x16x32_bf16 v[36:39], v[132:135], v[184:187], v[36:39]
	v_mfma_f32_16x16x32_bf16 v[32:35], v[140:143], v[184:187], v[32:35]
	v_mfma_f32_16x16x32_bf16 v[20:23], v[132:135], v[192:195], v[20:23]
	v_mfma_f32_16x16x32_bf16 v[16:19], v[140:143], v[192:195], v[16:19]
	s_barrier
	s_mov_b32 m0, s60
	s_nop 0
	global_load_lds_dwordx4 v160, s[100:101]
	s_mov_b32 m0, s61
	s_nop 0
	global_load_lds_dwordx4 v162, s[100:101]
	s_add_i32 m0, s54, 0x1c000
	s_add_u32 s2, s2, 0x40080
	s_addc_u32 s3, s3, 0
	global_load_lds_dwordx4 v160, s[2:3]
	s_add_i32 m0, s54, 0x1e000
	s_add_i32 s41, s41, 2
	global_load_lds_dwordx4 v162, s[2:3]
	s_waitcnt vmcnt(6)
	s_barrier
	v_mfma_f32_16x16x32_bf16 v[44:47], v[196:199], v[144:147], v[44:47]
	v_mfma_f32_16x16x32_bf16 v[40:43], v[210:213], v[144:147], v[40:43]
	v_mfma_f32_16x16x32_bf16 v[28:31], v[196:199], v[152:155], v[28:31]
	v_mfma_f32_16x16x32_bf16 v[24:27], v[210:213], v[152:155], v[24:27]
	v_mfma_f32_16x16x32_bf16 v[12:15], v[196:199], v[180:183], v[12:15]
	v_mfma_f32_16x16x32_bf16 v[8:11], v[210:213], v[180:183], v[8:11]
	v_mfma_f32_16x16x32_bf16 v[4:7], v[196:199], v[188:191], v[4:7]
	v_mfma_f32_16x16x32_bf16 v[0:3], v[210:213], v[188:191], v[0:3]
	v_mfma_f32_16x16x32_bf16 v[44:47], v[200:203], v[148:151], v[44:47]
	v_mfma_f32_16x16x32_bf16 v[40:43], v[214:217], v[148:151], v[40:43]
	v_mfma_f32_16x16x32_bf16 v[28:31], v[200:203], v[156:159], v[28:31]
	v_mfma_f32_16x16x32_bf16 v[24:27], v[214:217], v[156:159], v[24:27]
	v_mfma_f32_16x16x32_bf16 v[12:15], v[200:203], v[184:187], v[12:15]
	v_mfma_f32_16x16x32_bf16 v[8:11], v[214:217], v[184:187], v[8:11]
	v_mfma_f32_16x16x32_bf16 v[4:7], v[200:203], v[192:195], v[4:7]
	v_mfma_f32_16x16x32_bf16 v[0:3], v[214:217], v[192:195], v[0:3]
	s_add_u32 s6, s6, 0x100
	s_addc_u32 s7, s7, 0
	s_add_u32 s39, s39, 0x100
	s_addc_u32 s40, s40, 0
	s_cmp_gt_u32 s41, 13
	s_barrier
	s_cbranch_scc0 .LBB0_355
	s_lshl_b32 s1, s0, 8
	v_mov_b32_e32 v211, v206
	v_mov_b32_e32 v210, v207
	s_add_i32 s1, s1, s59
	s_cmp_lt_i32 s20, 3
	v_add_u32_e32 v180, s1, v211
	s_mov_b64 s[2:3], -1
	s_cbranch_scc0 .LBB0_490
	s_cmp_gt_i32 s0, 15
	s_cselect_b64 s[2:3], -1, 0
	s_cmp_lt_i32 s0, 16
	s_cselect_b64 s[38:39], -1, 0
	s_cmp_eq_u32 s20, 2
	s_cselect_b64 s[8:9], -1, 0
	s_cmp_lg_u32 s20, 2
	s_cselect_b64 s[0:1], -1, 0
	s_and_b64 s[40:41], s[8:9], s[22:23]
	v_lshlrev_b32_e32 v182, 2, v210
	s_mov_b64 s[6:7], -1
	s_and_b64 vcc, exec, s[40:41]
	v_ashrrev_i32_e32 v183, 31, v182
	s_cbranch_vccnz .LBB0_447
	s_and_b64 s[6:7], s[8:9], exec
	s_cselect_b32 s6, s46, s44
	s_cselect_b32 s7, s47, s45
	v_mov_b32_e32 v128, s7
	v_mov_b32_e32 v129, s6
	v_lshl_add_u64 v[128:129], v[182:183], 2, v[128:129]
	global_load_dwordx4 v[140:143], v[128:129], off
	global_load_dwordx4 v[136:139], v[128:129], off offset:64
	global_load_dwordx4 v[132:135], v[128:129], off offset:128
	s_nop 0
	global_load_dwordx4 v[128:131], v[128:129], off offset:192
	v_mul_f32_e32 v144, v125, v125
	v_mul_f32_e32 v145, v127, v127
	v_fmac_f32_e32 v144, v124, v124
	v_fmac_f32_e32 v145, v126, v126
	v_add_f32_e32 v144, v144, v145
	v_mul_f32_e32 v145, v121, v121
	v_mul_f32_e32 v146, v123, v123
	v_fmac_f32_e32 v145, v120, v120
	v_fmac_f32_e32 v146, v122, v122
	v_add_f32_e32 v145, v145, v146
	v_add_f32_e32 v144, v144, v145
	v_mul_f32_e32 v145, v109, v109
	v_mul_f32_e32 v146, v111, v111
	v_fmac_f32_e32 v145, v108, v108
	v_fmac_f32_e32 v146, v110, v110
	v_add_f32_e32 v145, v145, v146
	v_add_f32_e32 v144, v144, v145
	v_mul_f32_e32 v145, v105, v105
	v_mul_f32_e32 v146, v107, v107
	v_fmac_f32_e32 v145, v104, v104
	v_fmac_f32_e32 v146, v106, v106
	v_add_f32_e32 v145, v145, v146
	v_add_f32_e32 v144, v144, v145
	v_mov_b32_e32 v145, v144
	s_nop 1
	v_permlane16_swap_b32_e32 v144, v145
	v_add_f32_e32 v144, v144, v145
	v_mov_b32_e32 v145, v144
	s_nop 1
	v_permlane32_swap_b32_e32 v144, v145
	v_add_f32_e32 v144, v144, v145
	v_fmamk_f32 v144, v144, 0x3c800000, v225
	v_cmp_gt_f32_e32 vcc, s93, v144
	v_mul_f32_e32 v145, 0x4b800000, v144
	v_and_b32_e32 v202, 63, v211
	v_cndmask_b32_e32 v144, v144, v145, vcc
	v_rsq_f32_e32 v144, v144
	v_cndmask_b32_e64 v168, 0, 1, s[2:3]
	v_cmp_ne_u32_e64 s[6:7], 1, v168
	v_lshlrev_b32_e32 v186, 7, v202
	v_mul_f32_e32 v145, 0x45800000, v144
	v_cndmask_b32_e32 v152, v144, v145, vcc
	v_pk_mul_f32 v[144:145], v[124:125], v[152:153] op_sel_hi:[1,0]
	v_pk_mul_f32 v[146:147], v[126:127], v[152:153] op_sel_hi:[1,0]
	v_pk_mul_f32 v[148:149], v[108:109], v[152:153] op_sel_hi:[1,0]
	v_pk_mul_f32 v[150:151], v[110:111], v[152:153] op_sel_hi:[1,0]
	v_pk_mul_f32 v[184:185], v[104:105], v[152:153] op_sel_hi:[1,0]
	s_andn2_b64 vcc, exec, s[2:3]
	s_waitcnt vmcnt(0)
	v_pk_mul_f32 v[158:159], v[142:143], v[146:147]
	v_pk_mul_f32 v[156:157], v[140:141], v[144:145]
	v_pk_mul_f32 v[144:145], v[120:121], v[152:153] op_sel_hi:[1,0]
	v_pk_mul_f32 v[146:147], v[122:123], v[152:153] op_sel_hi:[1,0]
	v_pk_mul_f32 v[152:153], v[106:107], v[152:153] op_sel_hi:[1,0]
	v_pk_mul_f32 v[146:147], v[138:139], v[146:147]
	v_pk_mul_f32 v[144:145], v[136:137], v[144:145]
	v_pk_mul_f32 v[150:151], v[134:135], v[150:151]
	v_pk_mul_f32 v[148:149], v[132:133], v[148:149]
	v_pk_mul_f32 v[154:155], v[130:131], v[152:153]
	v_pk_mul_f32 v[152:153], v[128:129], v[184:185]
	v_lshl_add_u64 v[184:185], v[182:183], 3, s[18:19]
	s_cbranch_vccnz .LBB0_360
	v_lshlrev_b32_e32 v168, 1, v180
	v_and_b32_e32 v168, 0xf80, v168
	v_lshl_add_u64 v[188:189], v[184:185], 0, v[168:169]
	global_load_dwordx4 v[190:193], v[188:189], off offset:16
	global_load_dwordx4 v[194:197], v[188:189], off
	v_mov_b32_e32 v187, v169
	s_waitcnt vmcnt(0)
	v_mul_f32_e32 v198, v158, v190
	v_mov_b32_e32 v188, v194
	v_mov_b32_e32 v189, v196
	v_mov_b32_e32 v196, v195
	v_mul_f32_e32 v200, v146, v191
	v_mul_f32_e32 v204, v146, v190
	v_mul_f32_e32 v212, v158, v191
	v_mov_b32_e32 v146, v159
	v_mov_b32_e32 v158, v147
	v_pk_mul_f32 v[194:195], v[144:145], v[196:197]
	v_pk_mul_f32 v[144:145], v[144:145], v[188:189]
	v_pk_mul_f32 v[190:191], v[146:147], v[192:193]
	v_pk_mul_f32 v[146:147], v[158:159], v[192:193]
	v_lshl_add_u64 v[192:193], v[184:185], 0, v[186:187]
	v_mov_b32_e32 v199, v190
	v_mov_b32_e32 v201, v191
	v_pk_fma_f32 v[190:191], v[156:157], v[188:189], v[194:195] neg_lo:[0,0,1] neg_hi:[0,0,1]
	v_pk_fma_f32 v[144:145], v[156:157], v[196:197], v[144:145]
	global_load_dwordx4 v[156:159], v[192:193], off offset:16
	s_nop 0
	global_load_dwordx4 v[192:195], v[192:193], off
	v_pk_add_f32 v[188:189], v[198:199], v[200:201] neg_lo:[0,1] neg_hi:[0,1]
	v_mov_b32_e32 v213, v147
	v_mov_b32_e32 v205, v146
	v_pk_add_f32 v[146:147], v[212:213], v[204:205]
	s_waitcnt vmcnt(0)
	v_mul_f32_e32 v198, v150, v156
	v_mul_f32_e32 v200, v154, v157
	v_mul_f32_e32 v156, v154, v156
	v_mov_b32_e32 v154, v151
	v_mov_b32_e32 v197, v194
	v_mov_b32_e32 v194, v193
	v_mul_f32_e32 v204, v150, v157
	v_pk_mul_f32 v[212:213], v[154:155], v[158:159]
	v_mov_b32_e32 v150, v155
	v_mov_b32_e32 v196, v192
	v_pk_mul_f32 v[192:193], v[152:153], v[194:195]
	v_mov_b32_e32 v199, v212
	v_mov_b32_e32 v201, v213
	v_pk_mul_f32 v[150:151], v[150:151], v[158:159]
	v_pk_mul_f32 v[152:153], v[152:153], v[196:197]
	v_pk_fma_f32 v[192:193], v[148:149], v[196:197], v[192:193] neg_lo:[0,0,1] neg_hi:[0,0,1]
	v_pk_add_f32 v[196:197], v[198:199], v[200:201] neg_lo:[0,1] neg_hi:[0,1]
	v_mov_b32_e32 v205, v151
	v_mov_b32_e32 v157, v150
	v_pk_fma_f32 v[152:153], v[148:149], v[194:195], v[152:153]
	v_pk_add_f32 v[154:155], v[204:205], v[156:157]
	v_mov_b32_e32 v148, v192
	v_mov_b32_e32 v149, v193
	v_mov_b32_e32 v150, v196
	v_mov_b32_e32 v151, v197
	v_mov_b32_e32 v156, v190
	v_mov_b32_e32 v157, v191
	v_mov_b32_e32 v158, v188
	v_mov_b32_e32 v159, v189

.LBB0_677:
	s_ashr_i32 s23, s22, 31
	v_cmp_lt_i64_e32 vcc, s[24:25], v[174:175]
	s_lshl_b64 s[24:25], s[22:23], 19
	s_add_u32 s24, s36, s24
	s_addc_u32 s25, s37, s25
	s_and_b64 s[26:27], vcc, exec
	s_cselect_b32 s1, s25, s9
	s_cselect_b32 s7, s24, s8
	s_ashr_i32 s21, s20, 31
	s_lshl_b64 s[26:27], s[20:21], 19
	s_add_u32 s26, s38, s26
	s_addc_u32 s27, s39, s27
	s_and_b64 s[28:29], vcc, exec
	s_cselect_b32 s21, s27, s3
	s_cselect_b32 s23, s26, s2
	s_add_u32 s8, s8, 0x40080
	s_addc_u32 s9, s9, 0
	s_add_u32 s56, s2, 0x100
	s_addc_u32 s57, s3, 0
	s_mov_b32 s58, -2
	s_add_u32 s2, s8, 0xfffc0080
	s_addc_u32 s3, s9, -1
	ds_read_b128 v[48:51], v206
	ds_read_b128 v[52:55], v206 offset:1024
	ds_read_b128 v[60:63], v206 offset:2048
	ds_read_b128 v[68:71], v206 offset:3072
	s_cmp_eq_u32 s58, 12
	s_cselect_b32 s29, s1, s3
	s_cselect_b32 s28, s7, s2
	s_cselect_b32 s3, s21, s57
	s_cselect_b32 s2, s23, s56
	ds_read_b128 v[72:75], v207
	ds_read_b128 v[76:79], v207 offset:1024
	ds_read_b128 v[80:83], v207 offset:2048
	ds_read_b128 v[84:87], v207 offset:3072
	ds_read_b128 v[160:163], v207 offset:4096
	ds_read_b128 v[164:167], v207 offset:5120
	ds_read_b128 v[192:195], v207 offset:6144
	ds_read_b128 v[196:199], v207 offset:7168
	s_waitcnt lgkmcnt(8)
	s_barrier
	s_waitcnt lgkmcnt(0)
	v_mfma_f32_16x16x32_bf16 v[156:159], v[48:51], v[72:75], 0
	v_mfma_f32_16x16x32_bf16 v[152:155], v[60:63], v[72:75], 0
	v_mfma_f32_16x16x32_bf16 v[140:143], v[48:51], v[80:83], 0
	v_mfma_f32_16x16x32_bf16 v[136:139], v[60:63], v[80:83], 0
	v_mfma_f32_16x16x32_bf16 v[124:127], v[48:51], v[160:163], 0
	v_mfma_f32_16x16x32_bf16 v[120:123], v[60:63], v[160:163], 0
	v_mfma_f32_16x16x32_bf16 v[108:111], v[48:51], v[192:195], 0
	v_mfma_f32_16x16x32_bf16 v[104:107], v[60:63], v[192:195], 0
	v_mfma_f32_16x16x32_bf16 v[156:159], v[52:55], v[76:79], v[156:159]
	v_mfma_f32_16x16x32_bf16 v[152:155], v[68:71], v[76:79], v[152:155]
	v_mfma_f32_16x16x32_bf16 v[140:143], v[52:55], v[84:87], v[140:143]
	v_mfma_f32_16x16x32_bf16 v[136:139], v[68:71], v[84:87], v[136:139]
	v_mfma_f32_16x16x32_bf16 v[124:127], v[52:55], v[164:167], v[124:127]
	v_mfma_f32_16x16x32_bf16 v[120:123], v[68:71], v[164:167], v[120:123]
	v_mfma_f32_16x16x32_bf16 v[108:111], v[52:55], v[196:199], v[108:111]
	v_mfma_f32_16x16x32_bf16 v[104:107], v[68:71], v[196:199], v[104:107]
	s_barrier
	s_add_i32 m0, s41, 0xc000
	ds_read_b128 v[200:203], v206 offset:16384
	ds_read_b128 v[208:211], v206 offset:17408
	ds_read_b128 v[212:215], v206 offset:18432
	global_load_lds_dwordx4 v188, s[8:9]
	s_add_i32 m0, s41, 0xe000
	ds_read_b128 v[216:219], v206 offset:19456
	global_load_lds_dwordx4 v190, s[8:9]
	s_add_u32 s98, s2, 0x80
	s_addc_u32 s99, s3, 0
	s_barrier
	s_waitcnt lgkmcnt(0)
	v_mfma_f32_16x16x32_bf16 v[148:151], v[200:203], v[72:75], 0
	v_mfma_f32_16x16x32_bf16 v[72:75], v[212:215], v[72:75], 0
	v_mfma_f32_16x16x32_bf16 v[148:151], v[208:211], v[76:79], v[148:151]
	v_mfma_f32_16x16x32_bf16 v[72:75], v[216:219], v[76:79], v[72:75]
	v_mfma_f32_16x16x32_bf16 v[76:79], v[200:203], v[80:83], 0
	v_mfma_f32_16x16x32_bf16 v[80:83], v[212:215], v[80:83], 0
	v_mfma_f32_16x16x32_bf16 v[112:115], v[212:215], v[160:163], 0
	v_mfma_f32_16x16x32_bf16 v[100:103], v[200:203], v[192:195], 0
	v_mfma_f32_16x16x32_bf16 v[96:99], v[212:215], v[192:195], 0
	v_mfma_f32_16x16x32_bf16 v[76:79], v[208:211], v[84:87], v[76:79]
	v_mfma_f32_16x16x32_bf16 v[80:83], v[216:219], v[84:87], v[80:83]
	v_mfma_f32_16x16x32_bf16 v[84:87], v[200:203], v[160:163], 0
	v_mfma_f32_16x16x32_bf16 v[112:115], v[216:219], v[164:167], v[112:115]
	v_mfma_f32_16x16x32_bf16 v[100:103], v[208:211], v[196:199], v[100:103]
	v_mfma_f32_16x16x32_bf16 v[96:99], v[216:219], v[196:199], v[96:99]
	v_mfma_f32_16x16x32_bf16 v[84:87], v[208:211], v[164:167], v[84:87]
	s_add_u32 s100, s28, 0x80
	s_addc_u32 s101, s29, 0
	s_barrier
	ds_read_b128 v[116:119], v207 offset:16384
	ds_read_b128 v[128:131], v207 offset:17408
	ds_read_b128 v[132:135], v207 offset:18432
	ds_read_b128 v[144:147], v207 offset:19456
	ds_read_b128 v[160:163], v207 offset:20480
	ds_read_b128 v[164:167], v207 offset:21504
	ds_read_b128 v[192:195], v207 offset:22528
	ds_read_b128 v[196:199], v207 offset:23552
	s_add_i32 m0, s40, 0x10000
	s_nop 0
	global_load_lds_dwordx4 v182, s[2:3]
	s_add_i32 m0, s40, 0x12000
	s_nop 0
	global_load_lds_dwordx4 v186, s[2:3]
	s_barrier
	s_waitcnt lgkmcnt(0)
	v_mfma_f32_16x16x32_bf16 v[92:95], v[48:51], v[116:119], 0
	v_mfma_f32_16x16x32_bf16 v[88:91], v[60:63], v[116:119], 0
	v_mfma_f32_16x16x32_bf16 v[44:47], v[48:51], v[132:135], 0
	v_mfma_f32_16x16x32_bf16 v[40:43], v[60:63], v[132:135], 0
	v_mfma_f32_16x16x32_bf16 v[28:31], v[48:51], v[160:163], 0
	v_mfma_f32_16x16x32_bf16 v[24:27], v[60:63], v[160:163], 0
	v_mfma_f32_16x16x32_bf16 v[12:15], v[48:51], v[192:195], 0
	v_mfma_f32_16x16x32_bf16 v[8:11], v[60:63], v[192:195], 0
	v_mfma_f32_16x16x32_bf16 v[92:95], v[52:55], v[128:131], v[92:95]
	v_mfma_f32_16x16x32_bf16 v[88:91], v[68:71], v[128:131], v[88:91]
	v_mfma_f32_16x16x32_bf16 v[44:47], v[52:55], v[144:147], v[44:47]
	v_mfma_f32_16x16x32_bf16 v[40:43], v[68:71], v[144:147], v[40:43]
	v_mfma_f32_16x16x32_bf16 v[28:31], v[52:55], v[164:167], v[28:31]
	v_mfma_f32_16x16x32_bf16 v[24:27], v[68:71], v[164:167], v[24:27]
	v_mfma_f32_16x16x32_bf16 v[12:15], v[52:55], v[196:199], v[12:15]
	v_mfma_f32_16x16x32_bf16 v[8:11], v[68:71], v[196:199], v[8:11]
	s_barrier
	s_mov_b32 m0, s41
	s_nop 0
	global_load_lds_dwordx4 v180, s[28:29]
	s_mov_b32 m0, s42
	s_nop 0
	global_load_lds_dwordx4 v184, s[28:29]
	s_add_i32 m0, s40, 0x14000
	s_add_u32 s60, s2, 0x40000
	s_addc_u32 s61, s3, 0
	global_load_lds_dwordx4 v182, s[60:61]
	s_add_i32 m0, s40, 0x16000
	s_add_u32 s28, s28, 0x40000
	s_addc_u32 s29, s29, 0
	global_load_lds_dwordx4 v186, s[60:61]
	s_waitcnt vmcnt(6)
	s_barrier
	v_mfma_f32_16x16x32_bf16 v[36:39], v[200:203], v[132:135], 0
	v_mfma_f32_16x16x32_bf16 v[32:35], v[212:215], v[132:135], 0
	v_mfma_f32_16x16x32_bf16 v[20:23], v[200:203], v[160:163], 0
	v_mfma_f32_16x16x32_bf16 v[16:19], v[212:215], v[160:163], 0
	v_mfma_f32_16x16x32_bf16 v[4:7], v[200:203], v[192:195], 0
	v_mfma_f32_16x16x32_bf16 v[0:3], v[212:215], v[192:195], 0
	v_mfma_f32_16x16x32_bf16 v[48:51], v[200:203], v[116:119], 0
	v_mfma_f32_16x16x32_bf16 v[52:55], v[212:215], v[116:119], 0
	v_mfma_f32_16x16x32_bf16 v[36:39], v[208:211], v[144:147], v[36:39]
	v_mfma_f32_16x16x32_bf16 v[32:35], v[216:219], v[144:147], v[32:35]
	v_mfma_f32_16x16x32_bf16 v[20:23], v[208:211], v[164:167], v[20:23]
	v_mfma_f32_16x16x32_bf16 v[16:19], v[216:219], v[164:167], v[16:19]
	v_mfma_f32_16x16x32_bf16 v[4:7], v[208:211], v[196:199], v[4:7]
	v_mfma_f32_16x16x32_bf16 v[0:3], v[216:219], v[196:199], v[0:3]
	v_mfma_f32_16x16x32_bf16 v[48:51], v[208:211], v[128:131], v[48:51]
	v_mfma_f32_16x16x32_bf16 v[52:55], v[216:219], v[128:131], v[52:55]
	s_barrier
	ds_read_b128 v[56:59], v206 offset:32768
	ds_read_b128 v[60:63], v206 offset:33792
	ds_read_b128 v[64:67], v206 offset:34816
	ds_read_b128 v[68:71], v206 offset:35840
	ds_read_b128 v[116:119], v207 offset:32768
	ds_read_b128 v[128:131], v207 offset:33792
	ds_read_b128 v[160:163], v207 offset:34816
	ds_read_b128 v[164:167], v207 offset:35840
	ds_read_b128 v[192:195], v207 offset:36864
	ds_read_b128 v[196:199], v207 offset:37888
	ds_read_b128 v[200:203], v207 offset:38912
	ds_read_b128 v[208:211], v207 offset:39936
	s_waitcnt lgkmcnt(8)
	s_barrier
	s_waitcnt lgkmcnt(0)
	v_mfma_f32_16x16x32_bf16 v[132:135], v[56:59], v[116:119], v[156:159]
	v_mfma_f32_16x16x32_bf16 v[156:159], v[60:63], v[128:131], v[132:135]
	v_mfma_f32_16x16x32_bf16 v[132:135], v[64:67], v[116:119], v[152:155]
	v_mfma_f32_16x16x32_bf16 v[152:155], v[68:71], v[128:131], v[132:135]
	v_mfma_f32_16x16x32_bf16 v[132:135], v[56:59], v[160:163], v[140:143]
	v_mfma_f32_16x16x32_bf16 v[140:143], v[60:63], v[164:167], v[132:135]
	v_mfma_f32_16x16x32_bf16 v[132:135], v[64:67], v[160:163], v[136:139]
	v_mfma_f32_16x16x32_bf16 v[124:127], v[56:59], v[192:195], v[124:127]
	v_mfma_f32_16x16x32_bf16 v[120:123], v[64:67], v[192:195], v[120:123]
	v_mfma_f32_16x16x32_bf16 v[108:111], v[56:59], v[200:203], v[108:111]
	v_mfma_f32_16x16x32_bf16 v[104:107], v[64:67], v[200:203], v[104:107]
	v_mfma_f32_16x16x32_bf16 v[136:139], v[68:71], v[164:167], v[132:135]
	v_mfma_f32_16x16x32_bf16 v[124:127], v[60:63], v[196:199], v[124:127]
	v_mfma_f32_16x16x32_bf16 v[120:123], v[68:71], v[196:199], v[120:123]
	v_mfma_f32_16x16x32_bf16 v[108:111], v[60:63], v[208:211], v[108:111]
	v_mfma_f32_16x16x32_bf16 v[104:107], v[68:71], v[208:211], v[104:107]
	s_barrier
	s_mov_b32 m0, s43
	ds_read_b128 v[212:215], v206 offset:49152
	ds_read_b128 v[216:219], v206 offset:50176
	ds_read_b128 v[220:223], v206 offset:51200
	global_load_lds_dwordx4 v180, s[28:29]
	s_mov_b32 m0, s44
	ds_read_b128 v[236:239], v206 offset:52224
	global_load_lds_dwordx4 v184, s[28:29]
	s_barrier
	s_waitcnt lgkmcnt(0)
	v_mfma_f32_16x16x32_bf16 v[72:75], v[220:223], v[116:119], v[72:75]
	v_mfma_f32_16x16x32_bf16 v[132:135], v[212:215], v[116:119], v[148:151]
	v_mfma_f32_16x16x32_bf16 v[144:147], v[236:239], v[128:131], v[72:75]
	v_mfma_f32_16x16x32_bf16 v[72:75], v[212:215], v[160:163], v[76:79]
	v_mfma_f32_16x16x32_bf16 v[148:151], v[216:219], v[128:131], v[132:135]
	v_mfma_f32_16x16x32_bf16 v[132:135], v[216:219], v[164:167], v[72:75]
	v_mfma_f32_16x16x32_bf16 v[72:75], v[220:223], v[160:163], v[80:83]
	v_mfma_f32_16x16x32_bf16 v[128:131], v[236:239], v[164:167], v[72:75]
	v_mfma_f32_16x16x32_bf16 v[72:75], v[212:215], v[192:195], v[84:87]
	v_mfma_f32_16x16x32_bf16 v[116:119], v[216:219], v[196:199], v[72:75]
	v_mfma_f32_16x16x32_bf16 v[72:75], v[220:223], v[192:195], v[112:115]
	v_mfma_f32_16x16x32_bf16 v[112:115], v[236:239], v[196:199], v[72:75]
	v_mfma_f32_16x16x32_bf16 v[72:75], v[212:215], v[200:203], v[100:103]
	v_mfma_f32_16x16x32_bf16 v[100:103], v[216:219], v[208:211], v[72:75]
	v_mfma_f32_16x16x32_bf16 v[72:75], v[220:223], v[200:203], v[96:99]
	v_mfma_f32_16x16x32_bf16 v[96:99], v[236:239], v[208:211], v[72:75]
	s_barrier
	s_nop 2
	ds_read_b128 v[72:75], v207 offset:49152
	ds_read_b128 v[76:79], v207 offset:50176
	ds_read_b128 v[80:83], v207 offset:51200
	ds_read_b128 v[84:87], v207 offset:52224
	ds_read_b128 v[160:163], v207 offset:53248
	ds_read_b128 v[164:167], v207 offset:54272
	ds_read_b128 v[192:195], v207 offset:55296
	ds_read_b128 v[196:199], v207 offset:56320
	s_add_i32 m0, s40, 0x18000
	s_nop 0
	global_load_lds_dwordx4 v182, s[98:99]
	s_add_i32 m0, s40, 0x1a000
	s_nop 0
	global_load_lds_dwordx4 v186, s[98:99]
	s_barrier
	s_waitcnt lgkmcnt(0)
	v_mfma_f32_16x16x32_bf16 v[92:95], v[56:59], v[72:75], v[92:95]
	v_mfma_f32_16x16x32_bf16 v[88:91], v[64:67], v[72:75], v[88:91]
	v_mfma_f32_16x16x32_bf16 v[44:47], v[56:59], v[80:83], v[44:47]
	v_mfma_f32_16x16x32_bf16 v[40:43], v[64:67], v[80:83], v[40:43]
	v_mfma_f32_16x16x32_bf16 v[28:31], v[56:59], v[160:163], v[28:31]
	v_mfma_f32_16x16x32_bf16 v[24:27], v[64:67], v[160:163], v[24:27]
	v_mfma_f32_16x16x32_bf16 v[12:15], v[56:59], v[192:195], v[12:15]
	v_mfma_f32_16x16x32_bf16 v[8:11], v[64:67], v[192:195], v[8:11]
	v_mfma_f32_16x16x32_bf16 v[92:95], v[60:63], v[76:79], v[92:95]
	v_mfma_f32_16x16x32_bf16 v[88:91], v[68:71], v[76:79], v[88:91]
	v_mfma_f32_16x16x32_bf16 v[44:47], v[60:63], v[84:87], v[44:47]
	v_mfma_f32_16x16x32_bf16 v[40:43], v[68:71], v[84:87], v[40:43]
	v_mfma_f32_16x16x32_bf16 v[28:31], v[60:63], v[164:167], v[28:31]
	v_mfma_f32_16x16x32_bf16 v[24:27], v[68:71], v[164:167], v[24:27]
	v_mfma_f32_16x16x32_bf16 v[12:15], v[60:63], v[196:199], v[12:15]
	v_mfma_f32_16x16x32_bf16 v[8:11], v[68:71], v[196:199], v[8:11]
	s_barrier
	s_mov_b32 m0, s53
	s_nop 0
	global_load_lds_dwordx4 v180, s[100:101]
	s_mov_b32 m0, s54
	s_nop 0
	global_load_lds_dwordx4 v184, s[100:101]
	s_add_i32 m0, s40, 0x1c000
	s_add_u32 s2, s2, 0x40080
	s_addc_u32 s3, s3, 0
	global_load_lds_dwordx4 v182, s[2:3]
	s_add_i32 m0, s40, 0x1e000
	s_add_i32 s58, s58, 2
	global_load_lds_dwordx4 v186, s[2:3]
	s_waitcnt vmcnt(6)
	s_barrier
	v_mfma_f32_16x16x32_bf16 v[48:51], v[212:215], v[72:75], v[48:51]
	v_mfma_f32_16x16x32_bf16 v[64:67], v[216:219], v[76:79], v[48:51]
	v_mfma_f32_16x16x32_bf16 v[48:51], v[220:223], v[72:75], v[52:55]
	v_mfma_f32_16x16x32_bf16 v[36:39], v[212:215], v[80:83], v[36:39]
	v_mfma_f32_16x16x32_bf16 v[32:35], v[220:223], v[80:83], v[32:35]
	v_mfma_f32_16x16x32_bf16 v[20:23], v[212:215], v[160:163], v[20:23]
	v_mfma_f32_16x16x32_bf16 v[16:19], v[220:223], v[160:163], v[16:19]
	v_mfma_f32_16x16x32_bf16 v[4:7], v[212:215], v[192:195], v[4:7]
	v_mfma_f32_16x16x32_bf16 v[0:3], v[220:223], v[192:195], v[0:3]
	v_mfma_f32_16x16x32_bf16 v[56:59], v[236:239], v[76:79], v[48:51]
	v_mfma_f32_16x16x32_bf16 v[36:39], v[216:219], v[84:87], v[36:39]
	v_mfma_f32_16x16x32_bf16 v[32:35], v[236:239], v[84:87], v[32:35]
	v_mfma_f32_16x16x32_bf16 v[20:23], v[216:219], v[164:167], v[20:23]
	v_mfma_f32_16x16x32_bf16 v[16:19], v[236:239], v[164:167], v[16:19]
	v_mfma_f32_16x16x32_bf16 v[4:7], v[216:219], v[196:199], v[4:7]
	v_mfma_f32_16x16x32_bf16 v[0:3], v[236:239], v[196:199], v[0:3]
	s_add_u32 s8, s8, 0x100
	s_addc_u32 s9, s9, 0
	s_add_u32 s56, s56, 0x100
	s_addc_u32 s57, s57, 0
	s_cmp_gt_u32 s58, 13
	s_barrier
.LBB0_678:
	s_add_u32 s2, s8, 0xfffc0080
	s_addc_u32 s3, s9, -1
	ds_read_b128 v[48:51], v206
	ds_read_b128 v[52:55], v206 offset:1024
	ds_read_b128 v[60:63], v206 offset:2048
	ds_read_b128 v[68:71], v206 offset:3072
	s_cmp_eq_u32 s58, 12
	s_cselect_b32 s29, s1, s3
	s_cselect_b32 s28, s7, s2
	s_cselect_b32 s3, s21, s57
	s_cselect_b32 s2, s23, s56
	ds_read_b128 v[72:75], v207
	ds_read_b128 v[76:79], v207 offset:1024
	ds_read_b128 v[80:83], v207 offset:2048
	ds_read_b128 v[84:87], v207 offset:3072
	ds_read_b128 v[160:163], v207 offset:4096
	ds_read_b128 v[164:167], v207 offset:5120
	ds_read_b128 v[192:195], v207 offset:6144
	ds_read_b128 v[196:199], v207 offset:7168
	s_waitcnt lgkmcnt(8)
	s_barrier
	s_waitcnt lgkmcnt(0)
	v_mfma_f32_16x16x32_bf16 v[156:159], v[48:51], v[72:75], v[156:159]
	v_mfma_f32_16x16x32_bf16 v[152:155], v[60:63], v[72:75], v[152:155]
	v_mfma_f32_16x16x32_bf16 v[140:143], v[48:51], v[80:83], v[140:143]
	v_mfma_f32_16x16x32_bf16 v[136:139], v[60:63], v[80:83], v[136:139]
	v_mfma_f32_16x16x32_bf16 v[124:127], v[48:51], v[160:163], v[124:127]
	v_mfma_f32_16x16x32_bf16 v[120:123], v[60:63], v[160:163], v[120:123]
	v_mfma_f32_16x16x32_bf16 v[108:111], v[48:51], v[192:195], v[108:111]
	v_mfma_f32_16x16x32_bf16 v[104:107], v[60:63], v[192:195], v[104:107]
	v_mfma_f32_16x16x32_bf16 v[156:159], v[52:55], v[76:79], v[156:159]
	v_mfma_f32_16x16x32_bf16 v[152:155], v[68:71], v[76:79], v[152:155]
	v_mfma_f32_16x16x32_bf16 v[140:143], v[52:55], v[84:87], v[140:143]
	v_mfma_f32_16x16x32_bf16 v[136:139], v[68:71], v[84:87], v[136:139]
	v_mfma_f32_16x16x32_bf16 v[124:127], v[52:55], v[164:167], v[124:127]
	v_mfma_f32_16x16x32_bf16 v[120:123], v[68:71], v[164:167], v[120:123]
	v_mfma_f32_16x16x32_bf16 v[108:111], v[52:55], v[196:199], v[108:111]
	v_mfma_f32_16x16x32_bf16 v[104:107], v[68:71], v[196:199], v[104:107]
	s_barrier
	s_add_i32 m0, s41, 0xc000
	ds_read_b128 v[200:203], v206 offset:16384
	ds_read_b128 v[208:211], v206 offset:17408
	ds_read_b128 v[212:215], v206 offset:18432
	global_load_lds_dwordx4 v188, s[8:9]
	s_add_i32 m0, s41, 0xe000
	ds_read_b128 v[216:219], v206 offset:19456
	global_load_lds_dwordx4 v190, s[8:9]
	s_add_u32 s98, s2, 0x80
	s_addc_u32 s99, s3, 0
	s_barrier
	s_waitcnt lgkmcnt(0)
	v_mfma_f32_16x16x32_bf16 v[148:151], v[200:203], v[72:75], v[148:151]
	v_mfma_f32_16x16x32_bf16 v[72:75], v[212:215], v[72:75], v[144:147]
	v_mfma_f32_16x16x32_bf16 v[148:151], v[208:211], v[76:79], v[148:151]
	v_mfma_f32_16x16x32_bf16 v[72:75], v[216:219], v[76:79], v[72:75]
	v_mfma_f32_16x16x32_bf16 v[76:79], v[200:203], v[80:83], v[132:135]
	v_mfma_f32_16x16x32_bf16 v[80:83], v[212:215], v[80:83], v[128:131]
	v_mfma_f32_16x16x32_bf16 v[112:115], v[212:215], v[160:163], v[112:115]
	v_mfma_f32_16x16x32_bf16 v[100:103], v[200:203], v[192:195], v[100:103]
	v_mfma_f32_16x16x32_bf16 v[96:99], v[212:215], v[192:195], v[96:99]
	v_mfma_f32_16x16x32_bf16 v[76:79], v[208:211], v[84:87], v[76:79]
	v_mfma_f32_16x16x32_bf16 v[80:83], v[216:219], v[84:87], v[80:83]
	v_mfma_f32_16x16x32_bf16 v[84:87], v[200:203], v[160:163], v[116:119]
	v_mfma_f32_16x16x32_bf16 v[112:115], v[216:219], v[164:167], v[112:115]
	v_mfma_f32_16x16x32_bf16 v[100:103], v[208:211], v[196:199], v[100:103]
	v_mfma_f32_16x16x32_bf16 v[96:99], v[216:219], v[196:199], v[96:99]
	v_mfma_f32_16x16x32_bf16 v[84:87], v[208:211], v[164:167], v[84:87]
	s_add_u32 s100, s28, 0x80
	s_addc_u32 s101, s29, 0
	s_barrier
	ds_read_b128 v[116:119], v207 offset:16384
	ds_read_b128 v[128:131], v207 offset:17408
	ds_read_b128 v[132:135], v207 offset:18432
	ds_read_b128 v[144:147], v207 offset:19456
	ds_read_b128 v[160:163], v207 offset:20480
	ds_read_b128 v[164:167], v207 offset:21504
	ds_read_b128 v[192:195], v207 offset:22528
	ds_read_b128 v[196:199], v207 offset:23552
	s_add_i32 m0, s40, 0x10000
	s_nop 0
	global_load_lds_dwordx4 v182, s[2:3]
	s_add_i32 m0, s40, 0x12000
	s_nop 0
	global_load_lds_dwordx4 v186, s[2:3]
	s_barrier
	s_waitcnt lgkmcnt(0)
	v_mfma_f32_16x16x32_bf16 v[92:95], v[48:51], v[116:119], v[92:95]
	v_mfma_f32_16x16x32_bf16 v[88:91], v[60:63], v[116:119], v[88:91]
	v_mfma_f32_16x16x32_bf16 v[44:47], v[48:51], v[132:135], v[44:47]
	v_mfma_f32_16x16x32_bf16 v[40:43], v[60:63], v[132:135], v[40:43]
	v_mfma_f32_16x16x32_bf16 v[28:31], v[48:51], v[160:163], v[28:31]
	v_mfma_f32_16x16x32_bf16 v[24:27], v[60:63], v[160:163], v[24:27]
	v_mfma_f32_16x16x32_bf16 v[12:15], v[48:51], v[192:195], v[12:15]
	v_mfma_f32_16x16x32_bf16 v[8:11], v[60:63], v[192:195], v[8:11]
	v_mfma_f32_16x16x32_bf16 v[92:95], v[52:55], v[128:131], v[92:95]
	v_mfma_f32_16x16x32_bf16 v[88:91], v[68:71], v[128:131], v[88:91]
	v_mfma_f32_16x16x32_bf16 v[44:47], v[52:55], v[144:147], v[44:47]
	v_mfma_f32_16x16x32_bf16 v[40:43], v[68:71], v[144:147], v[40:43]
	v_mfma_f32_16x16x32_bf16 v[28:31], v[52:55], v[164:167], v[28:31]
	v_mfma_f32_16x16x32_bf16 v[24:27], v[68:71], v[164:167], v[24:27]
	v_mfma_f32_16x16x32_bf16 v[12:15], v[52:55], v[196:199], v[12:15]
	v_mfma_f32_16x16x32_bf16 v[8:11], v[68:71], v[196:199], v[8:11]
	s_barrier
	s_mov_b32 m0, s41
	s_nop 0
	global_load_lds_dwordx4 v180, s[28:29]
	s_mov_b32 m0, s42
	s_nop 0
	global_load_lds_dwordx4 v184, s[28:29]
	s_add_i32 m0, s40, 0x14000
	s_add_u32 s60, s2, 0x40000
	s_addc_u32 s61, s3, 0
	global_load_lds_dwordx4 v182, s[60:61]
	s_add_i32 m0, s40, 0x16000
	s_add_u32 s28, s28, 0x40000
	s_addc_u32 s29, s29, 0
	global_load_lds_dwordx4 v186, s[60:61]
	s_waitcnt vmcnt(6)
	s_barrier
	v_mfma_f32_16x16x32_bf16 v[36:39], v[200:203], v[132:135], v[36:39]
	v_mfma_f32_16x16x32_bf16 v[32:35], v[212:215], v[132:135], v[32:35]
	v_mfma_f32_16x16x32_bf16 v[20:23], v[200:203], v[160:163], v[20:23]
	v_mfma_f32_16x16x32_bf16 v[16:19], v[212:215], v[160:163], v[16:19]
	v_mfma_f32_16x16x32_bf16 v[4:7], v[200:203], v[192:195], v[4:7]
	v_mfma_f32_16x16x32_bf16 v[0:3], v[212:215], v[192:195], v[0:3]
	v_mfma_f32_16x16x32_bf16 v[48:51], v[200:203], v[116:119], v[64:67]
	v_mfma_f32_16x16x32_bf16 v[52:55], v[212:215], v[116:119], v[56:59]
	v_mfma_f32_16x16x32_bf16 v[36:39], v[208:211], v[144:147], v[36:39]
	v_mfma_f32_16x16x32_bf16 v[32:35], v[216:219], v[144:147], v[32:35]
	v_mfma_f32_16x16x32_bf16 v[20:23], v[208:211], v[164:167], v[20:23]
	v_mfma_f32_16x16x32_bf16 v[16:19], v[216:219], v[164:167], v[16:19]
	v_mfma_f32_16x16x32_bf16 v[4:7], v[208:211], v[196:199], v[4:7]
	v_mfma_f32_16x16x32_bf16 v[0:3], v[216:219], v[196:199], v[0:3]
	v_mfma_f32_16x16x32_bf16 v[48:51], v[208:211], v[128:131], v[48:51]
	v_mfma_f32_16x16x32_bf16 v[52:55], v[216:219], v[128:131], v[52:55]
	s_barrier
	ds_read_b128 v[56:59], v206 offset:32768
	ds_read_b128 v[60:63], v206 offset:33792
	ds_read_b128 v[64:67], v206 offset:34816
	ds_read_b128 v[68:71], v206 offset:35840
	ds_read_b128 v[116:119], v207 offset:32768
	ds_read_b128 v[128:131], v207 offset:33792
	ds_read_b128 v[160:163], v207 offset:34816
	ds_read_b128 v[164:167], v207 offset:35840
	ds_read_b128 v[192:195], v207 offset:36864
	ds_read_b128 v[196:199], v207 offset:37888
	ds_read_b128 v[200:203], v207 offset:38912
	ds_read_b128 v[208:211], v207 offset:39936
	s_waitcnt lgkmcnt(8)
	s_barrier
	s_waitcnt lgkmcnt(0)
	v_mfma_f32_16x16x32_bf16 v[132:135], v[56:59], v[116:119], v[156:159]
	v_mfma_f32_16x16x32_bf16 v[156:159], v[60:63], v[128:131], v[132:135]
	v_mfma_f32_16x16x32_bf16 v[132:135], v[64:67], v[116:119], v[152:155]
	v_mfma_f32_16x16x32_bf16 v[152:155], v[68:71], v[128:131], v[132:135]
	v_mfma_f32_16x16x32_bf16 v[132:135], v[56:59], v[160:163], v[140:143]
	v_mfma_f32_16x16x32_bf16 v[140:143], v[60:63], v[164:167], v[132:135]
	v_mfma_f32_16x16x32_bf16 v[132:135], v[64:67], v[160:163], v[136:139]
	v_mfma_f32_16x16x32_bf16 v[124:127], v[56:59], v[192:195], v[124:127]
	v_mfma_f32_16x16x32_bf16 v[120:123], v[64:67], v[192:195], v[120:123]
	v_mfma_f32_16x16x32_bf16 v[108:111], v[56:59], v[200:203], v[108:111]
	v_mfma_f32_16x16x32_bf16 v[104:107], v[64:67], v[200:203], v[104:107]
	v_mfma_f32_16x16x32_bf16 v[136:139], v[68:71], v[164:167], v[132:135]
	v_mfma_f32_16x16x32_bf16 v[124:127], v[60:63], v[196:199], v[124:127]
	v_mfma_f32_16x16x32_bf16 v[120:123], v[68:71], v[196:199], v[120:123]
	v_mfma_f32_16x16x32_bf16 v[108:111], v[60:63], v[208:211], v[108:111]
	v_mfma_f32_16x16x32_bf16 v[104:107], v[68:71], v[208:211], v[104:107]
	s_barrier
	s_mov_b32 m0, s43
	ds_read_b128 v[212:215], v206 offset:49152
	ds_read_b128 v[216:219], v206 offset:50176
	ds_read_b128 v[220:223], v206 offset:51200
	global_load_lds_dwordx4 v180, s[28:29]
	s_mov_b32 m0, s44
	ds_read_b128 v[236:239], v206 offset:52224
	global_load_lds_dwordx4 v184, s[28:29]
	s_barrier
	s_waitcnt lgkmcnt(0)
	v_mfma_f32_16x16x32_bf16 v[72:75], v[220:223], v[116:119], v[72:75]
	v_mfma_f32_16x16x32_bf16 v[132:135], v[212:215], v[116:119], v[148:151]
	v_mfma_f32_16x16x32_bf16 v[144:147], v[236:239], v[128:131], v[72:75]
	v_mfma_f32_16x16x32_bf16 v[72:75], v[212:215], v[160:163], v[76:79]
	v_mfma_f32_16x16x32_bf16 v[148:151], v[216:219], v[128:131], v[132:135]
	v_mfma_f32_16x16x32_bf16 v[132:135], v[216:219], v[164:167], v[72:75]
	v_mfma_f32_16x16x32_bf16 v[72:75], v[220:223], v[160:163], v[80:83]
	v_mfma_f32_16x16x32_bf16 v[128:131], v[236:239], v[164:167], v[72:75]
	v_mfma_f32_16x16x32_bf16 v[72:75], v[212:215], v[192:195], v[84:87]
	v_mfma_f32_16x16x32_bf16 v[116:119], v[216:219], v[196:199], v[72:75]
	v_mfma_f32_16x16x32_bf16 v[72:75], v[220:223], v[192:195], v[112:115]
	v_mfma_f32_16x16x32_bf16 v[112:115], v[236:239], v[196:199], v[72:75]
	v_mfma_f32_16x16x32_bf16 v[72:75], v[212:215], v[200:203], v[100:103]
	v_mfma_f32_16x16x32_bf16 v[100:103], v[216:219], v[208:211], v[72:75]
	v_mfma_f32_16x16x32_bf16 v[72:75], v[220:223], v[200:203], v[96:99]
	v_mfma_f32_16x16x32_bf16 v[96:99], v[236:239], v[208:211], v[72:75]
	s_barrier
	s_nop 2
	ds_read_b128 v[72:75], v207 offset:49152
	ds_read_b128 v[76:79], v207 offset:50176
	ds_read_b128 v[80:83], v207 offset:51200
	ds_read_b128 v[84:87], v207 offset:52224
	ds_read_b128 v[160:163], v207 offset:53248
	ds_read_b128 v[164:167], v207 offset:54272
	ds_read_b128 v[192:195], v207 offset:55296
	ds_read_b128 v[196:199], v207 offset:56320
	s_add_i32 m0, s40, 0x18000
	s_nop 0
	global_load_lds_dwordx4 v182, s[98:99]
	s_add_i32 m0, s40, 0x1a000
	s_nop 0
	global_load_lds_dwordx4 v186, s[98:99]
	s_barrier
	s_waitcnt lgkmcnt(0)
	v_mfma_f32_16x16x32_bf16 v[92:95], v[56:59], v[72:75], v[92:95]
	v_mfma_f32_16x16x32_bf16 v[88:91], v[64:67], v[72:75], v[88:91]
	v_mfma_f32_16x16x32_bf16 v[44:47], v[56:59], v[80:83], v[44:47]
	v_mfma_f32_16x16x32_bf16 v[40:43], v[64:67], v[80:83], v[40:43]
	v_mfma_f32_16x16x32_bf16 v[28:31], v[56:59], v[160:163], v[28:31]
	v_mfma_f32_16x16x32_bf16 v[24:27], v[64:67], v[160:163], v[24:27]
	v_mfma_f32_16x16x32_bf16 v[12:15], v[56:59], v[192:195], v[12:15]
	v_mfma_f32_16x16x32_bf16 v[8:11], v[64:67], v[192:195], v[8:11]
	v_mfma_f32_16x16x32_bf16 v[92:95], v[60:63], v[76:79], v[92:95]
	v_mfma_f32_16x16x32_bf16 v[88:91], v[68:71], v[76:79], v[88:91]
	v_mfma_f32_16x16x32_bf16 v[44:47], v[60:63], v[84:87], v[44:47]
	v_mfma_f32_16x16x32_bf16 v[40:43], v[68:71], v[84:87], v[40:43]
	v_mfma_f32_16x16x32_bf16 v[28:31], v[60:63], v[164:167], v[28:31]
	v_mfma_f32_16x16x32_bf16 v[24:27], v[68:71], v[164:167], v[24:27]
	v_mfma_f32_16x16x32_bf16 v[12:15], v[60:63], v[196:199], v[12:15]
	v_mfma_f32_16x16x32_bf16 v[8:11], v[68:71], v[196:199], v[8:11]
	s_barrier
	s_mov_b32 m0, s53
	s_nop 0
	global_load_lds_dwordx4 v180, s[100:101]
	s_mov_b32 m0, s54
	s_nop 0
	global_load_lds_dwordx4 v184, s[100:101]
	s_add_i32 m0, s40, 0x1c000
	s_add_u32 s2, s2, 0x40080
	s_addc_u32 s3, s3, 0
	global_load_lds_dwordx4 v182, s[2:3]
	s_add_i32 m0, s40, 0x1e000
	s_add_i32 s58, s58, 2
	global_load_lds_dwordx4 v186, s[2:3]
	s_waitcnt vmcnt(6)
	s_barrier
	v_mfma_f32_16x16x32_bf16 v[48:51], v[212:215], v[72:75], v[48:51]
	v_mfma_f32_16x16x32_bf16 v[64:67], v[216:219], v[76:79], v[48:51]
	v_mfma_f32_16x16x32_bf16 v[48:51], v[220:223], v[72:75], v[52:55]
	v_mfma_f32_16x16x32_bf16 v[36:39], v[212:215], v[80:83], v[36:39]
	v_mfma_f32_16x16x32_bf16 v[32:35], v[220:223], v[80:83], v[32:35]
	v_mfma_f32_16x16x32_bf16 v[20:23], v[212:215], v[160:163], v[20:23]
	v_mfma_f32_16x16x32_bf16 v[16:19], v[220:223], v[160:163], v[16:19]
	v_mfma_f32_16x16x32_bf16 v[4:7], v[212:215], v[192:195], v[4:7]
	v_mfma_f32_16x16x32_bf16 v[0:3], v[220:223], v[192:195], v[0:3]
	v_mfma_f32_16x16x32_bf16 v[56:59], v[236:239], v[76:79], v[48:51]
	v_mfma_f32_16x16x32_bf16 v[36:39], v[216:219], v[84:87], v[36:39]
	v_mfma_f32_16x16x32_bf16 v[32:35], v[236:239], v[84:87], v[32:35]
	v_mfma_f32_16x16x32_bf16 v[20:23], v[216:219], v[164:167], v[20:23]
	v_mfma_f32_16x16x32_bf16 v[16:19], v[236:239], v[164:167], v[16:19]
	v_mfma_f32_16x16x32_bf16 v[4:7], v[216:219], v[196:199], v[4:7]
	v_mfma_f32_16x16x32_bf16 v[0:3], v[236:239], v[196:199], v[0:3]
	s_add_u32 s8, s8, 0x100
	s_addc_u32 s9, s9, 0
	s_add_u32 s56, s56, 0x100
	s_addc_u32 s57, s57, 0
	s_cmp_gt_u32 s58, 13
	s_barrier
	s_cbranch_scc0 .LBB0_678
	s_lshl_b32 s1, s0, 8
	s_add_i32 s2, s1, s51
	s_lshl_b32 s1, s6, 8
	v_mov_b32_e32 v160, v205
	v_mov_b32_e32 v208, v204
	s_or_b32 s1, s1, s52
	s_nop 0
	v_lshl_add_u32 v192, v208, 3, s1
	s_add_i32 s1, s0, -16
	s_lshr_b32 s1, s1, 3
	s_add_i32 s1, s1, 1
	s_cmp_gt_i32 s0, 15
	s_cselect_b32 s3, s1, 0
	s_mul_i32 s96, s3, 0x1800
	s_lshl_b64 s[0:1], s[96:97], 2
	s_add_u32 s0, s45, s0
	v_ashrrev_i32_e32 v193, 31, v192
	s_addc_u32 s1, s46, s1
	v_lshlrev_b64 v[196:197], 2, v[192:193]
	s_lshl_b32 s96, s3, 10
	v_lshl_add_u64 v[48:49], s[0:1], 0, v[196:197]
	s_lshl_b64 s[0:1], s[96:97], 2
	s_add_u32 s0, s49, s0
	s_addc_u32 s1, s50, s1
	v_lshl_add_u64 v[52:53], s[0:1], 0, v[196:197]
	global_load_dwordx4 v[80:83], v[48:49], off offset:16
	global_load_dwordx4 v[84:87], v[48:49], off
	global_load_dwordx4 v[72:75], v[52:53], off offset:16
	global_load_dwordx4 v[76:79], v[52:53], off
	global_load_dwordx4 v[60:63], v[48:49], off offset:528
	global_load_dwordx4 v[68:71], v[48:49], off offset:512
	s_nop 0
	global_load_dwordx4 v[48:51], v[52:53], off offset:528
	s_nop 0
	global_load_dwordx4 v[52:55], v[52:53], off offset:512
	v_add_u32_e32 v194, s2, v160
	v_ashrrev_i32_e32 v195, 31, v194
	v_lshlrev_b64 v[160:161], 10, v[194:195]
	v_lshl_add_u64 v[198:199], v[160:161], 0, v[192:193]
	v_cndmask_b32_e64 v160, 0, 1, s[74:75]
	v_cmp_gt_i32_e64 s[0:1], s71, v194
	v_cmp_ne_u32_e64 s[6:7], 1, v160
	s_andn2_b64 vcc, exec, s[74:75]
	s_mov_b64 s[2:3], -1
	s_cbranch_vccnz .LBB0_681
	v_lshl_add_u64 v[160:161], v[198:199], 1, s[14:15]
	v_mov_b32_e32 v222, v160
	v_mov_b32_e32 v223, v161
	global_load_dwordx4 v[210:213], v[222:223], off
	global_load_dwordx4 v[214:217], v[222:223], off offset:256
	s_mov_b64 s[80:81], 0x8000
	v_lshl_add_u64 v[222:223], v[222:223], 0, s[80:81]
	global_load_dwordx4 v[218:221], v[222:223], off
	global_load_dwordx4 v[236:239], v[222:223], off offset:256
	s_mov_b64 s[2:3], 0
	s_waitcnt vmcnt(3)
	v_lshlrev_b32_e32 v164, 16, v210
	v_and_b32_e32 v165, 0xffff0000, v210
	v_lshlrev_b32_e32 v166, 16, v211
	v_and_b32_e32 v167, 0xffff0000, v211
	v_lshlrev_b32_e32 v160, 16, v212
	v_and_b32_e32 v161, 0xffff0000, v212
	v_lshlrev_b32_e32 v162, 16, v213
	v_and_b32_e32 v163, 0xffff0000, v213
	s_mov_b64 s[80:81], 0x8000
	v_lshl_add_u64 v[222:223], v[222:223], 0, s[80:81]
	global_load_dwordx4 v[210:213], v[222:223], off

.LBB0_879:
	s_ashr_i32 s39, s38, 31
	v_cmp_lt_i64_e32 vcc, s[12:13], v[178:179]
	s_lshl_b64 s[12:13], s[38:39], 19
	s_add_u32 s40, s49, s12
	s_addc_u32 s41, s50, s13
	s_lshl_b32 s84, s82, 18
	s_add_u32 s40, s40, s84
	s_addc_u32 s41, s41, 0
	s_and_b64 s[12:13], vcc, exec
	s_cselect_b32 s1, s41, s11
	s_cselect_b32 s9, s40, s10
	s_ashr_i32 s37, s36, 31
	s_lshl_b64 s[12:13], s[36:37], 19
	s_add_u32 s42, s51, s12
	s_addc_u32 s43, s52, s13
	s_and_b64 s[12:13], vcc, exec
	s_cselect_b32 s14, s43, s3
	s_cselect_b32 s15, s42, s2
	s_add_u32 s10, s10, 0x40080
	s_addc_u32 s11, s11, 0
	s_add_u32 s37, s2, 0x100
	s_addc_u32 s39, s3, 0
	s_mov_b32 s67, -2
	s_cmp_lg_u32 s83, 0
	s_cbranch_scc1 .Lup_half_peel
	s_add_u32 s2, s10, 0xfffc0080
	s_addc_u32 s3, s11, -1
	ds_read_b128 v[48:51], v237
	ds_read_b128 v[52:55], v237 offset:1024
	ds_read_b128 v[104:107], v237 offset:2048
	ds_read_b128 v[108:111], v237 offset:3072
	s_cmp_eq_u32 s67, 12
	s_cselect_b32 s13, s1, s3
	s_cselect_b32 s12, s9, s2
	s_cselect_b32 s3, s14, s39
	s_cselect_b32 s2, s15, s37
	ds_read_b128 v[112:115], v238
	ds_read_b128 v[116:119], v238 offset:1024
	ds_read_b128 v[120:123], v238 offset:2048
	ds_read_b128 v[156:159], v238 offset:3072
	ds_read_b128 v[160:163], v238 offset:4096
	ds_read_b128 v[164:167], v238 offset:5120
	ds_read_b128 v[190:193], v238 offset:6144
	ds_read_b128 v[194:197], v238 offset:7168
	s_waitcnt lgkmcnt(8)
	s_barrier
	s_waitcnt lgkmcnt(0)
	v_mfma_f32_16x16x32_bf16 v[152:155], v[48:51], v[112:115], 0
	v_mfma_f32_16x16x32_bf16 v[68:71], v[104:107], v[112:115], 0
	v_mfma_f32_16x16x32_bf16 v[148:151], v[48:51], v[120:123], 0
	v_mfma_f32_16x16x32_bf16 v[64:67], v[104:107], v[120:123], 0
	v_mfma_f32_16x16x32_bf16 v[136:139], v[48:51], v[160:163], 0
	v_mfma_f32_16x16x32_bf16 v[44:47], v[104:107], v[160:163], 0
	v_mfma_f32_16x16x32_bf16 v[128:131], v[48:51], v[190:193], 0
	v_mfma_f32_16x16x32_bf16 v[40:43], v[104:107], v[190:193], 0
	v_mfma_f32_16x16x32_bf16 v[152:155], v[52:55], v[116:119], v[152:155]
	v_mfma_f32_16x16x32_bf16 v[68:71], v[108:111], v[116:119], v[68:71]
	v_mfma_f32_16x16x32_bf16 v[148:151], v[52:55], v[156:159], v[148:151]
	v_mfma_f32_16x16x32_bf16 v[64:67], v[108:111], v[156:159], v[64:67]
	v_mfma_f32_16x16x32_bf16 v[136:139], v[52:55], v[164:167], v[136:139]
	v_mfma_f32_16x16x32_bf16 v[44:47], v[108:111], v[164:167], v[44:47]
	v_mfma_f32_16x16x32_bf16 v[128:131], v[52:55], v[194:197], v[128:131]
	v_mfma_f32_16x16x32_bf16 v[40:43], v[108:111], v[194:197], v[40:43]
	s_barrier
	s_add_i32 m0, s54, 0xc000
	ds_read_b128 v[198:201], v237 offset:16384
	ds_read_b128 v[202:205], v237 offset:17408
	ds_read_b128 v[206:209], v237 offset:18432
	global_load_lds_dwordx4 v186, s[10:11]
	s_add_i32 m0, s54, 0xe000
	ds_read_b128 v[210:213], v237 offset:19456
	global_load_lds_dwordx4 v188, s[10:11]
	s_add_u32 s98, s2, 0x80
	s_addc_u32 s99, s3, 0
	s_barrier
	s_waitcnt lgkmcnt(0)
	v_mfma_f32_16x16x32_bf16 v[144:147], v[198:201], v[112:115], 0
	v_mfma_f32_16x16x32_bf16 v[60:63], v[206:209], v[112:115], 0
	v_mfma_f32_16x16x32_bf16 v[56:59], v[206:209], v[120:123], 0
	v_mfma_f32_16x16x32_bf16 v[36:39], v[206:209], v[160:163], 0
	v_mfma_f32_16x16x32_bf16 v[32:35], v[206:209], v[190:193], 0
	v_mfma_f32_16x16x32_bf16 v[144:147], v[202:205], v[116:119], v[144:147]
	v_mfma_f32_16x16x32_bf16 v[60:63], v[210:213], v[116:119], v[60:63]
	v_mfma_f32_16x16x32_bf16 v[112:115], v[198:201], v[120:123], 0
	v_mfma_f32_16x16x32_bf16 v[56:59], v[210:213], v[156:159], v[56:59]
	v_mfma_f32_16x16x32_bf16 v[116:119], v[198:201], v[160:163], 0
	v_mfma_f32_16x16x32_bf16 v[36:39], v[210:213], v[164:167], v[36:39]
	v_mfma_f32_16x16x32_bf16 v[120:123], v[198:201], v[190:193], 0
	v_mfma_f32_16x16x32_bf16 v[32:35], v[210:213], v[194:197], v[32:35]
	v_mfma_f32_16x16x32_bf16 v[112:115], v[202:205], v[156:159], v[112:115]
	v_mfma_f32_16x16x32_bf16 v[116:119], v[202:205], v[164:167], v[116:119]
	v_mfma_f32_16x16x32_bf16 v[120:123], v[202:205], v[194:197], v[120:123]
	s_add_u32 s100, s12, 0x80
	s_addc_u32 s101, s13, 0
	s_barrier
	ds_read_b128 v[124:127], v238 offset:16384
	ds_read_b128 v[132:135], v238 offset:17408
	ds_read_b128 v[140:143], v238 offset:18432
	ds_read_b128 v[156:159], v238 offset:19456
	ds_read_b128 v[160:163], v238 offset:20480
	ds_read_b128 v[164:167], v238 offset:21504
	ds_read_b128 v[190:193], v238 offset:22528
	ds_read_b128 v[194:197], v238 offset:23552
	s_add_i32 m0, s53, 0x10000
	s_nop 0
	global_load_lds_dwordx4 v168, s[2:3]
	s_add_i32 m0, s53, 0x12000
	s_nop 0
	global_load_lds_dwordx4 v184, s[2:3]
	s_barrier
	s_waitcnt lgkmcnt(0)
	v_mfma_f32_16x16x32_bf16 v[100:103], v[48:51], v[124:127], 0
	v_mfma_f32_16x16x32_bf16 v[28:31], v[104:107], v[124:127], 0
	v_mfma_f32_16x16x32_bf16 v[96:99], v[48:51], v[140:143], 0
	v_mfma_f32_16x16x32_bf16 v[24:27], v[104:107], v[140:143], 0
	v_mfma_f32_16x16x32_bf16 v[84:87], v[48:51], v[160:163], 0
	v_mfma_f32_16x16x32_bf16 v[12:15], v[104:107], v[160:163], 0
	v_mfma_f32_16x16x32_bf16 v[8:11], v[104:107], v[190:193], 0
	v_mfma_f32_16x16x32_bf16 v[100:103], v[52:55], v[132:135], v[100:103]
	v_mfma_f32_16x16x32_bf16 v[28:31], v[108:111], v[132:135], v[28:31]
	v_mfma_f32_16x16x32_bf16 v[96:99], v[52:55], v[156:159], v[96:99]
	v_mfma_f32_16x16x32_bf16 v[24:27], v[108:111], v[156:159], v[24:27]
	v_mfma_f32_16x16x32_bf16 v[84:87], v[52:55], v[164:167], v[84:87]
	v_mfma_f32_16x16x32_bf16 v[12:15], v[108:111], v[164:167], v[12:15]
	v_mfma_f32_16x16x32_bf16 v[48:51], v[48:51], v[190:193], 0
	v_mfma_f32_16x16x32_bf16 v[8:11], v[108:111], v[194:197], v[8:11]
	v_mfma_f32_16x16x32_bf16 v[48:51], v[52:55], v[194:197], v[48:51]
	s_barrier
	s_mov_b32 m0, s54
	s_nop 0
	global_load_lds_dwordx4 v180, s[12:13]
	s_mov_b32 m0, s55
	s_nop 0
	global_load_lds_dwordx4 v182, s[12:13]
	s_add_i32 m0, s53, 0x14000
	s_add_u32 s68, s2, 0x40000
	s_addc_u32 s69, s3, 0
	global_load_lds_dwordx4 v168, s[68:69]
	s_add_i32 m0, s53, 0x16000
	s_add_u32 s12, s12, 0x40000
	s_addc_u32 s13, s13, 0
	global_load_lds_dwordx4 v184, s[68:69]
	s_waitcnt vmcnt(6)
	s_barrier
	v_mfma_f32_16x16x32_bf16 v[76:79], v[198:201], v[140:143], 0
	v_mfma_f32_16x16x32_bf16 v[20:23], v[206:209], v[124:127], 0
	v_mfma_f32_16x16x32_bf16 v[88:91], v[202:205], v[156:159], v[76:79]
	v_mfma_f32_16x16x32_bf16 v[16:19], v[206:209], v[140:143], 0
	v_mfma_f32_16x16x32_bf16 v[76:79], v[198:201], v[160:163], 0
	v_mfma_f32_16x16x32_bf16 v[4:7], v[206:209], v[160:163], 0
	v_mfma_f32_16x16x32_bf16 v[72:75], v[198:201], v[190:193], 0
	v_mfma_f32_16x16x32_bf16 v[0:3], v[206:209], v[190:193], 0
	v_mfma_f32_16x16x32_bf16 v[52:55], v[198:201], v[124:127], 0
	v_mfma_f32_16x16x32_bf16 v[20:23], v[210:213], v[132:135], v[20:23]
	v_mfma_f32_16x16x32_bf16 v[16:19], v[210:213], v[156:159], v[16:19]
	v_mfma_f32_16x16x32_bf16 v[80:83], v[202:205], v[164:167], v[76:79]
	v_mfma_f32_16x16x32_bf16 v[4:7], v[210:213], v[164:167], v[4:7]
	v_mfma_f32_16x16x32_bf16 v[72:75], v[202:205], v[194:197], v[72:75]
	v_mfma_f32_16x16x32_bf16 v[0:3], v[210:213], v[194:197], v[0:3]
	v_mfma_f32_16x16x32_bf16 v[52:55], v[202:205], v[132:135], v[52:55]
	s_barrier
	ds_read_b128 v[76:79], v237 offset:32768
	ds_read_b128 v[92:95], v237 offset:33792
	ds_read_b128 v[104:107], v237 offset:34816
	ds_read_b128 v[108:111], v237 offset:35840
	ds_read_b128 v[124:127], v238 offset:32768
	ds_read_b128 v[132:135], v238 offset:33792
	ds_read_b128 v[156:159], v238 offset:34816
	ds_read_b128 v[160:163], v238 offset:35840
	ds_read_b128 v[164:167], v238 offset:36864
	ds_read_b128 v[190:193], v238 offset:37888
	ds_read_b128 v[194:197], v238 offset:38912
	ds_read_b128 v[198:201], v238 offset:39936
	s_waitcnt lgkmcnt(8)
	s_barrier
	s_waitcnt lgkmcnt(0)
	v_mfma_f32_16x16x32_bf16 v[140:143], v[76:79], v[124:127], v[152:155]
	v_mfma_f32_16x16x32_bf16 v[152:155], v[92:95], v[132:135], v[140:143]
	v_mfma_f32_16x16x32_bf16 v[68:71], v[104:107], v[124:127], v[68:71]
	v_mfma_f32_16x16x32_bf16 v[140:143], v[76:79], v[156:159], v[148:151]
	v_mfma_f32_16x16x32_bf16 v[64:67], v[104:107], v[156:159], v[64:67]
	v_mfma_f32_16x16x32_bf16 v[136:139], v[76:79], v[164:167], v[136:139]
	v_mfma_f32_16x16x32_bf16 v[44:47], v[104:107], v[164:167], v[44:47]
	v_mfma_f32_16x16x32_bf16 v[128:131], v[76:79], v[194:197], v[128:131]
	v_mfma_f32_16x16x32_bf16 v[40:43], v[104:107], v[194:197], v[40:43]
	v_mfma_f32_16x16x32_bf16 v[68:71], v[108:111], v[132:135], v[68:71]
	v_mfma_f32_16x16x32_bf16 v[148:151], v[92:95], v[160:163], v[140:143]
	v_mfma_f32_16x16x32_bf16 v[64:67], v[108:111], v[160:163], v[64:67]
	v_mfma_f32_16x16x32_bf16 v[136:139], v[92:95], v[190:193], v[136:139]
	v_mfma_f32_16x16x32_bf16 v[44:47], v[108:111], v[190:193], v[44:47]
	v_mfma_f32_16x16x32_bf16 v[128:131], v[92:95], v[198:201], v[128:131]
	v_mfma_f32_16x16x32_bf16 v[40:43], v[108:111], v[198:201], v[40:43]
	s_barrier
	s_mov_b32 m0, s56
	ds_read_b128 v[202:205], v237 offset:49152
	ds_read_b128 v[206:209], v237 offset:50176
	ds_read_b128 v[210:213], v237 offset:51200
	global_load_lds_dwordx4 v180, s[12:13]
	s_mov_b32 m0, s57
	ds_read_b128 v[214:217], v237 offset:52224
	global_load_lds_dwordx4 v182, s[12:13]
	s_barrier
	s_waitcnt lgkmcnt(0)
	v_mfma_f32_16x16x32_bf16 v[140:143], v[202:205], v[124:127], v[144:147]
	v_mfma_f32_16x16x32_bf16 v[112:115], v[202:205], v[156:159], v[112:115]
	v_mfma_f32_16x16x32_bf16 v[144:147], v[206:209], v[132:135], v[140:143]
	v_mfma_f32_16x16x32_bf16 v[60:63], v[210:213], v[124:127], v[60:63]
	v_mfma_f32_16x16x32_bf16 v[140:143], v[206:209], v[160:163], v[112:115]
	v_mfma_f32_16x16x32_bf16 v[112:115], v[202:205], v[164:167], v[116:119]
	v_mfma_f32_16x16x32_bf16 v[60:63], v[214:217], v[132:135], v[60:63]
	v_mfma_f32_16x16x32_bf16 v[56:59], v[210:213], v[156:159], v[56:59]
	v_mfma_f32_16x16x32_bf16 v[132:135], v[206:209], v[190:193], v[112:115]
	v_mfma_f32_16x16x32_bf16 v[36:39], v[210:213], v[164:167], v[36:39]
	v_mfma_f32_16x16x32_bf16 v[112:115], v[202:205], v[194:197], v[120:123]
	v_mfma_f32_16x16x32_bf16 v[32:35], v[210:213], v[194:197], v[32:35]
	v_mfma_f32_16x16x32_bf16 v[56:59], v[214:217], v[160:163], v[56:59]
	v_mfma_f32_16x16x32_bf16 v[36:39], v[214:217], v[190:193], v[36:39]
	v_mfma_f32_16x16x32_bf16 v[124:127], v[206:209], v[198:201], v[112:115]
	v_mfma_f32_16x16x32_bf16 v[32:35], v[214:217], v[198:201], v[32:35]
	s_barrier
	ds_read_b128 v[112:115], v238 offset:49152
	ds_read_b128 v[116:119], v238 offset:50176
	ds_read_b128 v[120:123], v238 offset:51200
	ds_read_b128 v[156:159], v238 offset:52224
	ds_read_b128 v[160:163], v238 offset:53248
	ds_read_b128 v[164:167], v238 offset:54272
	ds_read_b128 v[190:193], v238 offset:55296
	ds_read_b128 v[194:197], v238 offset:56320
	s_add_i32 m0, s53, 0x18000
	s_nop 0
	global_load_lds_dwordx4 v168, s[98:99]
	s_add_i32 m0, s53, 0x1a000
	s_nop 0
	global_load_lds_dwordx4 v184, s[98:99]
	s_barrier
	s_waitcnt lgkmcnt(0)
	v_mfma_f32_16x16x32_bf16 v[100:103], v[76:79], v[112:115], v[100:103]
	v_mfma_f32_16x16x32_bf16 v[28:31], v[104:107], v[112:115], v[28:31]
	v_mfma_f32_16x16x32_bf16 v[96:99], v[76:79], v[120:123], v[96:99]
	v_mfma_f32_16x16x32_bf16 v[24:27], v[104:107], v[120:123], v[24:27]
	v_mfma_f32_16x16x32_bf16 v[84:87], v[76:79], v[160:163], v[84:87]
	v_mfma_f32_16x16x32_bf16 v[12:15], v[104:107], v[160:163], v[12:15]
	v_mfma_f32_16x16x32_bf16 v[48:51], v[76:79], v[190:193], v[48:51]
	v_mfma_f32_16x16x32_bf16 v[8:11], v[104:107], v[190:193], v[8:11]
	v_mfma_f32_16x16x32_bf16 v[100:103], v[92:95], v[116:119], v[100:103]
	v_mfma_f32_16x16x32_bf16 v[28:31], v[108:111], v[116:119], v[28:31]
	v_mfma_f32_16x16x32_bf16 v[96:99], v[92:95], v[156:159], v[96:99]
	v_mfma_f32_16x16x32_bf16 v[24:27], v[108:111], v[156:159], v[24:27]
	v_mfma_f32_16x16x32_bf16 v[84:87], v[92:95], v[164:167], v[84:87]
	v_mfma_f32_16x16x32_bf16 v[12:15], v[108:111], v[164:167], v[12:15]
	v_mfma_f32_16x16x32_bf16 v[76:79], v[92:95], v[194:197], v[48:51]
	v_mfma_f32_16x16x32_bf16 v[8:11], v[108:111], v[194:197], v[8:11]
	s_barrier
	s_mov_b32 m0, s62
	s_nop 0
	global_load_lds_dwordx4 v180, s[100:101]
	s_mov_b32 m0, s63
	s_nop 0
	global_load_lds_dwordx4 v182, s[100:101]
	s_add_i32 m0, s53, 0x1c000
	s_add_u32 s2, s2, 0x40080
	s_addc_u32 s3, s3, 0
	global_load_lds_dwordx4 v168, s[2:3]
	s_add_i32 m0, s53, 0x1e000
	s_add_i32 s67, s67, 2
	global_load_lds_dwordx4 v184, s[2:3]
	s_waitcnt vmcnt(6)
	s_barrier
	v_mfma_f32_16x16x32_bf16 v[48:51], v[202:205], v[112:115], v[52:55]
	v_mfma_f32_16x16x32_bf16 v[92:95], v[206:209], v[116:119], v[48:51]
	v_mfma_f32_16x16x32_bf16 v[48:51], v[202:205], v[120:123], v[88:91]
	v_mfma_f32_16x16x32_bf16 v[88:91], v[206:209], v[156:159], v[48:51]
	v_mfma_f32_16x16x32_bf16 v[48:51], v[202:205], v[160:163], v[80:83]
	v_mfma_f32_16x16x32_bf16 v[20:23], v[210:213], v[112:115], v[20:23]
	v_mfma_f32_16x16x32_bf16 v[16:19], v[210:213], v[120:123], v[16:19]
	v_mfma_f32_16x16x32_bf16 v[80:83], v[206:209], v[164:167], v[48:51]
	v_mfma_f32_16x16x32_bf16 v[4:7], v[210:213], v[160:163], v[4:7]
	v_mfma_f32_16x16x32_bf16 v[48:51], v[202:205], v[190:193], v[72:75]
	v_mfma_f32_16x16x32_bf16 v[0:3], v[210:213], v[190:193], v[0:3]
	v_mfma_f32_16x16x32_bf16 v[20:23], v[214:217], v[116:119], v[20:23]
	v_mfma_f32_16x16x32_bf16 v[16:19], v[214:217], v[156:159], v[16:19]
	v_mfma_f32_16x16x32_bf16 v[4:7], v[214:217], v[164:167], v[4:7]
	v_mfma_f32_16x16x32_bf16 v[72:75], v[206:209], v[194:197], v[48:51]
	v_mfma_f32_16x16x32_bf16 v[0:3], v[214:217], v[194:197], v[0:3]
	s_add_u32 s10, s10, 0x100
	s_addc_u32 s11, s11, 0
	s_add_u32 s37, s37, 0x100
	s_addc_u32 s39, s39, 0
	s_cmp_gt_u32 s67, 13
	s_barrier
.LBB0_880:
	s_add_u32 s2, s10, 0xfffc0080
	s_addc_u32 s3, s11, -1
	ds_read_b128 v[48:51], v237
	ds_read_b128 v[52:55], v237 offset:1024
	ds_read_b128 v[104:107], v237 offset:2048
	ds_read_b128 v[108:111], v237 offset:3072
	s_cmp_eq_u32 s67, 12
	s_cselect_b32 s13, s1, s3
	s_cselect_b32 s12, s9, s2
	s_cselect_b32 s3, s14, s39
	s_cselect_b32 s2, s15, s37
	ds_read_b128 v[112:115], v238
	ds_read_b128 v[116:119], v238 offset:1024
	ds_read_b128 v[120:123], v238 offset:2048
	ds_read_b128 v[156:159], v238 offset:3072
	ds_read_b128 v[160:163], v238 offset:4096
	ds_read_b128 v[164:167], v238 offset:5120
	ds_read_b128 v[190:193], v238 offset:6144
	ds_read_b128 v[194:197], v238 offset:7168
	s_waitcnt lgkmcnt(8)
	s_barrier
	s_waitcnt lgkmcnt(0)
	v_mfma_f32_16x16x32_bf16 v[152:155], v[48:51], v[112:115], v[152:155]
	v_mfma_f32_16x16x32_bf16 v[68:71], v[104:107], v[112:115], v[68:71]
	v_mfma_f32_16x16x32_bf16 v[148:151], v[48:51], v[120:123], v[148:151]
	v_mfma_f32_16x16x32_bf16 v[64:67], v[104:107], v[120:123], v[64:67]
	v_mfma_f32_16x16x32_bf16 v[136:139], v[48:51], v[160:163], v[136:139]
	v_mfma_f32_16x16x32_bf16 v[44:47], v[104:107], v[160:163], v[44:47]
	v_mfma_f32_16x16x32_bf16 v[128:131], v[48:51], v[190:193], v[128:131]
	v_mfma_f32_16x16x32_bf16 v[40:43], v[104:107], v[190:193], v[40:43]
	v_mfma_f32_16x16x32_bf16 v[152:155], v[52:55], v[116:119], v[152:155]
	v_mfma_f32_16x16x32_bf16 v[68:71], v[108:111], v[116:119], v[68:71]
	v_mfma_f32_16x16x32_bf16 v[148:151], v[52:55], v[156:159], v[148:151]
	v_mfma_f32_16x16x32_bf16 v[64:67], v[108:111], v[156:159], v[64:67]
	v_mfma_f32_16x16x32_bf16 v[136:139], v[52:55], v[164:167], v[136:139]
	v_mfma_f32_16x16x32_bf16 v[44:47], v[108:111], v[164:167], v[44:47]
	v_mfma_f32_16x16x32_bf16 v[128:131], v[52:55], v[194:197], v[128:131]
	v_mfma_f32_16x16x32_bf16 v[40:43], v[108:111], v[194:197], v[40:43]
	s_barrier
	s_add_i32 m0, s54, 0xc000
	ds_read_b128 v[198:201], v237 offset:16384
	ds_read_b128 v[202:205], v237 offset:17408
	ds_read_b128 v[206:209], v237 offset:18432
	global_load_lds_dwordx4 v186, s[10:11]
	s_add_i32 m0, s54, 0xe000
	ds_read_b128 v[210:213], v237 offset:19456
	global_load_lds_dwordx4 v188, s[10:11]
	s_add_u32 s98, s2, 0x80
	s_addc_u32 s99, s3, 0
	s_barrier
	s_waitcnt lgkmcnt(0)
	v_mfma_f32_16x16x32_bf16 v[144:147], v[198:201], v[112:115], v[144:147]
	v_mfma_f32_16x16x32_bf16 v[60:63], v[206:209], v[112:115], v[60:63]
	v_mfma_f32_16x16x32_bf16 v[56:59], v[206:209], v[120:123], v[56:59]
	v_mfma_f32_16x16x32_bf16 v[36:39], v[206:209], v[160:163], v[36:39]
	v_mfma_f32_16x16x32_bf16 v[32:35], v[206:209], v[190:193], v[32:35]
	v_mfma_f32_16x16x32_bf16 v[144:147], v[202:205], v[116:119], v[144:147]
	v_mfma_f32_16x16x32_bf16 v[60:63], v[210:213], v[116:119], v[60:63]
	v_mfma_f32_16x16x32_bf16 v[112:115], v[198:201], v[120:123], v[140:143]
	v_mfma_f32_16x16x32_bf16 v[56:59], v[210:213], v[156:159], v[56:59]
	v_mfma_f32_16x16x32_bf16 v[116:119], v[198:201], v[160:163], v[132:135]
	v_mfma_f32_16x16x32_bf16 v[36:39], v[210:213], v[164:167], v[36:39]
	v_mfma_f32_16x16x32_bf16 v[120:123], v[198:201], v[190:193], v[124:127]
	v_mfma_f32_16x16x32_bf16 v[32:35], v[210:213], v[194:197], v[32:35]
	v_mfma_f32_16x16x32_bf16 v[112:115], v[202:205], v[156:159], v[112:115]
	v_mfma_f32_16x16x32_bf16 v[116:119], v[202:205], v[164:167], v[116:119]
	v_mfma_f32_16x16x32_bf16 v[120:123], v[202:205], v[194:197], v[120:123]
	s_add_u32 s100, s12, 0x80
	s_addc_u32 s101, s13, 0
	s_barrier
	ds_read_b128 v[124:127], v238 offset:16384
	ds_read_b128 v[132:135], v238 offset:17408
	ds_read_b128 v[140:143], v238 offset:18432
	ds_read_b128 v[156:159], v238 offset:19456
	ds_read_b128 v[160:163], v238 offset:20480
	ds_read_b128 v[164:167], v238 offset:21504
	ds_read_b128 v[190:193], v238 offset:22528
	ds_read_b128 v[194:197], v238 offset:23552
	s_add_i32 m0, s53, 0x10000
	s_nop 0
	global_load_lds_dwordx4 v168, s[2:3]
	s_add_i32 m0, s53, 0x12000
	s_nop 0
	global_load_lds_dwordx4 v184, s[2:3]
	s_barrier
	s_waitcnt lgkmcnt(0)
	v_mfma_f32_16x16x32_bf16 v[100:103], v[48:51], v[124:127], v[100:103]
	v_mfma_f32_16x16x32_bf16 v[28:31], v[104:107], v[124:127], v[28:31]
	v_mfma_f32_16x16x32_bf16 v[96:99], v[48:51], v[140:143], v[96:99]
	v_mfma_f32_16x16x32_bf16 v[24:27], v[104:107], v[140:143], v[24:27]
	v_mfma_f32_16x16x32_bf16 v[84:87], v[48:51], v[160:163], v[84:87]
	v_mfma_f32_16x16x32_bf16 v[12:15], v[104:107], v[160:163], v[12:15]
	v_mfma_f32_16x16x32_bf16 v[8:11], v[104:107], v[190:193], v[8:11]
	v_mfma_f32_16x16x32_bf16 v[100:103], v[52:55], v[132:135], v[100:103]
	v_mfma_f32_16x16x32_bf16 v[28:31], v[108:111], v[132:135], v[28:31]
	v_mfma_f32_16x16x32_bf16 v[96:99], v[52:55], v[156:159], v[96:99]
	v_mfma_f32_16x16x32_bf16 v[24:27], v[108:111], v[156:159], v[24:27]
	v_mfma_f32_16x16x32_bf16 v[84:87], v[52:55], v[164:167], v[84:87]
	v_mfma_f32_16x16x32_bf16 v[12:15], v[108:111], v[164:167], v[12:15]
	v_mfma_f32_16x16x32_bf16 v[48:51], v[48:51], v[190:193], v[76:79]
	v_mfma_f32_16x16x32_bf16 v[8:11], v[108:111], v[194:197], v[8:11]
	v_mfma_f32_16x16x32_bf16 v[48:51], v[52:55], v[194:197], v[48:51]
	s_barrier
	s_mov_b32 m0, s54
	s_nop 0
	global_load_lds_dwordx4 v180, s[12:13]
	s_mov_b32 m0, s55
	s_nop 0
	global_load_lds_dwordx4 v182, s[12:13]
	s_add_i32 m0, s53, 0x14000
	s_add_u32 s68, s2, 0x40000
	s_addc_u32 s69, s3, 0
	global_load_lds_dwordx4 v168, s[68:69]
	s_add_i32 m0, s53, 0x16000
	s_add_u32 s12, s12, 0x40000
	s_addc_u32 s13, s13, 0
	global_load_lds_dwordx4 v184, s[68:69]
	s_waitcnt vmcnt(6)
	s_barrier
	v_mfma_f32_16x16x32_bf16 v[76:79], v[198:201], v[140:143], v[88:91]
	v_mfma_f32_16x16x32_bf16 v[20:23], v[206:209], v[124:127], v[20:23]
	v_mfma_f32_16x16x32_bf16 v[88:91], v[202:205], v[156:159], v[76:79]
	v_mfma_f32_16x16x32_bf16 v[16:19], v[206:209], v[140:143], v[16:19]
	v_mfma_f32_16x16x32_bf16 v[76:79], v[198:201], v[160:163], v[80:83]
	v_mfma_f32_16x16x32_bf16 v[4:7], v[206:209], v[160:163], v[4:7]
	v_mfma_f32_16x16x32_bf16 v[72:75], v[198:201], v[190:193], v[72:75]
	v_mfma_f32_16x16x32_bf16 v[0:3], v[206:209], v[190:193], v[0:3]
	v_mfma_f32_16x16x32_bf16 v[52:55], v[198:201], v[124:127], v[92:95]
	v_mfma_f32_16x16x32_bf16 v[20:23], v[210:213], v[132:135], v[20:23]
	v_mfma_f32_16x16x32_bf16 v[16:19], v[210:213], v[156:159], v[16:19]
	v_mfma_f32_16x16x32_bf16 v[80:83], v[202:205], v[164:167], v[76:79]
	v_mfma_f32_16x16x32_bf16 v[4:7], v[210:213], v[164:167], v[4:7]
	v_mfma_f32_16x16x32_bf16 v[72:75], v[202:205], v[194:197], v[72:75]
	v_mfma_f32_16x16x32_bf16 v[0:3], v[210:213], v[194:197], v[0:3]
	v_mfma_f32_16x16x32_bf16 v[52:55], v[202:205], v[132:135], v[52:55]
	s_barrier
	ds_read_b128 v[76:79], v237 offset:32768
	ds_read_b128 v[92:95], v237 offset:33792
	ds_read_b128 v[104:107], v237 offset:34816
	ds_read_b128 v[108:111], v237 offset:35840
	ds_read_b128 v[124:127], v238 offset:32768
	ds_read_b128 v[132:135], v238 offset:33792
	ds_read_b128 v[156:159], v238 offset:34816
	ds_read_b128 v[160:163], v238 offset:35840
	ds_read_b128 v[164:167], v238 offset:36864
	ds_read_b128 v[190:193], v238 offset:37888
	ds_read_b128 v[194:197], v238 offset:38912
	ds_read_b128 v[198:201], v238 offset:39936
	s_waitcnt lgkmcnt(8)
	s_barrier
	s_waitcnt lgkmcnt(0)
	v_mfma_f32_16x16x32_bf16 v[140:143], v[76:79], v[124:127], v[152:155]
	v_mfma_f32_16x16x32_bf16 v[152:155], v[92:95], v[132:135], v[140:143]
	v_mfma_f32_16x16x32_bf16 v[68:71], v[104:107], v[124:127], v[68:71]
	v_mfma_f32_16x16x32_bf16 v[140:143], v[76:79], v[156:159], v[148:151]
	v_mfma_f32_16x16x32_bf16 v[64:67], v[104:107], v[156:159], v[64:67]
	v_mfma_f32_16x16x32_bf16 v[136:139], v[76:79], v[164:167], v[136:139]
	v_mfma_f32_16x16x32_bf16 v[44:47], v[104:107], v[164:167], v[44:47]
	v_mfma_f32_16x16x32_bf16 v[128:131], v[76:79], v[194:197], v[128:131]
	v_mfma_f32_16x16x32_bf16 v[40:43], v[104:107], v[194:197], v[40:43]
	v_mfma_f32_16x16x32_bf16 v[68:71], v[108:111], v[132:135], v[68:71]
	v_mfma_f32_16x16x32_bf16 v[148:151], v[92:95], v[160:163], v[140:143]
	v_mfma_f32_16x16x32_bf16 v[64:67], v[108:111], v[160:163], v[64:67]
	v_mfma_f32_16x16x32_bf16 v[136:139], v[92:95], v[190:193], v[136:139]
	v_mfma_f32_16x16x32_bf16 v[44:47], v[108:111], v[190:193], v[44:47]
	v_mfma_f32_16x16x32_bf16 v[128:131], v[92:95], v[198:201], v[128:131]
	v_mfma_f32_16x16x32_bf16 v[40:43], v[108:111], v[198:201], v[40:43]
	s_barrier
	s_mov_b32 m0, s56
	ds_read_b128 v[202:205], v237 offset:49152
	ds_read_b128 v[206:209], v237 offset:50176
	ds_read_b128 v[210:213], v237 offset:51200
	global_load_lds_dwordx4 v180, s[12:13]
	s_mov_b32 m0, s57
	ds_read_b128 v[214:217], v237 offset:52224
	global_load_lds_dwordx4 v182, s[12:13]
	s_barrier
	s_waitcnt lgkmcnt(0)
	v_mfma_f32_16x16x32_bf16 v[140:143], v[202:205], v[124:127], v[144:147]
	v_mfma_f32_16x16x32_bf16 v[112:115], v[202:205], v[156:159], v[112:115]
	v_mfma_f32_16x16x32_bf16 v[144:147], v[206:209], v[132:135], v[140:143]
	v_mfma_f32_16x16x32_bf16 v[60:63], v[210:213], v[124:127], v[60:63]
	v_mfma_f32_16x16x32_bf16 v[140:143], v[206:209], v[160:163], v[112:115]
	v_mfma_f32_16x16x32_bf16 v[112:115], v[202:205], v[164:167], v[116:119]
	v_mfma_f32_16x16x32_bf16 v[60:63], v[214:217], v[132:135], v[60:63]
	v_mfma_f32_16x16x32_bf16 v[56:59], v[210:213], v[156:159], v[56:59]
	v_mfma_f32_16x16x32_bf16 v[132:135], v[206:209], v[190:193], v[112:115]
	v_mfma_f32_16x16x32_bf16 v[36:39], v[210:213], v[164:167], v[36:39]
	v_mfma_f32_16x16x32_bf16 v[112:115], v[202:205], v[194:197], v[120:123]
	v_mfma_f32_16x16x32_bf16 v[32:35], v[210:213], v[194:197], v[32:35]
	v_mfma_f32_16x16x32_bf16 v[56:59], v[214:217], v[160:163], v[56:59]
	v_mfma_f32_16x16x32_bf16 v[36:39], v[214:217], v[190:193], v[36:39]
	v_mfma_f32_16x16x32_bf16 v[124:127], v[206:209], v[198:201], v[112:115]
	v_mfma_f32_16x16x32_bf16 v[32:35], v[214:217], v[198:201], v[32:35]
	s_barrier
	ds_read_b128 v[112:115], v238 offset:49152
	ds_read_b128 v[116:119], v238 offset:50176
	ds_read_b128 v[120:123], v238 offset:51200
	ds_read_b128 v[156:159], v238 offset:52224
	ds_read_b128 v[160:163], v238 offset:53248
	ds_read_b128 v[164:167], v238 offset:54272
	ds_read_b128 v[190:193], v238 offset:55296
	ds_read_b128 v[194:197], v238 offset:56320
	s_add_i32 m0, s53, 0x18000
	s_nop 0
	global_load_lds_dwordx4 v168, s[98:99]
	s_add_i32 m0, s53, 0x1a000
	s_nop 0
	global_load_lds_dwordx4 v184, s[98:99]
	s_barrier
	s_waitcnt lgkmcnt(0)
	v_mfma_f32_16x16x32_bf16 v[100:103], v[76:79], v[112:115], v[100:103]
	v_mfma_f32_16x16x32_bf16 v[28:31], v[104:107], v[112:115], v[28:31]
	v_mfma_f32_16x16x32_bf16 v[96:99], v[76:79], v[120:123], v[96:99]
	v_mfma_f32_16x16x32_bf16 v[24:27], v[104:107], v[120:123], v[24:27]
	v_mfma_f32_16x16x32_bf16 v[84:87], v[76:79], v[160:163], v[84:87]
	v_mfma_f32_16x16x32_bf16 v[12:15], v[104:107], v[160:163], v[12:15]
	v_mfma_f32_16x16x32_bf16 v[48:51], v[76:79], v[190:193], v[48:51]
	v_mfma_f32_16x16x32_bf16 v[8:11], v[104:107], v[190:193], v[8:11]
	v_mfma_f32_16x16x32_bf16 v[100:103], v[92:95], v[116:119], v[100:103]
	v_mfma_f32_16x16x32_bf16 v[28:31], v[108:111], v[116:119], v[28:31]
	v_mfma_f32_16x16x32_bf16 v[96:99], v[92:95], v[156:159], v[96:99]
	v_mfma_f32_16x16x32_bf16 v[24:27], v[108:111], v[156:159], v[24:27]
	v_mfma_f32_16x16x32_bf16 v[84:87], v[92:95], v[164:167], v[84:87]
	v_mfma_f32_16x16x32_bf16 v[12:15], v[108:111], v[164:167], v[12:15]
	v_mfma_f32_16x16x32_bf16 v[76:79], v[92:95], v[194:197], v[48:51]
	v_mfma_f32_16x16x32_bf16 v[8:11], v[108:111], v[194:197], v[8:11]
	s_barrier
	s_mov_b32 m0, s62
	s_nop 0
	global_load_lds_dwordx4 v180, s[100:101]
	s_mov_b32 m0, s63
	s_nop 0
	global_load_lds_dwordx4 v182, s[100:101]
	s_add_i32 m0, s53, 0x1c000
	s_add_u32 s2, s2, 0x40080
	s_addc_u32 s3, s3, 0
	global_load_lds_dwordx4 v168, s[2:3]
	s_add_i32 m0, s53, 0x1e000
	s_add_i32 s67, s67, 2
	global_load_lds_dwordx4 v184, s[2:3]
	s_waitcnt vmcnt(6)
	s_barrier
	v_mfma_f32_16x16x32_bf16 v[48:51], v[202:205], v[112:115], v[52:55]
	v_mfma_f32_16x16x32_bf16 v[92:95], v[206:209], v[116:119], v[48:51]
	v_mfma_f32_16x16x32_bf16 v[48:51], v[202:205], v[120:123], v[88:91]
	v_mfma_f32_16x16x32_bf16 v[88:91], v[206:209], v[156:159], v[48:51]
	v_mfma_f32_16x16x32_bf16 v[48:51], v[202:205], v[160:163], v[80:83]
	v_mfma_f32_16x16x32_bf16 v[20:23], v[210:213], v[112:115], v[20:23]
	v_mfma_f32_16x16x32_bf16 v[16:19], v[210:213], v[120:123], v[16:19]
	v_mfma_f32_16x16x32_bf16 v[80:83], v[206:209], v[164:167], v[48:51]
	v_mfma_f32_16x16x32_bf16 v[4:7], v[210:213], v[160:163], v[4:7]
	v_mfma_f32_16x16x32_bf16 v[48:51], v[202:205], v[190:193], v[72:75]
	v_mfma_f32_16x16x32_bf16 v[0:3], v[210:213], v[190:193], v[0:3]
	v_mfma_f32_16x16x32_bf16 v[20:23], v[214:217], v[116:119], v[20:23]
	v_mfma_f32_16x16x32_bf16 v[16:19], v[214:217], v[156:159], v[16:19]
	v_mfma_f32_16x16x32_bf16 v[4:7], v[214:217], v[164:167], v[4:7]
	v_mfma_f32_16x16x32_bf16 v[72:75], v[206:209], v[194:197], v[48:51]
	v_mfma_f32_16x16x32_bf16 v[0:3], v[214:217], v[194:197], v[0:3]
	s_add_u32 s10, s10, 0x100
	s_addc_u32 s11, s11, 0
	s_add_u32 s37, s37, 0x100
	s_addc_u32 s39, s39, 0
	s_cmp_gt_u32 s67, 13
	s_barrier
	s_cbranch_scc0 .LBB0_880

.LBB0_1048:
	s_add_u32 s56, s2, 0x100
	s_addc_u32 s57, s3, 0
	s_mov_b32 s58, -2
	s_add_u32 s2, s24, 0x100
	s_addc_u32 s3, s25, 0
	ds_read_b128 v[40:43], v194
	ds_read_b128 v[44:47], v194 offset:1024
	ds_read_b128 v[48:51], v194 offset:2048
	ds_read_b128 v[52:55], v194 offset:3072
	s_cmp_eq_u32 s58, 40
	s_cselect_b32 s27, s1, s3
	s_cselect_b32 s26, s0, s2
	s_cselect_b32 s9, s23, s57
	s_cselect_b32 s8, s22, s56
	ds_read_b128 v[56:59], v195
	ds_read_b128 v[60:63], v195 offset:1024
	ds_read_b128 v[72:75], v195 offset:2048
	ds_read_b128 v[84:87], v195 offset:3072
	ds_read_b128 v[182:185], v195 offset:4096
	ds_read_b128 v[186:189], v195 offset:5120
	ds_read_b128 v[196:199], v195 offset:6144
	ds_read_b128 v[200:203], v195 offset:7168
	s_waitcnt lgkmcnt(8)
	s_barrier
	s_waitcnt lgkmcnt(0)
	v_mfma_f32_16x16x32_bf16 v[156:159], v[40:43], v[56:59], 0
	v_mfma_f32_16x16x32_bf16 v[152:155], v[48:51], v[56:59], 0
	v_mfma_f32_16x16x32_bf16 v[140:143], v[40:43], v[72:75], 0
	v_mfma_f32_16x16x32_bf16 v[136:139], v[48:51], v[72:75], 0
	v_mfma_f32_16x16x32_bf16 v[124:127], v[40:43], v[182:185], 0
	v_mfma_f32_16x16x32_bf16 v[120:123], v[48:51], v[182:185], 0
	v_mfma_f32_16x16x32_bf16 v[108:111], v[40:43], v[196:199], 0
	v_mfma_f32_16x16x32_bf16 v[104:107], v[48:51], v[196:199], 0
	v_mfma_f32_16x16x32_bf16 v[156:159], v[44:47], v[60:63], v[156:159]
	v_mfma_f32_16x16x32_bf16 v[152:155], v[52:55], v[60:63], v[152:155]
	v_mfma_f32_16x16x32_bf16 v[140:143], v[44:47], v[84:87], v[140:143]
	v_mfma_f32_16x16x32_bf16 v[136:139], v[52:55], v[84:87], v[136:139]
	v_mfma_f32_16x16x32_bf16 v[124:127], v[44:47], v[186:189], v[124:127]
	v_mfma_f32_16x16x32_bf16 v[120:123], v[52:55], v[186:189], v[120:123]
	v_mfma_f32_16x16x32_bf16 v[108:111], v[44:47], v[200:203], v[108:111]
	v_mfma_f32_16x16x32_bf16 v[104:107], v[52:55], v[200:203], v[104:107]
	s_barrier
	s_add_i32 m0, s37, 0xc000
	ds_read_b128 v[204:207], v194 offset:16384
	ds_read_b128 v[208:211], v194 offset:17408
	ds_read_b128 v[212:215], v194 offset:18432
	global_load_lds_dwordx4 v166, s[24:25]
	s_add_i32 m0, s37, 0xe000
	ds_read_b128 v[216:219], v194 offset:19456
	global_load_lds_dwordx4 v180, s[24:25]
	s_add_u32 s98, s8, 0x80
	s_addc_u32 s99, s9, 0
	s_barrier
	s_waitcnt lgkmcnt(0)
	v_mfma_f32_16x16x32_bf16 v[148:151], v[204:207], v[56:59], 0
	v_mfma_f32_16x16x32_bf16 v[56:59], v[212:215], v[56:59], 0
	v_mfma_f32_16x16x32_bf16 v[148:151], v[208:211], v[60:63], v[148:151]
	v_mfma_f32_16x16x32_bf16 v[56:59], v[216:219], v[60:63], v[56:59]
	v_mfma_f32_16x16x32_bf16 v[60:63], v[204:207], v[72:75], 0
	v_mfma_f32_16x16x32_bf16 v[72:75], v[212:215], v[72:75], 0
	v_mfma_f32_16x16x32_bf16 v[112:115], v[212:215], v[182:185], 0
	v_mfma_f32_16x16x32_bf16 v[100:103], v[204:207], v[196:199], 0
	v_mfma_f32_16x16x32_bf16 v[96:99], v[212:215], v[196:199], 0
	v_mfma_f32_16x16x32_bf16 v[60:63], v[208:211], v[84:87], v[60:63]
	v_mfma_f32_16x16x32_bf16 v[72:75], v[216:219], v[84:87], v[72:75]
	v_mfma_f32_16x16x32_bf16 v[84:87], v[204:207], v[182:185], 0
	v_mfma_f32_16x16x32_bf16 v[112:115], v[216:219], v[186:189], v[112:115]
	v_mfma_f32_16x16x32_bf16 v[100:103], v[208:211], v[200:203], v[100:103]
	v_mfma_f32_16x16x32_bf16 v[96:99], v[216:219], v[200:203], v[96:99]
	v_mfma_f32_16x16x32_bf16 v[84:87], v[208:211], v[186:189], v[84:87]
	s_add_u32 s100, s26, 0x80
	s_addc_u32 s101, s27, 0
	s_barrier
	ds_read_b128 v[116:119], v195 offset:16384
	ds_read_b128 v[128:131], v195 offset:17408
	ds_read_b128 v[132:135], v195 offset:18432
	ds_read_b128 v[144:147], v195 offset:19456
	ds_read_b128 v[182:185], v195 offset:20480
	ds_read_b128 v[186:189], v195 offset:21504
	ds_read_b128 v[196:199], v195 offset:22528
	ds_read_b128 v[200:203], v195 offset:23552
	s_add_i32 m0, s36, 0x10000
	s_nop 0
	global_load_lds_dwordx4 v168, s[8:9]
	s_add_i32 m0, s36, 0x12000
	s_nop 0
	global_load_lds_dwordx4 v164, s[8:9]
	s_barrier
	s_waitcnt lgkmcnt(0)
	v_mfma_f32_16x16x32_bf16 v[92:95], v[40:43], v[116:119], 0
	v_mfma_f32_16x16x32_bf16 v[88:91], v[48:51], v[116:119], 0
	v_mfma_f32_16x16x32_bf16 v[68:71], v[40:43], v[132:135], 0
	v_mfma_f32_16x16x32_bf16 v[64:67], v[48:51], v[132:135], 0
	v_mfma_f32_16x16x32_bf16 v[28:31], v[40:43], v[182:185], 0
	v_mfma_f32_16x16x32_bf16 v[24:27], v[48:51], v[182:185], 0
	v_mfma_f32_16x16x32_bf16 v[12:15], v[40:43], v[196:199], 0
	v_mfma_f32_16x16x32_bf16 v[8:11], v[48:51], v[196:199], 0
	v_mfma_f32_16x16x32_bf16 v[92:95], v[44:47], v[128:131], v[92:95]
	v_mfma_f32_16x16x32_bf16 v[88:91], v[52:55], v[128:131], v[88:91]
	v_mfma_f32_16x16x32_bf16 v[68:71], v[44:47], v[144:147], v[68:71]
	v_mfma_f32_16x16x32_bf16 v[64:67], v[52:55], v[144:147], v[64:67]
	v_mfma_f32_16x16x32_bf16 v[28:31], v[44:47], v[186:189], v[28:31]
	v_mfma_f32_16x16x32_bf16 v[24:27], v[52:55], v[186:189], v[24:27]
	v_mfma_f32_16x16x32_bf16 v[12:15], v[44:47], v[200:203], v[12:15]
	v_mfma_f32_16x16x32_bf16 v[8:11], v[52:55], v[200:203], v[8:11]
	s_barrier
	s_mov_b32 m0, s37
	s_nop 0
	global_load_lds_dwordx4 v160, s[26:27]
	s_mov_b32 m0, s38
	s_nop 0
	global_load_lds_dwordx4 v162, s[26:27]
	s_add_i32 m0, s36, 0x14000
	s_add_u32 s24, s8, 0xb0000
	s_addc_u32 s25, s9, 0
	global_load_lds_dwordx4 v168, s[24:25]
	s_add_i32 m0, s36, 0x16000
	s_nop 0
	global_load_lds_dwordx4 v164, s[24:25]
	s_waitcnt vmcnt(6)
	s_barrier
	v_mfma_f32_16x16x32_bf16 v[36:39], v[204:207], v[132:135], 0
	v_mfma_f32_16x16x32_bf16 v[32:35], v[212:215], v[132:135], 0
	v_mfma_f32_16x16x32_bf16 v[20:23], v[204:207], v[182:185], 0
	v_mfma_f32_16x16x32_bf16 v[16:19], v[212:215], v[182:185], 0
	v_mfma_f32_16x16x32_bf16 v[4:7], v[204:207], v[196:199], 0
	v_mfma_f32_16x16x32_bf16 v[0:3], v[212:215], v[196:199], 0
	v_mfma_f32_16x16x32_bf16 v[40:43], v[204:207], v[116:119], 0
	v_mfma_f32_16x16x32_bf16 v[44:47], v[212:215], v[116:119], 0
	v_mfma_f32_16x16x32_bf16 v[36:39], v[208:211], v[144:147], v[36:39]
	v_mfma_f32_16x16x32_bf16 v[32:35], v[216:219], v[144:147], v[32:35]
	v_mfma_f32_16x16x32_bf16 v[20:23], v[208:211], v[186:189], v[20:23]
	v_mfma_f32_16x16x32_bf16 v[16:19], v[216:219], v[186:189], v[16:19]
	v_mfma_f32_16x16x32_bf16 v[4:7], v[208:211], v[200:203], v[4:7]
	v_mfma_f32_16x16x32_bf16 v[0:3], v[216:219], v[200:203], v[0:3]
	v_mfma_f32_16x16x32_bf16 v[40:43], v[208:211], v[128:131], v[40:43]
	v_mfma_f32_16x16x32_bf16 v[44:47], v[216:219], v[128:131], v[44:47]
	s_barrier
	ds_read_b128 v[48:51], v194 offset:32768
	ds_read_b128 v[52:55], v194 offset:33792
	ds_read_b128 v[76:79], v194 offset:34816
	ds_read_b128 v[80:83], v194 offset:35840
	s_add_u32 s24, s26, 0xb0000
	s_addc_u32 s25, s27, 0
	ds_read_b128 v[116:119], v195 offset:32768
	ds_read_b128 v[128:131], v195 offset:33792
	ds_read_b128 v[182:185], v195 offset:34816
	ds_read_b128 v[186:189], v195 offset:35840
	ds_read_b128 v[196:199], v195 offset:36864
	ds_read_b128 v[200:203], v195 offset:37888
	ds_read_b128 v[204:207], v195 offset:38912
	ds_read_b128 v[208:211], v195 offset:39936
	s_waitcnt lgkmcnt(8)
	s_barrier
	s_waitcnt lgkmcnt(0)
	v_mfma_f32_16x16x32_bf16 v[132:135], v[48:51], v[116:119], v[156:159]
	v_mfma_f32_16x16x32_bf16 v[156:159], v[52:55], v[128:131], v[132:135]
	v_mfma_f32_16x16x32_bf16 v[132:135], v[76:79], v[116:119], v[152:155]
	v_mfma_f32_16x16x32_bf16 v[152:155], v[80:83], v[128:131], v[132:135]
	v_mfma_f32_16x16x32_bf16 v[132:135], v[48:51], v[182:185], v[140:143]
	v_mfma_f32_16x16x32_bf16 v[140:143], v[52:55], v[186:189], v[132:135]
	v_mfma_f32_16x16x32_bf16 v[132:135], v[76:79], v[182:185], v[136:139]
	v_mfma_f32_16x16x32_bf16 v[124:127], v[48:51], v[196:199], v[124:127]
	v_mfma_f32_16x16x32_bf16 v[120:123], v[76:79], v[196:199], v[120:123]
	v_mfma_f32_16x16x32_bf16 v[108:111], v[48:51], v[204:207], v[108:111]
	v_mfma_f32_16x16x32_bf16 v[104:107], v[76:79], v[204:207], v[104:107]
	v_mfma_f32_16x16x32_bf16 v[136:139], v[80:83], v[186:189], v[132:135]
	v_mfma_f32_16x16x32_bf16 v[124:127], v[52:55], v[200:203], v[124:127]
	v_mfma_f32_16x16x32_bf16 v[120:123], v[80:83], v[200:203], v[120:123]
	v_mfma_f32_16x16x32_bf16 v[108:111], v[52:55], v[208:211], v[108:111]
	v_mfma_f32_16x16x32_bf16 v[104:107], v[80:83], v[208:211], v[104:107]
	s_barrier
	s_mov_b32 m0, s39
	ds_read_b128 v[212:215], v194 offset:49152
	ds_read_b128 v[216:219], v194 offset:50176
	ds_read_b128 v[220:223], v194 offset:51200
	global_load_lds_dwordx4 v160, s[24:25]
	s_mov_b32 m0, s40
	ds_read_b128 v[236:239], v194 offset:52224
	global_load_lds_dwordx4 v162, s[24:25]
	s_barrier
	s_waitcnt lgkmcnt(0)
	v_mfma_f32_16x16x32_bf16 v[56:59], v[220:223], v[116:119], v[56:59]
	v_mfma_f32_16x16x32_bf16 v[132:135], v[212:215], v[116:119], v[148:151]
	v_mfma_f32_16x16x32_bf16 v[144:147], v[236:239], v[128:131], v[56:59]
	v_mfma_f32_16x16x32_bf16 v[56:59], v[212:215], v[182:185], v[60:63]
	v_mfma_f32_16x16x32_bf16 v[148:151], v[216:219], v[128:131], v[132:135]
	v_mfma_f32_16x16x32_bf16 v[132:135], v[216:219], v[186:189], v[56:59]
	v_mfma_f32_16x16x32_bf16 v[56:59], v[220:223], v[182:185], v[72:75]
	v_mfma_f32_16x16x32_bf16 v[128:131], v[236:239], v[186:189], v[56:59]
	v_mfma_f32_16x16x32_bf16 v[56:59], v[212:215], v[196:199], v[84:87]
	v_mfma_f32_16x16x32_bf16 v[116:119], v[216:219], v[200:203], v[56:59]
	v_mfma_f32_16x16x32_bf16 v[56:59], v[220:223], v[196:199], v[112:115]
	v_mfma_f32_16x16x32_bf16 v[112:115], v[236:239], v[200:203], v[56:59]
	v_mfma_f32_16x16x32_bf16 v[56:59], v[212:215], v[204:207], v[100:103]
	v_mfma_f32_16x16x32_bf16 v[100:103], v[216:219], v[208:211], v[56:59]
	v_mfma_f32_16x16x32_bf16 v[56:59], v[220:223], v[204:207], v[96:99]
	v_mfma_f32_16x16x32_bf16 v[96:99], v[236:239], v[208:211], v[56:59]
	s_barrier
	s_nop 2
	ds_read_b128 v[56:59], v195 offset:49152
	ds_read_b128 v[60:63], v195 offset:50176
	ds_read_b128 v[72:75], v195 offset:51200
	ds_read_b128 v[84:87], v195 offset:52224
	ds_read_b128 v[182:185], v195 offset:53248
	ds_read_b128 v[186:189], v195 offset:54272
	ds_read_b128 v[196:199], v195 offset:55296
	ds_read_b128 v[200:203], v195 offset:56320
	s_add_i32 m0, s36, 0x18000
	s_nop 0
	global_load_lds_dwordx4 v168, s[98:99]
	s_add_i32 m0, s36, 0x1a000
	s_nop 0
	global_load_lds_dwordx4 v164, s[98:99]
	s_barrier
	s_waitcnt lgkmcnt(0)
	v_mfma_f32_16x16x32_bf16 v[92:95], v[48:51], v[56:59], v[92:95]
	v_mfma_f32_16x16x32_bf16 v[88:91], v[76:79], v[56:59], v[88:91]
	v_mfma_f32_16x16x32_bf16 v[68:71], v[48:51], v[72:75], v[68:71]
	v_mfma_f32_16x16x32_bf16 v[64:67], v[76:79], v[72:75], v[64:67]
	v_mfma_f32_16x16x32_bf16 v[28:31], v[48:51], v[182:185], v[28:31]
	v_mfma_f32_16x16x32_bf16 v[24:27], v[76:79], v[182:185], v[24:27]
	v_mfma_f32_16x16x32_bf16 v[12:15], v[48:51], v[196:199], v[12:15]
	v_mfma_f32_16x16x32_bf16 v[8:11], v[76:79], v[196:199], v[8:11]
	v_mfma_f32_16x16x32_bf16 v[92:95], v[52:55], v[60:63], v[92:95]
	v_mfma_f32_16x16x32_bf16 v[88:91], v[80:83], v[60:63], v[88:91]
	v_mfma_f32_16x16x32_bf16 v[68:71], v[52:55], v[84:87], v[68:71]
	v_mfma_f32_16x16x32_bf16 v[64:67], v[80:83], v[84:87], v[64:67]
	v_mfma_f32_16x16x32_bf16 v[28:31], v[52:55], v[186:189], v[28:31]
	v_mfma_f32_16x16x32_bf16 v[24:27], v[80:83], v[186:189], v[24:27]
	v_mfma_f32_16x16x32_bf16 v[12:15], v[52:55], v[200:203], v[12:15]
	v_mfma_f32_16x16x32_bf16 v[8:11], v[80:83], v[200:203], v[8:11]
	s_barrier
	s_mov_b32 m0, s47
	s_nop 0
	global_load_lds_dwordx4 v160, s[100:101]
	s_mov_b32 m0, s49
	s_nop 0
	global_load_lds_dwordx4 v162, s[100:101]
	s_add_i32 m0, s36, 0x1c000
	s_add_u32 s8, s8, 0xb0080
	s_addc_u32 s9, s9, 0
	global_load_lds_dwordx4 v168, s[8:9]
	s_add_i32 m0, s36, 0x1e000
	s_add_i32 s58, s58, 2
	global_load_lds_dwordx4 v164, s[8:9]
	s_waitcnt vmcnt(6)
	s_barrier
	v_mfma_f32_16x16x32_bf16 v[40:43], v[212:215], v[56:59], v[40:43]
	v_mfma_f32_16x16x32_bf16 v[80:83], v[216:219], v[60:63], v[40:43]
	v_mfma_f32_16x16x32_bf16 v[40:43], v[220:223], v[56:59], v[44:47]
	v_mfma_f32_16x16x32_bf16 v[36:39], v[212:215], v[72:75], v[36:39]
	v_mfma_f32_16x16x32_bf16 v[32:35], v[220:223], v[72:75], v[32:35]
	v_mfma_f32_16x16x32_bf16 v[20:23], v[212:215], v[182:185], v[20:23]
	v_mfma_f32_16x16x32_bf16 v[16:19], v[220:223], v[182:185], v[16:19]
	v_mfma_f32_16x16x32_bf16 v[4:7], v[212:215], v[196:199], v[4:7]
	v_mfma_f32_16x16x32_bf16 v[0:3], v[220:223], v[196:199], v[0:3]
	v_mfma_f32_16x16x32_bf16 v[76:79], v[236:239], v[60:63], v[40:43]
	v_mfma_f32_16x16x32_bf16 v[36:39], v[216:219], v[84:87], v[36:39]
	v_mfma_f32_16x16x32_bf16 v[32:35], v[236:239], v[84:87], v[32:35]
	v_mfma_f32_16x16x32_bf16 v[20:23], v[216:219], v[186:189], v[20:23]
	v_mfma_f32_16x16x32_bf16 v[16:19], v[236:239], v[186:189], v[16:19]
	v_mfma_f32_16x16x32_bf16 v[4:7], v[216:219], v[200:203], v[4:7]
	v_mfma_f32_16x16x32_bf16 v[0:3], v[236:239], v[200:203], v[0:3]
	s_add_u32 s56, s56, 0x100
	s_addc_u32 s57, s57, 0
	s_cmp_gt_u32 s58, 41
	s_mov_b64 s[24:25], s[2:3]
	s_barrier
.LBB0_1049:
	s_add_u32 s2, s24, 0x100
	s_addc_u32 s3, s25, 0
	ds_read_b128 v[40:43], v194
	ds_read_b128 v[44:47], v194 offset:1024
	ds_read_b128 v[48:51], v194 offset:2048
	ds_read_b128 v[52:55], v194 offset:3072
	s_cmp_eq_u32 s58, 40
	s_cselect_b32 s27, s1, s3
	s_cselect_b32 s26, s0, s2
	s_cselect_b32 s9, s23, s57
	s_cselect_b32 s8, s22, s56
	ds_read_b128 v[56:59], v195
	ds_read_b128 v[60:63], v195 offset:1024
	ds_read_b128 v[72:75], v195 offset:2048
	ds_read_b128 v[84:87], v195 offset:3072
	ds_read_b128 v[182:185], v195 offset:4096
	ds_read_b128 v[186:189], v195 offset:5120
	ds_read_b128 v[196:199], v195 offset:6144
	ds_read_b128 v[200:203], v195 offset:7168
	s_waitcnt lgkmcnt(8)
	s_barrier
	s_waitcnt lgkmcnt(0)
	v_mfma_f32_16x16x32_bf16 v[156:159], v[40:43], v[56:59], v[156:159]
	v_mfma_f32_16x16x32_bf16 v[152:155], v[48:51], v[56:59], v[152:155]
	v_mfma_f32_16x16x32_bf16 v[140:143], v[40:43], v[72:75], v[140:143]
	v_mfma_f32_16x16x32_bf16 v[136:139], v[48:51], v[72:75], v[136:139]
	v_mfma_f32_16x16x32_bf16 v[124:127], v[40:43], v[182:185], v[124:127]
	v_mfma_f32_16x16x32_bf16 v[120:123], v[48:51], v[182:185], v[120:123]
	v_mfma_f32_16x16x32_bf16 v[108:111], v[40:43], v[196:199], v[108:111]
	v_mfma_f32_16x16x32_bf16 v[104:107], v[48:51], v[196:199], v[104:107]
	v_mfma_f32_16x16x32_bf16 v[156:159], v[44:47], v[60:63], v[156:159]
	v_mfma_f32_16x16x32_bf16 v[152:155], v[52:55], v[60:63], v[152:155]
	v_mfma_f32_16x16x32_bf16 v[140:143], v[44:47], v[84:87], v[140:143]
	v_mfma_f32_16x16x32_bf16 v[136:139], v[52:55], v[84:87], v[136:139]
	v_mfma_f32_16x16x32_bf16 v[124:127], v[44:47], v[186:189], v[124:127]
	v_mfma_f32_16x16x32_bf16 v[120:123], v[52:55], v[186:189], v[120:123]
	v_mfma_f32_16x16x32_bf16 v[108:111], v[44:47], v[200:203], v[108:111]
	v_mfma_f32_16x16x32_bf16 v[104:107], v[52:55], v[200:203], v[104:107]
	s_barrier
	s_add_i32 m0, s37, 0xc000
	ds_read_b128 v[204:207], v194 offset:16384
	ds_read_b128 v[208:211], v194 offset:17408
	ds_read_b128 v[212:215], v194 offset:18432
	global_load_lds_dwordx4 v166, s[24:25]
	s_add_i32 m0, s37, 0xe000
	ds_read_b128 v[216:219], v194 offset:19456
	global_load_lds_dwordx4 v180, s[24:25]
	s_add_u32 s98, s8, 0x80
	s_addc_u32 s99, s9, 0
	s_barrier
	s_waitcnt lgkmcnt(0)
	v_mfma_f32_16x16x32_bf16 v[148:151], v[204:207], v[56:59], v[148:151]
	v_mfma_f32_16x16x32_bf16 v[56:59], v[212:215], v[56:59], v[144:147]
	v_mfma_f32_16x16x32_bf16 v[148:151], v[208:211], v[60:63], v[148:151]
	v_mfma_f32_16x16x32_bf16 v[56:59], v[216:219], v[60:63], v[56:59]
	v_mfma_f32_16x16x32_bf16 v[60:63], v[204:207], v[72:75], v[132:135]
	v_mfma_f32_16x16x32_bf16 v[72:75], v[212:215], v[72:75], v[128:131]
	v_mfma_f32_16x16x32_bf16 v[112:115], v[212:215], v[182:185], v[112:115]
	v_mfma_f32_16x16x32_bf16 v[100:103], v[204:207], v[196:199], v[100:103]
	v_mfma_f32_16x16x32_bf16 v[96:99], v[212:215], v[196:199], v[96:99]
	v_mfma_f32_16x16x32_bf16 v[60:63], v[208:211], v[84:87], v[60:63]
	v_mfma_f32_16x16x32_bf16 v[72:75], v[216:219], v[84:87], v[72:75]
	v_mfma_f32_16x16x32_bf16 v[84:87], v[204:207], v[182:185], v[116:119]
	v_mfma_f32_16x16x32_bf16 v[112:115], v[216:219], v[186:189], v[112:115]
	v_mfma_f32_16x16x32_bf16 v[100:103], v[208:211], v[200:203], v[100:103]
	v_mfma_f32_16x16x32_bf16 v[96:99], v[216:219], v[200:203], v[96:99]
	v_mfma_f32_16x16x32_bf16 v[84:87], v[208:211], v[186:189], v[84:87]
	s_add_u32 s100, s26, 0x80
	s_addc_u32 s101, s27, 0
	s_barrier
	ds_read_b128 v[116:119], v195 offset:16384
	ds_read_b128 v[128:131], v195 offset:17408
	ds_read_b128 v[132:135], v195 offset:18432
	ds_read_b128 v[144:147], v195 offset:19456
	ds_read_b128 v[182:185], v195 offset:20480
	ds_read_b128 v[186:189], v195 offset:21504
	ds_read_b128 v[196:199], v195 offset:22528
	ds_read_b128 v[200:203], v195 offset:23552
	s_add_i32 m0, s36, 0x10000
	s_nop 0
	global_load_lds_dwordx4 v168, s[8:9]
	s_add_i32 m0, s36, 0x12000
	s_nop 0
	global_load_lds_dwordx4 v164, s[8:9]
	s_barrier
	s_waitcnt lgkmcnt(0)
	v_mfma_f32_16x16x32_bf16 v[92:95], v[40:43], v[116:119], v[92:95]
	v_mfma_f32_16x16x32_bf16 v[88:91], v[48:51], v[116:119], v[88:91]
	v_mfma_f32_16x16x32_bf16 v[68:71], v[40:43], v[132:135], v[68:71]
	v_mfma_f32_16x16x32_bf16 v[64:67], v[48:51], v[132:135], v[64:67]
	v_mfma_f32_16x16x32_bf16 v[28:31], v[40:43], v[182:185], v[28:31]
	v_mfma_f32_16x16x32_bf16 v[24:27], v[48:51], v[182:185], v[24:27]
	v_mfma_f32_16x16x32_bf16 v[12:15], v[40:43], v[196:199], v[12:15]
	v_mfma_f32_16x16x32_bf16 v[8:11], v[48:51], v[196:199], v[8:11]
	v_mfma_f32_16x16x32_bf16 v[92:95], v[44:47], v[128:131], v[92:95]
	v_mfma_f32_16x16x32_bf16 v[88:91], v[52:55], v[128:131], v[88:91]
	v_mfma_f32_16x16x32_bf16 v[68:71], v[44:47], v[144:147], v[68:71]
	v_mfma_f32_16x16x32_bf16 v[64:67], v[52:55], v[144:147], v[64:67]
	v_mfma_f32_16x16x32_bf16 v[28:31], v[44:47], v[186:189], v[28:31]
	v_mfma_f32_16x16x32_bf16 v[24:27], v[52:55], v[186:189], v[24:27]
	v_mfma_f32_16x16x32_bf16 v[12:15], v[44:47], v[200:203], v[12:15]
	v_mfma_f32_16x16x32_bf16 v[8:11], v[52:55], v[200:203], v[8:11]
	s_barrier
	s_mov_b32 m0, s37
	s_nop 0
	global_load_lds_dwordx4 v160, s[26:27]
	s_mov_b32 m0, s38
	s_nop 0
	global_load_lds_dwordx4 v162, s[26:27]
	s_add_i32 m0, s36, 0x14000
	s_add_u32 s24, s8, 0xb0000
	s_addc_u32 s25, s9, 0
	global_load_lds_dwordx4 v168, s[24:25]
	s_add_i32 m0, s36, 0x16000
	s_nop 0
	global_load_lds_dwordx4 v164, s[24:25]
	s_waitcnt vmcnt(6)
	s_barrier
	v_mfma_f32_16x16x32_bf16 v[36:39], v[204:207], v[132:135], v[36:39]
	v_mfma_f32_16x16x32_bf16 v[32:35], v[212:215], v[132:135], v[32:35]
	v_mfma_f32_16x16x32_bf16 v[20:23], v[204:207], v[182:185], v[20:23]
	v_mfma_f32_16x16x32_bf16 v[16:19], v[212:215], v[182:185], v[16:19]
	v_mfma_f32_16x16x32_bf16 v[4:7], v[204:207], v[196:199], v[4:7]
	v_mfma_f32_16x16x32_bf16 v[0:3], v[212:215], v[196:199], v[0:3]
	v_mfma_f32_16x16x32_bf16 v[40:43], v[204:207], v[116:119], v[80:83]
	v_mfma_f32_16x16x32_bf16 v[44:47], v[212:215], v[116:119], v[76:79]
	v_mfma_f32_16x16x32_bf16 v[36:39], v[208:211], v[144:147], v[36:39]
	v_mfma_f32_16x16x32_bf16 v[32:35], v[216:219], v[144:147], v[32:35]
	v_mfma_f32_16x16x32_bf16 v[20:23], v[208:211], v[186:189], v[20:23]
	v_mfma_f32_16x16x32_bf16 v[16:19], v[216:219], v[186:189], v[16:19]
	v_mfma_f32_16x16x32_bf16 v[4:7], v[208:211], v[200:203], v[4:7]
	v_mfma_f32_16x16x32_bf16 v[0:3], v[216:219], v[200:203], v[0:3]
	v_mfma_f32_16x16x32_bf16 v[40:43], v[208:211], v[128:131], v[40:43]
	v_mfma_f32_16x16x32_bf16 v[44:47], v[216:219], v[128:131], v[44:47]
	s_barrier
	ds_read_b128 v[48:51], v194 offset:32768
	ds_read_b128 v[52:55], v194 offset:33792
	ds_read_b128 v[76:79], v194 offset:34816
	ds_read_b128 v[80:83], v194 offset:35840
	s_add_u32 s24, s26, 0xb0000
	s_addc_u32 s25, s27, 0
	ds_read_b128 v[116:119], v195 offset:32768
	ds_read_b128 v[128:131], v195 offset:33792
	ds_read_b128 v[182:185], v195 offset:34816
	ds_read_b128 v[186:189], v195 offset:35840
	ds_read_b128 v[196:199], v195 offset:36864
	ds_read_b128 v[200:203], v195 offset:37888
	ds_read_b128 v[204:207], v195 offset:38912
	ds_read_b128 v[208:211], v195 offset:39936
	s_waitcnt lgkmcnt(8)
	s_barrier
	s_waitcnt lgkmcnt(0)
	v_mfma_f32_16x16x32_bf16 v[132:135], v[48:51], v[116:119], v[156:159]
	v_mfma_f32_16x16x32_bf16 v[156:159], v[52:55], v[128:131], v[132:135]
	v_mfma_f32_16x16x32_bf16 v[132:135], v[76:79], v[116:119], v[152:155]
	v_mfma_f32_16x16x32_bf16 v[152:155], v[80:83], v[128:131], v[132:135]
	v_mfma_f32_16x16x32_bf16 v[132:135], v[48:51], v[182:185], v[140:143]
	v_mfma_f32_16x16x32_bf16 v[140:143], v[52:55], v[186:189], v[132:135]
	v_mfma_f32_16x16x32_bf16 v[132:135], v[76:79], v[182:185], v[136:139]
	v_mfma_f32_16x16x32_bf16 v[124:127], v[48:51], v[196:199], v[124:127]
	v_mfma_f32_16x16x32_bf16 v[120:123], v[76:79], v[196:199], v[120:123]
	v_mfma_f32_16x16x32_bf16 v[108:111], v[48:51], v[204:207], v[108:111]
	v_mfma_f32_16x16x32_bf16 v[104:107], v[76:79], v[204:207], v[104:107]
	v_mfma_f32_16x16x32_bf16 v[136:139], v[80:83], v[186:189], v[132:135]
	v_mfma_f32_16x16x32_bf16 v[124:127], v[52:55], v[200:203], v[124:127]
	v_mfma_f32_16x16x32_bf16 v[120:123], v[80:83], v[200:203], v[120:123]
	v_mfma_f32_16x16x32_bf16 v[108:111], v[52:55], v[208:211], v[108:111]
	v_mfma_f32_16x16x32_bf16 v[104:107], v[80:83], v[208:211], v[104:107]
	s_barrier
	s_mov_b32 m0, s39
	ds_read_b128 v[212:215], v194 offset:49152
	ds_read_b128 v[216:219], v194 offset:50176
	ds_read_b128 v[220:223], v194 offset:51200
	global_load_lds_dwordx4 v160, s[24:25]
	s_mov_b32 m0, s40
	ds_read_b128 v[236:239], v194 offset:52224
	global_load_lds_dwordx4 v162, s[24:25]
	s_barrier
	s_waitcnt lgkmcnt(0)
	v_mfma_f32_16x16x32_bf16 v[56:59], v[220:223], v[116:119], v[56:59]
	v_mfma_f32_16x16x32_bf16 v[132:135], v[212:215], v[116:119], v[148:151]
	v_mfma_f32_16x16x32_bf16 v[144:147], v[236:239], v[128:131], v[56:59]
	v_mfma_f32_16x16x32_bf16 v[56:59], v[212:215], v[182:185], v[60:63]
	v_mfma_f32_16x16x32_bf16 v[148:151], v[216:219], v[128:131], v[132:135]
	v_mfma_f32_16x16x32_bf16 v[132:135], v[216:219], v[186:189], v[56:59]
	v_mfma_f32_16x16x32_bf16 v[56:59], v[220:223], v[182:185], v[72:75]
	v_mfma_f32_16x16x32_bf16 v[128:131], v[236:239], v[186:189], v[56:59]
	v_mfma_f32_16x16x32_bf16 v[56:59], v[212:215], v[196:199], v[84:87]
	v_mfma_f32_16x16x32_bf16 v[116:119], v[216:219], v[200:203], v[56:59]
	v_mfma_f32_16x16x32_bf16 v[56:59], v[220:223], v[196:199], v[112:115]
	v_mfma_f32_16x16x32_bf16 v[112:115], v[236:239], v[200:203], v[56:59]
	v_mfma_f32_16x16x32_bf16 v[56:59], v[212:215], v[204:207], v[100:103]
	v_mfma_f32_16x16x32_bf16 v[100:103], v[216:219], v[208:211], v[56:59]
	v_mfma_f32_16x16x32_bf16 v[56:59], v[220:223], v[204:207], v[96:99]
	v_mfma_f32_16x16x32_bf16 v[96:99], v[236:239], v[208:211], v[56:59]
	s_barrier
	s_nop 2
	ds_read_b128 v[56:59], v195 offset:49152
	ds_read_b128 v[60:63], v195 offset:50176
	ds_read_b128 v[72:75], v195 offset:51200
	ds_read_b128 v[84:87], v195 offset:52224
	ds_read_b128 v[182:185], v195 offset:53248
	ds_read_b128 v[186:189], v195 offset:54272
	ds_read_b128 v[196:199], v195 offset:55296
	ds_read_b128 v[200:203], v195 offset:56320
	s_add_i32 m0, s36, 0x18000
	s_nop 0
	global_load_lds_dwordx4 v168, s[98:99]
	s_add_i32 m0, s36, 0x1a000
	s_nop 0
	global_load_lds_dwordx4 v164, s[98:99]
	s_barrier
	s_waitcnt lgkmcnt(0)
	v_mfma_f32_16x16x32_bf16 v[92:95], v[48:51], v[56:59], v[92:95]
	v_mfma_f32_16x16x32_bf16 v[88:91], v[76:79], v[56:59], v[88:91]
	v_mfma_f32_16x16x32_bf16 v[68:71], v[48:51], v[72:75], v[68:71]
	v_mfma_f32_16x16x32_bf16 v[64:67], v[76:79], v[72:75], v[64:67]
	v_mfma_f32_16x16x32_bf16 v[28:31], v[48:51], v[182:185], v[28:31]
	v_mfma_f32_16x16x32_bf16 v[24:27], v[76:79], v[182:185], v[24:27]
	v_mfma_f32_16x16x32_bf16 v[12:15], v[48:51], v[196:199], v[12:15]
	v_mfma_f32_16x16x32_bf16 v[8:11], v[76:79], v[196:199], v[8:11]
	v_mfma_f32_16x16x32_bf16 v[92:95], v[52:55], v[60:63], v[92:95]
	v_mfma_f32_16x16x32_bf16 v[88:91], v[80:83], v[60:63], v[88:91]
	v_mfma_f32_16x16x32_bf16 v[68:71], v[52:55], v[84:87], v[68:71]
	v_mfma_f32_16x16x32_bf16 v[64:67], v[80:83], v[84:87], v[64:67]
	v_mfma_f32_16x16x32_bf16 v[28:31], v[52:55], v[186:189], v[28:31]
	v_mfma_f32_16x16x32_bf16 v[24:27], v[80:83], v[186:189], v[24:27]
	v_mfma_f32_16x16x32_bf16 v[12:15], v[52:55], v[200:203], v[12:15]
	v_mfma_f32_16x16x32_bf16 v[8:11], v[80:83], v[200:203], v[8:11]
	s_barrier
	s_mov_b32 m0, s47
	s_nop 0
	global_load_lds_dwordx4 v160, s[100:101]
	s_mov_b32 m0, s49
	s_nop 0
	global_load_lds_dwordx4 v162, s[100:101]
	s_add_i32 m0, s36, 0x1c000
	s_add_u32 s8, s8, 0xb0080
	s_addc_u32 s9, s9, 0
	global_load_lds_dwordx4 v168, s[8:9]
	s_add_i32 m0, s36, 0x1e000
	s_add_i32 s58, s58, 2
	global_load_lds_dwordx4 v164, s[8:9]
	s_waitcnt vmcnt(6)
	s_barrier
	v_mfma_f32_16x16x32_bf16 v[40:43], v[212:215], v[56:59], v[40:43]
	v_mfma_f32_16x16x32_bf16 v[80:83], v[216:219], v[60:63], v[40:43]
	v_mfma_f32_16x16x32_bf16 v[40:43], v[220:223], v[56:59], v[44:47]
	v_mfma_f32_16x16x32_bf16 v[36:39], v[212:215], v[72:75], v[36:39]
	v_mfma_f32_16x16x32_bf16 v[32:35], v[220:223], v[72:75], v[32:35]
	v_mfma_f32_16x16x32_bf16 v[20:23], v[212:215], v[182:185], v[20:23]
	v_mfma_f32_16x16x32_bf16 v[16:19], v[220:223], v[182:185], v[16:19]
	v_mfma_f32_16x16x32_bf16 v[4:7], v[212:215], v[196:199], v[4:7]
	v_mfma_f32_16x16x32_bf16 v[0:3], v[220:223], v[196:199], v[0:3]
	v_mfma_f32_16x16x32_bf16 v[76:79], v[236:239], v[60:63], v[40:43]
	v_mfma_f32_16x16x32_bf16 v[36:39], v[216:219], v[84:87], v[36:39]
	v_mfma_f32_16x16x32_bf16 v[32:35], v[236:239], v[84:87], v[32:35]
	v_mfma_f32_16x16x32_bf16 v[20:23], v[216:219], v[186:189], v[20:23]
	v_mfma_f32_16x16x32_bf16 v[16:19], v[236:239], v[186:189], v[16:19]
	v_mfma_f32_16x16x32_bf16 v[4:7], v[216:219], v[200:203], v[4:7]
	v_mfma_f32_16x16x32_bf16 v[0:3], v[236:239], v[200:203], v[0:3]
	s_add_u32 s56, s56, 0x100
	s_addc_u32 s57, s57, 0
	s_cmp_gt_u32 s58, 41
	s_mov_b64 s[24:25], s[2:3]
	s_barrier
	s_cbranch_scc0 .LBB0_1049
	s_lshl_b32 s2, s55, 8
	v_mov_b32_e32 v186, v193
	v_mov_b32_e32 v196, v192
	s_or_b32 s2, s2, s46
	v_mov_b32_e32 v52, 0
	v_lshl_add_u32 v182, v196, 3, s2
	s_add_i32 s2, s54, -16
	s_lshr_b32 s2, s2, 3
	s_add_i32 s2, s2, 1
	s_cmp_gt_i32 s54, 15
	s_cselect_b32 s8, s2, 0
	s_mul_i32 s96, s8, 0x1800
	s_lshl_b64 s[2:3], s[96:97], 2
	s_add_u32 s2, s41, s2
	v_ashrrev_i32_e32 v183, 31, v182
	s_addc_u32 s3, s42, s3
	v_lshlrev_b64 v[40:41], 2, v[182:183]
	v_lshl_add_u64 v[42:43], s[2:3], 0, v[40:41]
	global_load_dwordx4 v[72:75], v[42:43], off
	s_lshl_b32 s96, s8, 10
	s_lshl_b64 s[2:3], s[96:97], 2
	s_add_u32 s2, s43, s2
	s_addc_u32 s3, s44, s3
	v_lshl_add_u64 v[184:185], s[2:3], 0, v[40:41]
	s_and_b64 vcc, exec, s[4:5]
	v_mov_b32_e32 v60, 0
	v_mov_b32_e32 v61, v52
	v_mov_b32_e32 v62, 0
	v_mov_b32_e32 v63, 0
	s_cbranch_vccnz .LBB0_1052
	global_load_dwordx4 v[60:63], v[184:185], off
